# hyena FFT: split every ds_read2_b64 into two ds_read_b64 (half-rate read2 on gfx950), lgkmcnt waits rescaled
# speedup vs baseline: 1.0006x; 1.0006x over previous
.LBB0_275:
	s_or_b64 exec, exec, s[10:11]
	s_add_i32 s77, 0, 0x22000
	v_mov_b32_e32 v0, s77
	s_waitcnt lgkmcnt(0)
	s_barrier
	ds_read_b128 v[28:31], v0
	v_mov_b32_e32 v0, s92
	ds_read_b128 v[32:35], v0
	s_waitcnt vmcnt(1)
	v_mov_b32_e32 v59, v58
	v_mov_b32_e32 v57, v56
	s_waitcnt lgkmcnt(1)
	v_add_f32_e32 v0, 0, v28
	v_add_f32_e32 v0, v0, v29
	v_add_f32_e32 v0, v0, v30
	v_add_f32_e32 v0, v0, v31
	s_waitcnt lgkmcnt(0)
	v_add_f32_e32 v0, v0, v32
	v_add_f32_e32 v0, v0, v33
	v_add_f32_e32 v0, v0, v34
	v_add_f32_e32 v0, v0, v35
	v_add_f32_e32 v0, 0x358637bd, v0
	v_mul_f32_e32 v28, 0x4f800000, v0
	v_cmp_gt_f32_e32 vcc, s23, v0
	s_waitcnt vmcnt(0)
	v_mov_b32_e32 v61, v60
	s_mov_b64 s[18:19], -1
	v_cndmask_b32_e32 v0, v0, v28, vcc
	v_sqrt_f32_e32 v28, v0
	s_nop 0
	v_add_u32_e32 v29, -1, v28
	v_fma_f32 v30, -v29, v28, v0
	v_cmp_ge_f32_e64 s[50:51], 0, v30
	v_add_u32_e32 v30, 1, v28
	s_nop 0
	v_cndmask_b32_e64 v29, v28, v29, s[50:51]
	v_fma_f32 v28, -v30, v28, v0
	v_cmp_lt_f32_e64 s[50:51], 0, v28
	s_nop 1
	v_cndmask_b32_e64 v28, v29, v30, s[50:51]
	v_mul_f32_e32 v29, 0x37800000, v28
	v_cndmask_b32_e32 v28, v28, v29, vcc
	v_cmp_class_f32_e32 vcc, v0, v210
	v_cmp_gt_i32_e64 s[50:51], s52, v137
	s_nop 0
	v_cndmask_b32_e32 v0, v28, v0, vcc
	v_div_scale_f32 v28, s[10:11], v0, v0, 1.0
	v_rcp_f32_e32 v29, v28
	s_mul_hi_i32 s10, s16, 0x8800
	s_mul_i32 s16, s16, 0x8800
	s_add_u32 s40, s85, s16
	v_fma_f32 v30, -v28, v29, 1.0
	v_fmac_f32_e32 v29, v30, v29
	v_div_scale_f32 v30, vcc, 1.0, v0, 1.0
	v_mul_f32_e32 v31, v30, v29
	v_fma_f32 v32, -v28, v31, v30
	v_fmac_f32_e32 v31, v32, v29
	v_fma_f32 v28, -v28, v31, v30
	v_div_fmas_f32 v28, v28, v29, v31
	v_div_fixup_f32 v0, v28, v0, 1.0
	v_mov_b32_e32 v29, v208
	v_mul_f32_e32 v28, v7, v0
	s_addc_u32 s41, s39, s10
	v_and_b32_e32 v0, 0xff, v29
	v_lshlrev_b32_e32 v30, 4, v29
	v_and_or_b32 v0, v30, s93, v0
	v_ashrrev_i32_e32 v30, 4, v0
	v_lshlrev_b32_e32 v30, 3, v30
	v_lshlrev_b32_e32 v0, 3, v0
	v_add3_u32 v55, 0, v30, v0
	ds_read_b64 v[32:33], v55
	ds_read_b64 v[34:35], v55 offset:2176
	ds_read_b64 v[62:63], v55 offset:4352
	ds_read_b64 v[64:65], v55 offset:6528
	ds_read_b64 v[66:67], v55 offset:8704
	ds_read_b64 v[68:69], v55 offset:10880
	ds_read_b64 v[70:71], v55 offset:13056
	ds_read_b64 v[72:73], v55 offset:15232
	ds_read_b64 v[74:75], v55 offset:17408
	ds_read_b64 v[76:77], v55 offset:19584
	ds_read_b64 v[78:79], v55 offset:21760
	ds_read_b64 v[80:81], v55 offset:23936
	ds_read_b64 v[82:83], v55 offset:26112
	ds_read_b64 v[84:85], v55 offset:28288
	ds_read_b64 v[86:87], v55 offset:30464
	ds_read_b64 v[88:89], v55 offset:32640
	s_waitcnt lgkmcnt(5)
	v_pk_add_f32 v[96:97], v[62:63], v[78:79]
	v_pk_add_f32 v[62:63], v[62:63], v[78:79] neg_lo:[0,1] neg_hi:[0,1]
	s_waitcnt lgkmcnt(2)
	v_pk_add_f32 v[106:107], v[68:69], v[84:85]
	s_waitcnt lgkmcnt(1)
	v_pk_add_f32 v[98:99], v[70:71], v[86:87]
	v_pk_add_f32 v[70:71], v[70:71], v[86:87] neg_lo:[0,1] neg_hi:[0,1]
	v_pk_add_f32 v[68:69], v[68:69], v[84:85] neg_lo:[0,1] neg_hi:[0,1]
	v_xor_b32_e32 v79, 0x80000000, v70
	v_mov_b32_e32 v78, v71
	v_pk_add_f32 v[104:105], v[34:35], v[76:77]
	v_pk_add_f32 v[70:71], v[62:63], v[78:79]
	v_pk_add_f32 v[34:35], v[34:35], v[76:77] neg_lo:[0,1] neg_hi:[0,1]
	v_xor_b32_e32 v77, 0x80000000, v68
	v_mov_b32_e32 v76, v69
	v_pk_add_f32 v[92:93], v[66:67], v[82:83]
	v_pk_add_f32 v[66:67], v[66:67], v[82:83] neg_lo:[0,1] neg_hi:[0,1]
	v_pk_mul_f32 v[82:83], v[70:71], s[24:25] op_sel_hi:[1,0]
	v_pk_add_f32 v[68:69], v[34:35], v[76:77]
	v_pk_fma_f32 v[86:87], v[70:71], s[24:25], v[82:83] op_sel:[0,0,1] op_sel_hi:[1,0,0]
	v_pk_fma_f32 v[70:71], v[70:71], s[24:25], v[82:83] op_sel_hi:[1,0,0] neg_lo:[0,0,1] neg_hi:[0,0,1]
	v_pk_mul_f32 v[82:83], v[68:69], s[30:31] op_sel_hi:[1,0]
	v_pk_add_f32 v[90:91], v[32:33], v[74:75]
	v_pk_fma_f32 v[84:85], v[68:69], s[22:23], v[82:83] op_sel:[0,0,1] op_sel_hi:[1,0,0]
	v_pk_fma_f32 v[68:69], v[68:69], s[22:23], v[82:83] op_sel:[0,0,1] op_sel_hi:[1,0,0] neg_lo:[0,0,1] neg_hi:[0,0,1]
	v_pk_add_f32 v[94:95], v[90:91], v[92:93]
	v_pk_add_f32 v[100:101], v[96:97], v[98:99]
	s_waitcnt lgkmcnt(0)
	v_pk_add_f32 v[112:113], v[72:73], v[88:89]
	v_mov_b32_e32 v85, v69
	v_pk_add_f32 v[68:69], v[72:73], v[88:89] neg_lo:[0,1] neg_hi:[0,1]
	v_pk_add_f32 v[88:89], v[90:91], v[92:93] neg_lo:[0,1] neg_hi:[0,1]
	v_pk_add_f32 v[90:91], v[96:97], v[98:99] neg_lo:[0,1] neg_hi:[0,1]
	v_pk_add_f32 v[96:97], v[104:105], v[106:107] neg_lo:[0,1] neg_hi:[0,1]
	v_pk_add_f32 v[110:111], v[64:65], v[80:81]
	v_pk_add_f32 v[64:65], v[64:65], v[80:81] neg_lo:[0,1] neg_hi:[0,1]
	v_xor_b32_e32 v73, 0x80000000, v68
	v_mov_b32_e32 v72, v69
	v_pk_mul_f32 v[98:99], v[96:97], s[24:25] op_sel_hi:[1,0]
	v_pk_add_f32 v[108:109], v[104:105], v[106:107]
	v_pk_add_f32 v[68:69], v[64:65], v[72:73]
	v_pk_fma_f32 v[104:105], v[96:97], s[24:25], v[98:99] op_sel:[0,0,1] op_sel_hi:[1,0,0]
	v_pk_fma_f32 v[96:97], v[96:97], s[24:25], v[98:99] op_sel_hi:[1,0,0] neg_lo:[0,0,1] neg_hi:[0,0,1]
	v_pk_mul_f32 v[80:81], v[68:69], s[22:23] op_sel_hi:[1,0]
	v_mov_b32_e32 v105, v97
	v_pk_add_f32 v[96:97], v[110:111], v[112:113] neg_lo:[0,1] neg_hi:[0,1]
	v_pk_add_f32 v[34:35], v[34:35], v[76:77] neg_lo:[0,1] neg_hi:[0,1]
	v_pk_fma_f32 v[82:83], v[68:69], s[30:31], v[80:81] op_sel:[0,0,1] op_sel_hi:[1,0,0]
	v_pk_fma_f32 v[68:69], v[68:69], s[30:31], v[80:81] op_sel:[0,0,1] op_sel_hi:[1,0,0] neg_lo:[0,0,1] neg_hi:[0,0,1]
	v_mul_f32_e32 v0, 0x3f3504f3, v96
	v_pk_add_f32 v[62:63], v[62:63], v[78:79] neg_lo:[0,1] neg_hi:[0,1]
	v_pk_mul_f32 v[76:77], v[34:35], s[22:23] op_sel_hi:[1,0]
	v_pk_add_f32 v[32:33], v[32:33], v[74:75] neg_lo:[0,1] neg_hi:[0,1]
	v_xor_b32_e32 v75, 0x80000000, v66
	v_mov_b32_e32 v74, v67
	v_mov_b32_e32 v83, v69
	v_pk_fma_f32 v[96:97], v[96:97], s[24:25], v[0:1] op_sel:[1,0,0] op_sel_hi:[1,1,0] neg_lo:[0,0,1] neg_hi:[0,0,1]
	v_mul_f32_e32 v0, 0x3f3504f3, v62
	v_pk_fma_f32 v[78:79], v[34:35], s[30:31], v[76:77] op_sel:[0,0,1] op_sel_hi:[1,0,0]
	v_pk_fma_f32 v[34:35], v[34:35], s[30:31], v[76:77] op_sel:[0,0,1] op_sel_hi:[1,0,0] neg_lo:[0,0,1] neg_hi:[0,0,1]
	v_pk_add_f32 v[66:67], v[32:33], v[74:75]
	v_mov_b32_e32 v87, v71
	v_pk_add_f32 v[68:69], v[84:85], v[82:83] neg_lo:[0,1] neg_hi:[0,1]
	v_xor_b32_e32 v93, 0x80000000, v90
	v_mov_b32_e32 v92, v91
	v_pk_add_f32 v[98:99], v[104:105], v[96:97] neg_lo:[0,1] neg_hi:[0,1]
	v_pk_fma_f32 v[62:63], v[62:63], s[24:25], v[0:1] op_sel:[1,0,0] op_sel_hi:[1,1,0] neg_lo:[0,0,1] neg_hi:[0,0,1]
	v_mov_b32_e32 v79, v35
	v_pk_add_f32 v[34:35], v[64:65], v[72:73] neg_lo:[0,1] neg_hi:[0,1]
	v_cvt_f32_ubyte0_e32 v0, v29
	v_pk_add_f32 v[70:71], v[66:67], v[86:87] neg_lo:[0,1] neg_hi:[0,1]
	v_xor_b32_e32 v81, 0x80000000, v68
	v_mov_b32_e32 v80, v69
	v_pk_add_f32 v[90:91], v[88:89], v[92:93] neg_lo:[0,1] neg_hi:[0,1]
	v_xor_b32_e32 v107, 0x80000000, v98
	v_mov_b32_e32 v106, v99
	v_pk_mul_f32 v[64:65], v[34:35], s[30:31]
	v_mul_f32_e32 v0, 0x39800000, v0
	v_pk_add_f32 v[68:69], v[70:71], v[80:81]
	v_pk_add_f32 v[98:99], v[90:91], v[106:107]
	v_pk_fma_f32 v[34:35], v[34:35], s[22:23], v[64:65] op_sel:[0,0,1] op_sel_hi:[1,0,0] neg_lo:[1,0,0] neg_hi:[1,0,0]
	v_pk_add_f32 v[70:71], v[70:71], v[80:81] neg_lo:[0,1] neg_hi:[0,1]
	v_pk_add_f32 v[80:81], v[90:91], v[106:107] neg_lo:[0,1] neg_hi:[0,1]
	v_sin_f32_e32 v90, v0
	v_pk_add_f32 v[102:103], v[94:95], v[100:101]
	v_pk_add_f32 v[64:65], v[78:79], v[34:35] neg_lo:[0,1] neg_hi:[0,1]
	v_pk_add_f32 v[34:35], v[78:79], v[34:35]
	v_pk_add_f32 v[78:79], v[94:95], v[100:101] neg_lo:[0,1] neg_hi:[0,1]
	v_cos_f32_e32 v100, v0
	v_pk_add_f32 v[32:33], v[32:33], v[74:75] neg_lo:[0,1] neg_hi:[0,1]
	v_pk_add_f32 v[66:67], v[66:67], v[86:87]
	v_pk_add_f32 v[82:83], v[84:85], v[82:83]
	v_pk_add_f32 v[74:75], v[32:33], v[62:63] neg_lo:[0,1] neg_hi:[0,1]
	v_xor_b32_e32 v73, 0x80000000, v64
	v_mov_b32_e32 v72, v65
	v_pk_add_f32 v[84:85], v[66:67], v[82:83] neg_lo:[0,1] neg_hi:[0,1]
	v_pk_add_f32 v[66:67], v[66:67], v[82:83]
	v_pk_add_f32 v[64:65], v[74:75], v[72:73]
	v_pk_add_f32 v[72:73], v[74:75], v[72:73] neg_lo:[0,1] neg_hi:[0,1]
	v_pk_mul_f32 v[74:75], v[90:91], v[66:67] op_sel:[0,1] op_sel_hi:[0,0]
	v_pk_add_f32 v[86:87], v[88:89], v[92:93]
	v_pk_add_f32 v[88:89], v[104:105], v[96:97]
	v_pk_fma_f32 v[82:83], v[100:101], v[66:67], v[74:75]
	v_pk_fma_f32 v[66:67], v[100:101], v[66:67], v[74:75] op_sel_hi:[0,1,1] neg_lo:[0,0,1] neg_hi:[0,0,1]
	v_mov_b32_e32 v101, v90
	v_pk_add_f32 v[92:93], v[86:87], v[88:89] neg_lo:[0,1] neg_hi:[0,1]
	v_mov_b32_e32 v83, v67
	v_pk_mul_f32 v[66:67], v[100:101], v[100:101]
	v_pk_add_f32 v[74:75], v[86:87], v[88:89]
	v_mul_f32_e32 v87, v100, v90
	v_mov_b32_e32 v86, v66
	v_mov_b32_e32 v66, v67
	v_mov_b32_e32 v67, v87
	v_pk_add_f32 v[114:115], v[110:111], v[112:113]
	v_pk_add_f32 v[88:89], v[86:87], v[66:67] neg_lo:[0,1] neg_hi:[0,1]
	v_pk_add_f32 v[66:67], v[86:87], v[66:67]
	v_pk_add_f32 v[116:117], v[108:109], v[114:115]
	v_pk_add_f32 v[32:33], v[32:33], v[62:63]
	v_mov_b32_e32 v86, v88
	v_mov_b32_e32 v87, v67
	v_pk_mul_f32 v[66:67], v[66:67], v[74:75] op_sel:[1,1] op_sel_hi:[1,0]
	v_mov_b32_e32 v91, v100
	v_pk_add_f32 v[30:31], v[102:103], v[116:117]
	v_pk_add_f32 v[76:77], v[102:103], v[116:117] neg_lo:[0,1] neg_hi:[0,1]
	v_pk_add_f32 v[62:63], v[32:33], v[34:35] neg_lo:[0,1] neg_hi:[0,1]
	v_pk_fma_f32 v[102:103], v[88:89], v[74:75], v[66:67]
	v_pk_fma_f32 v[66:67], v[88:89], v[74:75], v[66:67] op_sel_hi:[0,1,1] neg_lo:[0,0,1] neg_hi:[0,0,1]
	v_pk_add_f32 v[32:33], v[32:33], v[34:35]
	v_pk_mul_f32 v[34:35], v[90:91], v[86:87]
	v_mov_b32_e32 v103, v67
	v_pk_mul_f32 v[66:67], v[100:101], v[86:87]
	v_pk_add_f32 v[34:35], v[34:35], v[34:35] op_sel:[1,0] op_sel_hi:[1,0]
	v_pk_add_f32 v[66:67], v[66:67], v[66:67] op_sel:[0,1] op_sel_hi:[0,1] neg_lo:[0,1] neg_hi:[0,1]
	v_pk_mul_f32 v[34:35], v[34:35], v[32:33] op_sel:[0,1] op_sel_hi:[1,0]
	v_mul_f32_e32 v29, 4.0, v0
	v_pk_fma_f32 v[74:75], v[66:67], v[32:33], v[34:35]
	v_pk_fma_f32 v[32:33], v[66:67], v[32:33], v[34:35] neg_lo:[0,0,1] neg_hi:[0,0,1]
	v_pk_add_f32 v[94:95], v[108:109], v[114:115] neg_lo:[0,1] neg_hi:[0,1]
	v_sin_f32_e32 v32, v29
	v_cos_f32_e32 v34, v29
	v_xor_b32_e32 v97, 0x80000000, v94
	v_mov_b32_e32 v96, v95
	v_pk_add_f32 v[66:67], v[78:79], v[96:97]
	v_pk_add_f32 v[94:95], v[78:79], v[96:97] neg_lo:[0,1] neg_hi:[0,1]
	v_pk_mul_f32 v[78:79], v[32:33], v[66:67] op_sel:[0,1] op_sel_hi:[0,0]
	v_mov_b32_e32 v75, v33
	v_pk_fma_f32 v[86:87], v[34:35], v[66:67], v[78:79]
	v_pk_fma_f32 v[66:67], v[34:35], v[66:67], v[78:79] op_sel_hi:[0,1,1] neg_lo:[0,0,1] neg_hi:[0,0,1]
	v_mov_b32_e32 v35, v32
	v_mov_b32_e32 v33, v34
	v_mov_b32_e32 v87, v67
	v_pk_mul_f32 v[66:67], v[100:101], v[34:35]
	v_pk_mul_f32 v[32:33], v[100:101], v[32:33]
	v_mov_b32_e32 v34, v66
	v_mov_b32_e32 v35, v32
	v_mov_b32_e32 v32, v67
	v_pk_add_f32 v[66:67], v[34:35], v[32:33] neg_lo:[0,1] neg_hi:[0,1]
	v_pk_add_f32 v[32:33], v[34:35], v[32:33]
	v_mov_b32_e32 v34, v66
	v_mov_b32_e32 v35, v33
	v_pk_mul_f32 v[32:33], v[32:33], v[68:69] op_sel:[1,1] op_sel_hi:[1,0]
	v_mul_f32_e32 v29, 0x41000000, v0
	v_pk_fma_f32 v[78:79], v[66:67], v[68:69], v[32:33]
	v_pk_fma_f32 v[32:33], v[66:67], v[68:69], v[32:33] op_sel_hi:[0,1,1] neg_lo:[0,0,1] neg_hi:[0,0,1]
	v_mov_b32_e32 v79, v33
	v_pk_mul_f32 v[32:33], v[100:101], v[34:35]
	v_pk_mul_f32 v[34:35], v[90:91], v[34:35]
	v_mov_b32_e32 v66, v32
	v_mov_b32_e32 v67, v35
	v_pk_mov_b32 v[32:33], v[32:33], v[34:35] op_sel:[1,0]
	v_sin_f32_e32 v88, v29
	v_pk_add_f32 v[34:35], v[66:67], v[32:33] neg_lo:[0,1] neg_hi:[0,1]
	v_pk_add_f32 v[32:33], v[66:67], v[32:33]
	v_mov_b32_e32 v66, v34
	v_mov_b32_e32 v67, v33
	v_pk_mul_f32 v[32:33], v[32:33], v[98:99] op_sel:[1,1] op_sel_hi:[1,0]
	v_cos_f32_e32 v96, v29
	v_pk_fma_f32 v[68:69], v[34:35], v[98:99], v[32:33]
	v_pk_fma_f32 v[32:33], v[34:35], v[98:99], v[32:33] op_sel_hi:[0,1,1] neg_lo:[0,0,1] neg_hi:[0,0,1]
	v_pk_mul_f32 v[34:35], v[90:91], v[66:67]
	v_mov_b32_e32 v69, v33
	v_pk_mul_f32 v[32:33], v[100:101], v[66:67]
	v_pk_add_f32 v[34:35], v[34:35], v[34:35] op_sel:[1,0] op_sel_hi:[1,0]
	v_pk_add_f32 v[32:33], v[32:33], v[32:33] op_sel:[0,1] op_sel_hi:[0,1] neg_lo:[0,1] neg_hi:[0,1]
	v_pk_mul_f32 v[34:35], v[34:35], v[64:65] op_sel:[0,1] op_sel_hi:[1,0]
	v_mul_f32_e32 v0, 0x41400000, v0
	v_pk_fma_f32 v[66:67], v[32:33], v[64:65], v[34:35]
	v_pk_fma_f32 v[32:33], v[32:33], v[64:65], v[34:35] neg_lo:[0,0,1] neg_hi:[0,0,1]
	s_ashr_i32 s53, s52, 31
	v_mov_b32_e32 v67, v33
	v_pk_mul_f32 v[32:33], v[88:89], v[76:77] op_sel:[0,1] op_sel_hi:[0,0]
	v_pk_fma_f32 v[34:35], v[96:97], v[76:77], v[32:33]
	v_pk_fma_f32 v[32:33], v[96:97], v[76:77], v[32:33] op_sel_hi:[0,1,1] neg_lo:[0,0,1] neg_hi:[0,0,1]
	v_mov_b32_e32 v97, v88
	v_mov_b32_e32 v89, v96
	v_mov_b32_e32 v35, v33
	v_pk_mul_f32 v[32:33], v[100:101], v[96:97]
	v_pk_mul_f32 v[64:65], v[100:101], v[88:89]
	v_mov_b32_e32 v76, v32
	v_mov_b32_e32 v77, v64
	v_mov_b32_e32 v64, v33
	v_pk_add_f32 v[32:33], v[76:77], v[64:65] neg_lo:[0,1] neg_hi:[0,1]
	v_pk_add_f32 v[64:65], v[76:77], v[64:65]
	v_mov_b32_e32 v76, v32
	v_mov_b32_e32 v77, v65
	v_pk_mul_f32 v[64:65], v[64:65], v[84:85] op_sel:[1,1] op_sel_hi:[1,0]
	v_cos_f32_e32 v96, v0
	v_pk_fma_f32 v[88:89], v[32:33], v[84:85], v[64:65]
	v_pk_fma_f32 v[32:33], v[32:33], v[84:85], v[64:65] op_sel_hi:[0,1,1] neg_lo:[0,0,1] neg_hi:[0,0,1]
	v_mov_b32_e32 v89, v33
	v_pk_mul_f32 v[32:33], v[100:101], v[76:77]
	v_pk_mul_f32 v[64:65], v[90:91], v[76:77]
	v_mov_b32_e32 v76, v32
	v_mov_b32_e32 v77, v65
	v_pk_mov_b32 v[32:33], v[32:33], v[64:65] op_sel:[1,0]
	s_mov_b32 s10, 0
	v_pk_add_f32 v[64:65], v[76:77], v[32:33] neg_lo:[0,1] neg_hi:[0,1]
	v_pk_add_f32 v[32:33], v[76:77], v[32:33]
	v_mov_b32_e32 v76, v64
	v_mov_b32_e32 v77, v33
	v_pk_mul_f32 v[32:33], v[32:33], v[92:93] op_sel:[1,1] op_sel_hi:[1,0]
	s_nop 0
	v_pk_fma_f32 v[84:85], v[64:65], v[92:93], v[32:33]
	v_pk_fma_f32 v[32:33], v[64:65], v[92:93], v[32:33] op_sel_hi:[0,1,1] neg_lo:[0,0,1] neg_hi:[0,0,1]
	v_pk_mul_f32 v[64:65], v[90:91], v[76:77]
	v_sin_f32_e32 v92, v0
	v_mov_b32_e32 v85, v33
	v_pk_mul_f32 v[32:33], v[100:101], v[76:77]
	v_pk_add_f32 v[64:65], v[64:65], v[64:65] op_sel:[1,0] op_sel_hi:[1,0]
	v_pk_add_f32 v[32:33], v[32:33], v[32:33] op_sel:[0,1] op_sel_hi:[0,1] neg_lo:[0,1] neg_hi:[0,1]
	v_pk_mul_f32 v[64:65], v[64:65], v[62:63] op_sel:[0,1] op_sel_hi:[1,0]
	v_mov_b32_e32 v0, v208
	v_pk_fma_f32 v[76:77], v[32:33], v[62:63], v[64:65]
	v_pk_fma_f32 v[32:33], v[32:33], v[62:63], v[64:65] neg_lo:[0,0,1] neg_hi:[0,0,1]
	s_nop 0
	v_mov_b32_e32 v77, v33
	v_pk_mul_f32 v[32:33], v[92:93], v[94:95] op_sel:[0,1] op_sel_hi:[0,0]
	v_pk_fma_f32 v[62:63], v[96:97], v[94:95], v[32:33]
	v_pk_fma_f32 v[32:33], v[96:97], v[94:95], v[32:33] op_sel_hi:[0,1,1] neg_lo:[0,0,1] neg_hi:[0,0,1]
	v_mov_b32_e32 v97, v92
	v_mov_b32_e32 v93, v96
	v_mov_b32_e32 v63, v33
	v_pk_mul_f32 v[32:33], v[100:101], v[96:97]
	v_pk_mul_f32 v[64:65], v[100:101], v[92:93]
	v_mov_b32_e32 v92, v32
	v_mov_b32_e32 v93, v64
	v_mov_b32_e32 v64, v33
	v_pk_add_f32 v[32:33], v[92:93], v[64:65] neg_lo:[0,1] neg_hi:[0,1]
	v_pk_add_f32 v[64:65], v[92:93], v[64:65]
	v_mov_b32_e32 v92, v32
	v_mov_b32_e32 v93, v65
	v_pk_mul_f32 v[64:65], v[64:65], v[70:71] op_sel:[1,1] op_sel_hi:[1,0]
	s_nop 0
	v_pk_fma_f32 v[94:95], v[32:33], v[70:71], v[64:65]
	v_pk_fma_f32 v[32:33], v[32:33], v[70:71], v[64:65] op_sel_hi:[0,1,1] neg_lo:[0,0,1] neg_hi:[0,0,1]
	v_mov_b32_e32 v95, v33
	v_pk_mul_f32 v[32:33], v[100:101], v[92:93]
	v_pk_mul_f32 v[64:65], v[90:91], v[92:93]
	v_mov_b32_e32 v70, v32
	v_mov_b32_e32 v71, v65
	v_pk_mov_b32 v[32:33], v[32:33], v[64:65] op_sel:[1,0]
	s_nop 0
	v_pk_add_f32 v[64:65], v[70:71], v[32:33] neg_lo:[0,1] neg_hi:[0,1]
	v_pk_add_f32 v[32:33], v[70:71], v[32:33]
	v_mov_b32_e32 v70, v64
	v_mov_b32_e32 v71, v33
	v_pk_mul_f32 v[32:33], v[32:33], v[80:81] op_sel:[1,1] op_sel_hi:[1,0]
	s_nop 0
	v_pk_fma_f32 v[92:93], v[64:65], v[80:81], v[32:33]
	v_pk_fma_f32 v[32:33], v[64:65], v[80:81], v[32:33] op_sel_hi:[0,1,1] neg_lo:[0,0,1] neg_hi:[0,0,1]
	v_pk_mul_f32 v[64:65], v[90:91], v[70:71]
	v_mov_b32_e32 v93, v33
	v_pk_mul_f32 v[32:33], v[100:101], v[70:71]
	v_pk_add_f32 v[64:65], v[64:65], v[64:65] op_sel:[1,0] op_sel_hi:[1,0]
	v_pk_add_f32 v[32:33], v[32:33], v[32:33] op_sel:[0,1] op_sel_hi:[0,1] neg_lo:[0,1] neg_hi:[0,1]
	v_pk_mul_f32 v[64:65], v[64:65], v[72:73] op_sel:[0,1] op_sel_hi:[1,0]
	s_nop 0
	v_pk_fma_f32 v[70:71], v[32:33], v[72:73], v[64:65]
	v_pk_fma_f32 v[32:33], v[32:33], v[72:73], v[64:65] neg_lo:[0,0,1] neg_hi:[0,0,1]
	s_nop 0
	v_mov_b32_e32 v71, v33
	ds_write_b64 v55, v[30:31]
	ds_write_b64 v55, v[82:83] offset:2176
	ds_write_b64 v55, v[102:103] offset:4352
	ds_write_b64 v55, v[74:75] offset:6528
	ds_write_b64 v55, v[86:87] offset:8704
	ds_write_b64 v55, v[78:79] offset:10880
	ds_write_b64 v55, v[68:69] offset:13056
	ds_write_b64 v55, v[66:67] offset:15232
	ds_write_b64 v55, v[34:35] offset:17408
	ds_write_b64 v55, v[88:89] offset:19584
	ds_write_b64 v55, v[84:85] offset:21760
	ds_write_b64 v55, v[76:77] offset:23936
	ds_write_b64 v55, v[62:63] offset:26112
	ds_write_b64 v55, v[94:95] offset:28288
	ds_write_b64 v55, v[92:93] offset:30464
	ds_write_b64 v55, v[70:71] offset:32640
	s_waitcnt lgkmcnt(0)
	s_barrier
	s_nop 0
	v_and_b32_e32 v29, 15, v0
	v_lshlrev_b32_e32 v0, 4, v0
	v_and_b32_e32 v0, 0xffffff00, v0
	v_ashrrev_i32_e32 v30, 1, v0
	v_add_u32_e32 v30, 0, v30
	v_lshlrev_b32_e32 v0, 3, v0
	v_lshlrev_b32_e32 v31, 3, v29
	v_add3_u32 v55, v30, v0, v31
	ds_read_b64 v[32:33], v55
	ds_read_b64 v[34:35], v55 offset:136
	ds_read_b64 v[62:63], v55 offset:272
	ds_read_b64 v[64:65], v55 offset:408
	ds_read_b64 v[66:67], v55 offset:544
	ds_read_b64 v[68:69], v55 offset:680
	ds_read_b64 v[70:71], v55 offset:1088
	ds_read_b64 v[72:73], v55 offset:1224
	ds_read_b64 v[74:75], v55 offset:1632
	ds_read_b64 v[76:77], v55 offset:1768
	ds_read_b64 v[78:79], v55 offset:816
	ds_read_b64 v[80:81], v55 offset:952
	ds_read_b64 v[82:83], v55 offset:1360
	ds_read_b64 v[84:85], v55 offset:1496
	ds_read_b64 v[86:87], v55 offset:1904
	ds_read_b64 v[88:89], v55 offset:2040
	s_waitcnt lgkmcnt(8)
	v_pk_add_f32 v[104:105], v[34:35], v[72:73]
	s_waitcnt lgkmcnt(6)
	v_pk_add_f32 v[92:93], v[66:67], v[74:75]
	v_pk_add_f32 v[106:107], v[68:69], v[76:77]
	v_pk_add_f32 v[66:67], v[66:67], v[74:75] neg_lo:[0,1] neg_hi:[0,1]
	s_waitcnt lgkmcnt(0)
	v_pk_add_f32 v[74:75], v[78:79], v[86:87] neg_lo:[0,1] neg_hi:[0,1]
	v_pk_add_f32 v[68:69], v[68:69], v[76:77] neg_lo:[0,1] neg_hi:[0,1]
	v_pk_add_f32 v[96:97], v[62:63], v[82:83]
	v_pk_add_f32 v[98:99], v[78:79], v[86:87]
	v_pk_add_f32 v[62:63], v[62:63], v[82:83] neg_lo:[0,1] neg_hi:[0,1]
	v_xor_b32_e32 v79, 0x80000000, v74
	v_mov_b32_e32 v78, v75
	v_pk_add_f32 v[34:35], v[34:35], v[72:73] neg_lo:[0,1] neg_hi:[0,1]
	v_xor_b32_e32 v73, 0x80000000, v68
	v_mov_b32_e32 v72, v69
	v_pk_add_f32 v[74:75], v[62:63], v[78:79]
	v_pk_add_f32 v[68:69], v[34:35], v[72:73]
	v_pk_mul_f32 v[82:83], v[74:75], s[24:25] op_sel_hi:[1,0]
	v_pk_mul_f32 v[76:77], v[68:69], s[30:31] op_sel_hi:[1,0]
	v_pk_add_f32 v[90:91], v[32:33], v[70:71]
	v_pk_fma_f32 v[86:87], v[74:75], s[24:25], v[82:83] op_sel:[0,0,1] op_sel_hi:[1,0,0]
	v_pk_fma_f32 v[74:75], v[74:75], s[24:25], v[82:83] op_sel_hi:[1,0,0] neg_lo:[0,0,1] neg_hi:[0,0,1]
	v_pk_fma_f32 v[82:83], v[68:69], s[22:23], v[76:77] op_sel:[0,0,1] op_sel_hi:[1,0,0]
	v_pk_fma_f32 v[68:69], v[68:69], s[22:23], v[76:77] op_sel:[0,0,1] op_sel_hi:[1,0,0] neg_lo:[0,0,1] neg_hi:[0,0,1]
	v_pk_add_f32 v[94:95], v[90:91], v[92:93]
	v_pk_add_f32 v[100:101], v[96:97], v[98:99]
	v_pk_add_f32 v[112:113], v[80:81], v[88:89]
	v_mov_b32_e32 v83, v69
	v_pk_add_f32 v[68:69], v[80:81], v[88:89] neg_lo:[0,1] neg_hi:[0,1]
	v_pk_add_f32 v[88:89], v[90:91], v[92:93] neg_lo:[0,1] neg_hi:[0,1]
	v_pk_add_f32 v[90:91], v[96:97], v[98:99] neg_lo:[0,1] neg_hi:[0,1]
	v_pk_add_f32 v[96:97], v[104:105], v[106:107] neg_lo:[0,1] neg_hi:[0,1]
	v_pk_add_f32 v[110:111], v[64:65], v[84:85]
	v_pk_add_f32 v[64:65], v[64:65], v[84:85] neg_lo:[0,1] neg_hi:[0,1]
	v_xor_b32_e32 v77, 0x80000000, v68
	v_mov_b32_e32 v76, v69
	v_pk_mul_f32 v[98:99], v[96:97], s[24:25] op_sel_hi:[1,0]
	v_pk_add_f32 v[108:109], v[104:105], v[106:107]
	v_pk_add_f32 v[68:69], v[64:65], v[76:77]
	v_pk_fma_f32 v[104:105], v[96:97], s[24:25], v[98:99] op_sel:[0,0,1] op_sel_hi:[1,0,0]
	v_pk_fma_f32 v[96:97], v[96:97], s[24:25], v[98:99] op_sel_hi:[1,0,0] neg_lo:[0,0,1] neg_hi:[0,0,1]
	v_pk_mul_f32 v[80:81], v[68:69], s[22:23] op_sel_hi:[1,0]
	v_mov_b32_e32 v105, v97
	v_pk_add_f32 v[96:97], v[110:111], v[112:113] neg_lo:[0,1] neg_hi:[0,1]
	v_pk_add_f32 v[34:35], v[34:35], v[72:73] neg_lo:[0,1] neg_hi:[0,1]
	v_pk_fma_f32 v[84:85], v[68:69], s[30:31], v[80:81] op_sel:[0,0,1] op_sel_hi:[1,0,0]
	v_pk_fma_f32 v[68:69], v[68:69], s[30:31], v[80:81] op_sel:[0,0,1] op_sel_hi:[1,0,0] neg_lo:[0,0,1] neg_hi:[0,0,1]
	v_mul_f32_e32 v0, 0x3f3504f3, v96
	v_pk_add_f32 v[62:63], v[62:63], v[78:79] neg_lo:[0,1] neg_hi:[0,1]
	v_pk_mul_f32 v[72:73], v[34:35], s[22:23] op_sel_hi:[1,0]
	v_pk_add_f32 v[32:33], v[32:33], v[70:71] neg_lo:[0,1] neg_hi:[0,1]
	v_xor_b32_e32 v71, 0x80000000, v66
	v_mov_b32_e32 v70, v67
	v_mov_b32_e32 v85, v69
	v_pk_fma_f32 v[96:97], v[96:97], s[24:25], v[0:1] op_sel:[1,0,0] op_sel_hi:[1,1,0] neg_lo:[0,0,1] neg_hi:[0,0,1]
	v_mul_f32_e32 v0, 0x3f3504f3, v62
	v_pk_fma_f32 v[78:79], v[34:35], s[30:31], v[72:73] op_sel:[0,0,1] op_sel_hi:[1,0,0]
	v_pk_fma_f32 v[34:35], v[34:35], s[30:31], v[72:73] op_sel:[0,0,1] op_sel_hi:[1,0,0] neg_lo:[0,0,1] neg_hi:[0,0,1]
	v_pk_add_f32 v[66:67], v[32:33], v[70:71]
	v_mov_b32_e32 v87, v75
	v_pk_add_f32 v[68:69], v[82:83], v[84:85] neg_lo:[0,1] neg_hi:[0,1]
	v_xor_b32_e32 v93, 0x80000000, v90
	v_mov_b32_e32 v92, v91
	v_pk_add_f32 v[98:99], v[104:105], v[96:97] neg_lo:[0,1] neg_hi:[0,1]
	v_pk_fma_f32 v[62:63], v[62:63], s[24:25], v[0:1] op_sel:[1,0,0] op_sel_hi:[1,1,0] neg_lo:[0,0,1] neg_hi:[0,0,1]
	v_mov_b32_e32 v79, v35
	v_pk_add_f32 v[34:35], v[64:65], v[76:77] neg_lo:[0,1] neg_hi:[0,1]
	v_cvt_f32_ubyte0_e32 v0, v29
	v_pk_add_f32 v[74:75], v[66:67], v[86:87] neg_lo:[0,1] neg_hi:[0,1]
	v_xor_b32_e32 v81, 0x80000000, v68
	v_mov_b32_e32 v80, v69
	v_pk_add_f32 v[90:91], v[88:89], v[92:93] neg_lo:[0,1] neg_hi:[0,1]
	v_xor_b32_e32 v107, 0x80000000, v98
	v_mov_b32_e32 v106, v99
	v_pk_mul_f32 v[64:65], v[34:35], s[30:31]
	v_mul_f32_e32 v0, 0x3b800000, v0
	v_pk_add_f32 v[68:69], v[74:75], v[80:81]
	v_pk_add_f32 v[98:99], v[90:91], v[106:107]
	v_pk_fma_f32 v[34:35], v[34:35], s[22:23], v[64:65] op_sel:[0,0,1] op_sel_hi:[1,0,0] neg_lo:[1,0,0] neg_hi:[1,0,0]
	v_pk_add_f32 v[74:75], v[74:75], v[80:81] neg_lo:[0,1] neg_hi:[0,1]
	v_pk_add_f32 v[80:81], v[90:91], v[106:107] neg_lo:[0,1] neg_hi:[0,1]
	v_sin_f32_e32 v90, v0
	v_pk_add_f32 v[102:103], v[94:95], v[100:101]
	v_pk_add_f32 v[64:65], v[78:79], v[34:35] neg_lo:[0,1] neg_hi:[0,1]
	v_pk_add_f32 v[34:35], v[78:79], v[34:35]
	v_pk_add_f32 v[78:79], v[94:95], v[100:101] neg_lo:[0,1] neg_hi:[0,1]
	v_cos_f32_e32 v100, v0
	v_pk_add_f32 v[32:33], v[32:33], v[70:71] neg_lo:[0,1] neg_hi:[0,1]
	v_pk_add_f32 v[66:67], v[66:67], v[86:87]
	v_pk_add_f32 v[82:83], v[82:83], v[84:85]
	v_pk_add_f32 v[70:71], v[32:33], v[62:63] neg_lo:[0,1] neg_hi:[0,1]
	v_xor_b32_e32 v73, 0x80000000, v64
	v_mov_b32_e32 v72, v65
	v_pk_add_f32 v[84:85], v[66:67], v[82:83] neg_lo:[0,1] neg_hi:[0,1]
	v_pk_add_f32 v[66:67], v[66:67], v[82:83]
	v_pk_add_f32 v[64:65], v[70:71], v[72:73]
	v_pk_add_f32 v[70:71], v[70:71], v[72:73] neg_lo:[0,1] neg_hi:[0,1]
	v_pk_mul_f32 v[72:73], v[90:91], v[66:67] op_sel:[0,1] op_sel_hi:[0,0]
	v_pk_add_f32 v[86:87], v[88:89], v[92:93]
	v_pk_add_f32 v[88:89], v[104:105], v[96:97]
	v_pk_fma_f32 v[82:83], v[100:101], v[66:67], v[72:73]
	v_pk_fma_f32 v[66:67], v[100:101], v[66:67], v[72:73] op_sel_hi:[0,1,1] neg_lo:[0,0,1] neg_hi:[0,0,1]
	v_mov_b32_e32 v101, v90
	v_pk_add_f32 v[92:93], v[86:87], v[88:89] neg_lo:[0,1] neg_hi:[0,1]
	v_mov_b32_e32 v83, v67
	v_pk_mul_f32 v[66:67], v[100:101], v[100:101]
	v_pk_add_f32 v[72:73], v[86:87], v[88:89]
	v_mul_f32_e32 v87, v100, v90
	v_mov_b32_e32 v86, v66
	v_mov_b32_e32 v66, v67
	v_mov_b32_e32 v67, v87
	v_pk_add_f32 v[114:115], v[110:111], v[112:113]
	v_pk_add_f32 v[88:89], v[86:87], v[66:67] neg_lo:[0,1] neg_hi:[0,1]
	v_pk_add_f32 v[66:67], v[86:87], v[66:67]
	v_pk_add_f32 v[116:117], v[108:109], v[114:115]
	v_pk_add_f32 v[32:33], v[32:33], v[62:63]
	v_mov_b32_e32 v86, v88
	v_mov_b32_e32 v87, v67
	v_pk_mul_f32 v[66:67], v[66:67], v[72:73] op_sel:[1,1] op_sel_hi:[1,0]
	v_mov_b32_e32 v91, v100
	v_pk_add_f32 v[30:31], v[102:103], v[116:117]
	v_pk_add_f32 v[76:77], v[102:103], v[116:117] neg_lo:[0,1] neg_hi:[0,1]
	v_pk_add_f32 v[62:63], v[32:33], v[34:35] neg_lo:[0,1] neg_hi:[0,1]
	v_pk_fma_f32 v[102:103], v[88:89], v[72:73], v[66:67]
	v_pk_fma_f32 v[66:67], v[88:89], v[72:73], v[66:67] op_sel_hi:[0,1,1] neg_lo:[0,0,1] neg_hi:[0,0,1]
	v_pk_add_f32 v[32:33], v[32:33], v[34:35]
	v_pk_mul_f32 v[34:35], v[90:91], v[86:87]
	v_mov_b32_e32 v103, v67
	v_pk_mul_f32 v[66:67], v[100:101], v[86:87]
	v_pk_add_f32 v[34:35], v[34:35], v[34:35] op_sel:[1,0] op_sel_hi:[1,0]
	v_pk_add_f32 v[66:67], v[66:67], v[66:67] op_sel:[0,1] op_sel_hi:[0,1] neg_lo:[0,1] neg_hi:[0,1]
	v_pk_mul_f32 v[34:35], v[34:35], v[32:33] op_sel:[0,1] op_sel_hi:[1,0]
	v_mul_f32_e32 v29, 4.0, v0
	v_pk_fma_f32 v[72:73], v[66:67], v[32:33], v[34:35]
	v_pk_fma_f32 v[32:33], v[66:67], v[32:33], v[34:35] neg_lo:[0,0,1] neg_hi:[0,0,1]
	v_pk_add_f32 v[94:95], v[108:109], v[114:115] neg_lo:[0,1] neg_hi:[0,1]
	v_sin_f32_e32 v32, v29
	v_cos_f32_e32 v34, v29
	v_xor_b32_e32 v97, 0x80000000, v94
	v_mov_b32_e32 v96, v95
	v_pk_add_f32 v[66:67], v[78:79], v[96:97]
	v_pk_add_f32 v[94:95], v[78:79], v[96:97] neg_lo:[0,1] neg_hi:[0,1]
	v_pk_mul_f32 v[78:79], v[32:33], v[66:67] op_sel:[0,1] op_sel_hi:[0,0]
	v_mov_b32_e32 v73, v33
	v_pk_fma_f32 v[86:87], v[34:35], v[66:67], v[78:79]
	v_pk_fma_f32 v[66:67], v[34:35], v[66:67], v[78:79] op_sel_hi:[0,1,1] neg_lo:[0,0,1] neg_hi:[0,0,1]
	v_mov_b32_e32 v35, v32
	v_mov_b32_e32 v33, v34
	v_mov_b32_e32 v87, v67
	v_pk_mul_f32 v[66:67], v[100:101], v[34:35]
	v_pk_mul_f32 v[32:33], v[100:101], v[32:33]
	v_mov_b32_e32 v34, v66
	v_mov_b32_e32 v35, v32
	v_mov_b32_e32 v32, v67
	v_pk_add_f32 v[66:67], v[34:35], v[32:33] neg_lo:[0,1] neg_hi:[0,1]
	v_pk_add_f32 v[32:33], v[34:35], v[32:33]
	v_mov_b32_e32 v34, v66
	v_mov_b32_e32 v35, v33
	v_pk_mul_f32 v[32:33], v[32:33], v[68:69] op_sel:[1,1] op_sel_hi:[1,0]
	v_mul_f32_e32 v29, 0x41000000, v0
	v_pk_fma_f32 v[78:79], v[66:67], v[68:69], v[32:33]
	v_pk_fma_f32 v[32:33], v[66:67], v[68:69], v[32:33] op_sel_hi:[0,1,1] neg_lo:[0,0,1] neg_hi:[0,0,1]
	v_mov_b32_e32 v79, v33
	v_pk_mul_f32 v[32:33], v[100:101], v[34:35]
	v_pk_mul_f32 v[34:35], v[90:91], v[34:35]
	v_mov_b32_e32 v66, v32
	v_mov_b32_e32 v67, v35
	v_pk_mov_b32 v[32:33], v[32:33], v[34:35] op_sel:[1,0]
	v_sin_f32_e32 v88, v29
	v_pk_add_f32 v[34:35], v[66:67], v[32:33] neg_lo:[0,1] neg_hi:[0,1]
	v_pk_add_f32 v[32:33], v[66:67], v[32:33]
	v_mov_b32_e32 v66, v34
	v_mov_b32_e32 v67, v33
	v_pk_mul_f32 v[32:33], v[32:33], v[98:99] op_sel:[1,1] op_sel_hi:[1,0]
	v_cos_f32_e32 v96, v29
	v_pk_fma_f32 v[68:69], v[34:35], v[98:99], v[32:33]
	v_pk_fma_f32 v[32:33], v[34:35], v[98:99], v[32:33] op_sel_hi:[0,1,1] neg_lo:[0,0,1] neg_hi:[0,0,1]
	v_pk_mul_f32 v[34:35], v[90:91], v[66:67]
	v_mov_b32_e32 v69, v33
	v_pk_mul_f32 v[32:33], v[100:101], v[66:67]
	v_pk_add_f32 v[34:35], v[34:35], v[34:35] op_sel:[1,0] op_sel_hi:[1,0]
	v_pk_add_f32 v[32:33], v[32:33], v[32:33] op_sel:[0,1] op_sel_hi:[0,1] neg_lo:[0,1] neg_hi:[0,1]
	v_pk_mul_f32 v[34:35], v[34:35], v[64:65] op_sel:[0,1] op_sel_hi:[1,0]
	v_mul_f32_e32 v0, 0x41400000, v0
	v_pk_fma_f32 v[66:67], v[32:33], v[64:65], v[34:35]
	v_pk_fma_f32 v[32:33], v[32:33], v[64:65], v[34:35] neg_lo:[0,0,1] neg_hi:[0,0,1]
	s_nop 0
	v_mov_b32_e32 v67, v33
	v_pk_mul_f32 v[32:33], v[88:89], v[76:77] op_sel:[0,1] op_sel_hi:[0,0]
	v_pk_fma_f32 v[34:35], v[96:97], v[76:77], v[32:33]
	v_pk_fma_f32 v[32:33], v[96:97], v[76:77], v[32:33] op_sel_hi:[0,1,1] neg_lo:[0,0,1] neg_hi:[0,0,1]
	v_mov_b32_e32 v97, v88
	v_mov_b32_e32 v89, v96
	v_mov_b32_e32 v35, v33
	v_pk_mul_f32 v[32:33], v[100:101], v[96:97]
	v_pk_mul_f32 v[64:65], v[100:101], v[88:89]
	v_mov_b32_e32 v76, v32
	v_mov_b32_e32 v77, v64
	v_mov_b32_e32 v64, v33
	v_pk_add_f32 v[32:33], v[76:77], v[64:65] neg_lo:[0,1] neg_hi:[0,1]
	v_pk_add_f32 v[64:65], v[76:77], v[64:65]
	v_mov_b32_e32 v76, v32
	v_mov_b32_e32 v77, v65
	v_pk_mul_f32 v[64:65], v[64:65], v[84:85] op_sel:[1,1] op_sel_hi:[1,0]
	v_cos_f32_e32 v96, v0
	v_pk_fma_f32 v[88:89], v[32:33], v[84:85], v[64:65]
	v_pk_fma_f32 v[32:33], v[32:33], v[84:85], v[64:65] op_sel_hi:[0,1,1] neg_lo:[0,0,1] neg_hi:[0,0,1]
	v_mov_b32_e32 v89, v33
	v_pk_mul_f32 v[32:33], v[100:101], v[76:77]
	v_pk_mul_f32 v[64:65], v[90:91], v[76:77]
	v_mov_b32_e32 v76, v32
	v_mov_b32_e32 v77, v65
	v_pk_mov_b32 v[32:33], v[32:33], v[64:65] op_sel:[1,0]
	s_nop 0
	v_pk_add_f32 v[64:65], v[76:77], v[32:33] neg_lo:[0,1] neg_hi:[0,1]
	v_pk_add_f32 v[32:33], v[76:77], v[32:33]
	v_mov_b32_e32 v76, v64
	v_mov_b32_e32 v77, v33
	v_pk_mul_f32 v[32:33], v[32:33], v[92:93] op_sel:[1,1] op_sel_hi:[1,0]
	s_nop 0
	v_pk_fma_f32 v[84:85], v[64:65], v[92:93], v[32:33]
	v_pk_fma_f32 v[32:33], v[64:65], v[92:93], v[32:33] op_sel_hi:[0,1,1] neg_lo:[0,0,1] neg_hi:[0,0,1]
	v_pk_mul_f32 v[64:65], v[90:91], v[76:77]
	v_sin_f32_e32 v92, v0
	v_mov_b32_e32 v85, v33
	v_pk_mul_f32 v[32:33], v[100:101], v[76:77]
	v_pk_add_f32 v[64:65], v[64:65], v[64:65] op_sel:[1,0] op_sel_hi:[1,0]
	v_pk_add_f32 v[32:33], v[32:33], v[32:33] op_sel:[0,1] op_sel_hi:[0,1] neg_lo:[0,1] neg_hi:[0,1]
	v_pk_mul_f32 v[64:65], v[64:65], v[62:63] op_sel:[0,1] op_sel_hi:[1,0]
	v_mov_b32_e32 v0, v208
	v_pk_fma_f32 v[76:77], v[32:33], v[62:63], v[64:65]
	v_pk_fma_f32 v[32:33], v[32:33], v[62:63], v[64:65] neg_lo:[0,0,1] neg_hi:[0,0,1]
	s_nop 0
	v_mov_b32_e32 v77, v33
	v_pk_mul_f32 v[32:33], v[92:93], v[94:95] op_sel:[0,1] op_sel_hi:[0,0]
	v_pk_fma_f32 v[62:63], v[96:97], v[94:95], v[32:33]
	v_pk_fma_f32 v[32:33], v[96:97], v[94:95], v[32:33] op_sel_hi:[0,1,1] neg_lo:[0,0,1] neg_hi:[0,0,1]
	v_mov_b32_e32 v97, v92
	v_mov_b32_e32 v93, v96
	v_mov_b32_e32 v63, v33
	v_pk_mul_f32 v[32:33], v[100:101], v[96:97]
	v_pk_mul_f32 v[64:65], v[100:101], v[92:93]
	v_mov_b32_e32 v92, v32
	v_mov_b32_e32 v93, v64
	v_mov_b32_e32 v64, v33
	v_pk_add_f32 v[32:33], v[92:93], v[64:65] neg_lo:[0,1] neg_hi:[0,1]
	v_pk_add_f32 v[64:65], v[92:93], v[64:65]
	v_mov_b32_e32 v92, v32
	v_mov_b32_e32 v93, v65
	v_pk_mul_f32 v[64:65], v[64:65], v[74:75] op_sel:[1,1] op_sel_hi:[1,0]
	s_nop 0
	v_pk_fma_f32 v[94:95], v[32:33], v[74:75], v[64:65]
	v_pk_fma_f32 v[32:33], v[32:33], v[74:75], v[64:65] op_sel_hi:[0,1,1] neg_lo:[0,0,1] neg_hi:[0,0,1]
	v_mov_b32_e32 v95, v33
	v_pk_mul_f32 v[32:33], v[100:101], v[92:93]
	v_pk_mul_f32 v[64:65], v[90:91], v[92:93]
	v_mov_b32_e32 v74, v32
	v_mov_b32_e32 v75, v65
	v_pk_mov_b32 v[32:33], v[32:33], v[64:65] op_sel:[1,0]
	s_nop 0
	v_pk_add_f32 v[64:65], v[74:75], v[32:33] neg_lo:[0,1] neg_hi:[0,1]
	v_pk_add_f32 v[32:33], v[74:75], v[32:33]
	v_mov_b32_e32 v74, v64
	v_mov_b32_e32 v75, v33
	v_pk_mul_f32 v[32:33], v[32:33], v[80:81] op_sel:[1,1] op_sel_hi:[1,0]
	s_nop 0
	v_pk_fma_f32 v[92:93], v[64:65], v[80:81], v[32:33]
	v_pk_fma_f32 v[32:33], v[64:65], v[80:81], v[32:33] op_sel_hi:[0,1,1] neg_lo:[0,0,1] neg_hi:[0,0,1]
	v_pk_mul_f32 v[64:65], v[90:91], v[74:75]
	v_mov_b32_e32 v93, v33
	v_pk_mul_f32 v[32:33], v[100:101], v[74:75]
	v_pk_add_f32 v[64:65], v[64:65], v[64:65] op_sel:[1,0] op_sel_hi:[1,0]
	v_pk_add_f32 v[32:33], v[32:33], v[32:33] op_sel:[0,1] op_sel_hi:[0,1] neg_lo:[0,1] neg_hi:[0,1]
	v_pk_mul_f32 v[64:65], v[64:65], v[70:71] op_sel:[0,1] op_sel_hi:[1,0]
	s_nop 0
	v_pk_fma_f32 v[74:75], v[32:33], v[70:71], v[64:65]
	v_pk_fma_f32 v[32:33], v[32:33], v[70:71], v[64:65] neg_lo:[0,0,1] neg_hi:[0,0,1]
	s_nop 0
	v_mov_b32_e32 v75, v33
	ds_write2_b64 v55, v[30:31], v[82:83] offset1:17
	ds_write2_b64 v55, v[102:103], v[72:73] offset0:34 offset1:51
	ds_write2_b64 v55, v[86:87], v[78:79] offset0:68 offset1:85
	ds_write2_b64 v55, v[68:69], v[66:67] offset0:102 offset1:119
	ds_write2_b64 v55, v[34:35], v[88:89] offset0:136 offset1:153
	ds_write2_b64 v55, v[84:85], v[76:77] offset0:170 offset1:187
	ds_write2_b64 v55, v[62:63], v[94:95] offset0:204 offset1:221
	ds_write2_b64 v55, v[92:93], v[74:75] offset0:238 offset1:255
	s_waitcnt lgkmcnt(0)
	s_nop 0
	v_lshlrev_b32_e32 v29, 4, v0
	v_ashrrev_i32_e32 v29, 1, v29
	v_lshlrev_b32_e32 v0, 7, v0
	v_add3_u32 v29, 0, v29, v0
	ds_read_b64 v[30:31], v29
	ds_read_b64 v[32:33], v29 offset:8
	ds_read_b64 v[62:63], v29 offset:16
	ds_read_b64 v[64:65], v29 offset:24
	ds_read_b64 v[66:67], v29 offset:64
	ds_read_b64 v[68:69], v29 offset:72
	ds_read_b64 v[70:71], v29 offset:32
	ds_read_b64 v[72:73], v29 offset:40
	ds_read_b64 v[74:75], v29 offset:48
	ds_read_b64 v[76:77], v29 offset:56
	ds_read_b64 v[78:79], v29 offset:96
	ds_read_b64 v[80:81], v29 offset:104
	ds_read_b64 v[82:83], v29 offset:80
	ds_read_b64 v[84:85], v29 offset:88
	ds_read_b64 v[86:87], v29 offset:112
	ds_read_b64 v[88:89], v29 offset:120
	s_waitcnt lgkmcnt(10)
	v_pk_add_f32 v[34:35], v[30:31], v[66:67]
	v_pk_add_f32 v[30:31], v[30:31], v[66:67] neg_lo:[0,1] neg_hi:[0,1]
	s_waitcnt lgkmcnt(4)
	v_pk_add_f32 v[66:67], v[70:71], v[78:79]
	v_pk_add_f32 v[70:71], v[70:71], v[78:79] neg_lo:[0,1] neg_hi:[0,1]
	s_nop 0
	v_xor_b32_e32 v79, 0x80000000, v70
	v_mov_b32_e32 v78, v71
	v_pk_add_f32 v[70:71], v[34:35], v[66:67]
	v_pk_add_f32 v[34:35], v[34:35], v[66:67] neg_lo:[0,1] neg_hi:[0,1]
	v_pk_add_f32 v[66:67], v[30:31], v[78:79]
	v_pk_add_f32 v[30:31], v[30:31], v[78:79] neg_lo:[0,1] neg_hi:[0,1]
	v_pk_add_f32 v[78:79], v[32:33], v[68:69]
	v_pk_add_f32 v[32:33], v[32:33], v[68:69] neg_lo:[0,1] neg_hi:[0,1]
	v_pk_add_f32 v[68:69], v[72:73], v[80:81]
	v_pk_add_f32 v[72:73], v[72:73], v[80:81] neg_lo:[0,1] neg_hi:[0,1]
	s_nop 0
	v_xor_b32_e32 v81, 0x80000000, v72
	v_mov_b32_e32 v80, v73
	v_pk_add_f32 v[72:73], v[78:79], v[68:69]
	v_pk_add_f32 v[68:69], v[78:79], v[68:69] neg_lo:[0,1] neg_hi:[0,1]
	v_pk_add_f32 v[78:79], v[32:33], v[80:81]
	v_pk_add_f32 v[32:33], v[32:33], v[80:81] neg_lo:[0,1] neg_hi:[0,1]
	s_waitcnt lgkmcnt(2)
	v_pk_add_f32 v[80:81], v[62:63], v[82:83]
	v_pk_add_f32 v[62:63], v[62:63], v[82:83] neg_lo:[0,1] neg_hi:[0,1]
	s_waitcnt lgkmcnt(0)
	v_pk_add_f32 v[82:83], v[74:75], v[86:87]
	v_pk_add_f32 v[74:75], v[74:75], v[86:87] neg_lo:[0,1] neg_hi:[0,1]
	s_nop 0
	v_xor_b32_e32 v87, 0x80000000, v74
	v_mov_b32_e32 v86, v75
	v_pk_add_f32 v[74:75], v[80:81], v[82:83]
	v_pk_add_f32 v[80:81], v[80:81], v[82:83] neg_lo:[0,1] neg_hi:[0,1]
	v_pk_add_f32 v[82:83], v[62:63], v[86:87]
	v_pk_add_f32 v[62:63], v[62:63], v[86:87] neg_lo:[0,1] neg_hi:[0,1]
	v_pk_add_f32 v[86:87], v[64:65], v[84:85]
	v_pk_add_f32 v[64:65], v[64:65], v[84:85] neg_lo:[0,1] neg_hi:[0,1]
	v_pk_add_f32 v[84:85], v[76:77], v[88:89]
	v_pk_add_f32 v[76:77], v[76:77], v[88:89] neg_lo:[0,1] neg_hi:[0,1]
	v_mul_f32_e32 v0, 0x3f3504f3, v62
	v_xor_b32_e32 v89, 0x80000000, v76
	v_mov_b32_e32 v88, v77
	v_pk_add_f32 v[76:77], v[86:87], v[84:85]
	v_pk_add_f32 v[84:85], v[86:87], v[84:85] neg_lo:[0,1] neg_hi:[0,1]
	v_pk_add_f32 v[86:87], v[64:65], v[88:89]
	v_pk_add_f32 v[64:65], v[64:65], v[88:89] neg_lo:[0,1] neg_hi:[0,1]
	v_pk_mul_f32 v[88:89], v[78:79], s[30:31] op_sel_hi:[1,0]
	v_pk_fma_f32 v[62:63], v[62:63], s[24:25], v[0:1] op_sel:[1,0,0] op_sel_hi:[1,1,0] neg_lo:[0,0,1] neg_hi:[0,0,1]
	v_pk_fma_f32 v[90:91], v[78:79], s[22:23], v[88:89] op_sel:[0,0,1] op_sel_hi:[1,0,0]
	v_pk_fma_f32 v[78:79], v[78:79], s[22:23], v[88:89] op_sel:[0,0,1] op_sel_hi:[1,0,0] neg_lo:[0,0,1] neg_hi:[0,0,1]
	v_mul_f32_e32 v0, 0x3f3504f3, v84
	v_mov_b32_e32 v91, v79
	v_pk_mul_f32 v[78:79], v[68:69], s[24:25] op_sel_hi:[1,0]
	s_nop 0
	v_pk_fma_f32 v[88:89], v[68:69], s[24:25], v[78:79] op_sel:[0,0,1] op_sel_hi:[1,0,0]
	v_pk_fma_f32 v[68:69], v[68:69], s[24:25], v[78:79] op_sel_hi:[1,0,0] neg_lo:[0,0,1] neg_hi:[0,0,1]
	s_nop 0
	v_mov_b32_e32 v89, v69
	v_pk_mul_f32 v[68:69], v[32:33], s[22:23] op_sel_hi:[1,0]
	s_nop 0
	v_pk_fma_f32 v[78:79], v[32:33], s[30:31], v[68:69] op_sel:[0,0,1] op_sel_hi:[1,0,0]
	v_pk_fma_f32 v[32:33], v[32:33], s[30:31], v[68:69] op_sel:[0,0,1] op_sel_hi:[1,0,0] neg_lo:[0,0,1] neg_hi:[0,0,1]
	s_nop 0
	v_mov_b32_e32 v79, v33
	v_pk_mul_f32 v[32:33], v[82:83], s[24:25] op_sel_hi:[1,0]
	s_nop 0
	v_pk_fma_f32 v[68:69], v[82:83], s[24:25], v[32:33] op_sel:[0,0,1] op_sel_hi:[1,0,0]
	v_pk_fma_f32 v[32:33], v[82:83], s[24:25], v[32:33] op_sel_hi:[1,0,0] neg_lo:[0,0,1] neg_hi:[0,0,1]
	s_nop 0
	v_mov_b32_e32 v69, v33
	v_xor_b32_e32 v33, 0x80000000, v80
	v_mov_b32_e32 v32, v81
	v_pk_mul_f32 v[80:81], v[86:87], s[22:23] op_sel_hi:[1,0]
	s_nop 0
	v_pk_fma_f32 v[82:83], v[86:87], s[30:31], v[80:81] op_sel:[0,0,1] op_sel_hi:[1,0,0]
	v_pk_fma_f32 v[80:81], v[86:87], s[30:31], v[80:81] op_sel:[0,0,1] op_sel_hi:[1,0,0] neg_lo:[0,0,1] neg_hi:[0,0,1]
	s_nop 0
	v_mov_b32_e32 v83, v81
	v_pk_fma_f32 v[80:81], v[84:85], s[24:25], v[0:1] op_sel:[1,0,0] op_sel_hi:[1,1,0] neg_lo:[0,0,1] neg_hi:[0,0,1]
	v_pk_mul_f32 v[84:85], v[64:65], s[30:31]
	v_mul_f32_e32 v0, v7, v138
	v_pk_fma_f32 v[64:65], v[64:65], s[22:23], v[84:85] op_sel:[0,0,1] op_sel_hi:[1,0,0] neg_lo:[1,0,0] neg_hi:[1,0,0]
	v_pk_add_f32 v[84:85], v[70:71], v[74:75]
	v_pk_add_f32 v[70:71], v[70:71], v[74:75] neg_lo:[0,1] neg_hi:[0,1]
	v_pk_add_f32 v[74:75], v[72:73], v[76:77]
	v_pk_add_f32 v[72:73], v[72:73], v[76:77] neg_lo:[0,1] neg_hi:[0,1]
	s_nop 0
	v_xor_b32_e32 v77, 0x80000000, v72
	v_mov_b32_e32 v76, v73
	v_pk_add_f32 v[72:73], v[84:85], v[74:75]
	v_pk_add_f32 v[74:75], v[84:85], v[74:75] neg_lo:[0,1] neg_hi:[0,1]
	v_pk_add_f32 v[84:85], v[70:71], v[76:77]
	v_pk_add_f32 v[70:71], v[70:71], v[76:77] neg_lo:[0,1] neg_hi:[0,1]
	v_pk_add_f32 v[76:77], v[66:67], v[68:69]
	v_pk_add_f32 v[66:67], v[66:67], v[68:69] neg_lo:[0,1] neg_hi:[0,1]
	v_pk_add_f32 v[68:69], v[90:91], v[82:83]
	v_pk_add_f32 v[82:83], v[90:91], v[82:83] neg_lo:[0,1] neg_hi:[0,1]
	s_nop 0
	v_xor_b32_e32 v87, 0x80000000, v82
	v_mov_b32_e32 v86, v83
	v_pk_add_f32 v[82:83], v[76:77], v[68:69]
	v_pk_add_f32 v[68:69], v[76:77], v[68:69] neg_lo:[0,1] neg_hi:[0,1]
	v_pk_add_f32 v[76:77], v[66:67], v[86:87]
	v_pk_add_f32 v[66:67], v[66:67], v[86:87] neg_lo:[0,1] neg_hi:[0,1]
	v_pk_add_f32 v[86:87], v[34:35], v[32:33]
	v_pk_add_f32 v[32:33], v[34:35], v[32:33] neg_lo:[0,1] neg_hi:[0,1]
	v_pk_add_f32 v[34:35], v[88:89], v[80:81]
	v_pk_add_f32 v[80:81], v[88:89], v[80:81] neg_lo:[0,1] neg_hi:[0,1]
	s_nop 0
	v_xor_b32_e32 v89, 0x80000000, v80
	v_mov_b32_e32 v88, v81
	v_pk_add_f32 v[80:81], v[86:87], v[34:35]
	v_pk_add_f32 v[34:35], v[86:87], v[34:35] neg_lo:[0,1] neg_hi:[0,1]
	v_pk_add_f32 v[86:87], v[32:33], v[88:89]
	v_pk_add_f32 v[32:33], v[32:33], v[88:89] neg_lo:[0,1] neg_hi:[0,1]
	v_pk_add_f32 v[88:89], v[30:31], v[62:63]
	v_pk_add_f32 v[30:31], v[30:31], v[62:63] neg_lo:[0,1] neg_hi:[0,1]
	v_pk_add_f32 v[62:63], v[78:79], v[64:65]
	v_pk_add_f32 v[64:65], v[78:79], v[64:65] neg_lo:[0,1] neg_hi:[0,1]
	s_nop 0
	v_xor_b32_e32 v79, 0x80000000, v64
	v_mov_b32_e32 v78, v65
	v_pk_add_f32 v[64:65], v[88:89], v[62:63]
	v_pk_add_f32 v[62:63], v[88:89], v[62:63] neg_lo:[0,1] neg_hi:[0,1]
	v_pk_add_f32 v[88:89], v[30:31], v[78:79]
	v_pk_add_f32 v[30:31], v[30:31], v[78:79] neg_lo:[0,1] neg_hi:[0,1]
	ds_write2_b64 v29, v[72:73], v[82:83] offset1:1
	ds_write2_b64 v29, v[80:81], v[64:65] offset0:2 offset1:3
	ds_write2_b64 v29, v[84:85], v[76:77] offset0:4 offset1:5
	ds_write2_b64 v29, v[86:87], v[88:89] offset0:6 offset1:7
	ds_write2_b64 v29, v[74:75], v[68:69] offset0:8 offset1:9
	ds_write2_b64 v29, v[34:35], v[62:63] offset0:10 offset1:11
	ds_write2_b64 v29, v[70:71], v[66:67] offset0:12 offset1:13
	ds_write2_b64 v29, v[32:33], v[30:31] offset0:14 offset1:15
	v_cos_f32_e32 v30, v0
	v_sin_f32_e32 v32, v0
	v_add_u32_e32 v0, s52, v48
	v_ashrrev_i32_e32 v29, 4, v0
	v_lshlrev_b32_e32 v29, 3, v29
	v_lshlrev_b32_e32 v55, 3, v0
	v_add3_u32 v0, s35, v29, v55
	v_mul_f32_e32 v29, v7, v141
	v_cos_f32_e32 v31, v29
	v_sin_f32_e32 v33, v29
	v_add_u32_e32 v29, s52, v140
	v_ashrrev_i32_e32 v29, 4, v29
	v_lshlrev_b32_e32 v29, 3, v29
	v_add3_u32 v165, s35, v29, v55
	v_mul_f32_e32 v29, v7, v143
	v_cos_f32_e32 v34, v29
	v_sin_f32_e32 v62, v29
	v_add_u32_e32 v29, s52, v142
	v_ashrrev_i32_e32 v29, 4, v29
	v_lshlrev_b32_e32 v29, 3, v29
	v_add3_u32 v166, s35, v29, v55
	v_mul_f32_e32 v29, v7, v145
	v_cos_f32_e32 v35, v29
	v_sin_f32_e32 v63, v29
	v_add_u32_e32 v29, s52, v144
	v_ashrrev_i32_e32 v29, 4, v29
	v_lshlrev_b32_e32 v29, 3, v29
	v_add3_u32 v167, s35, v29, v55
	v_mul_f32_e32 v29, v7, v147
	v_cos_f32_e32 v64, v29
	v_sin_f32_e32 v66, v29
	v_add_u32_e32 v29, s52, v146
	v_ashrrev_i32_e32 v29, 4, v29
	v_lshlrev_b32_e32 v29, 3, v29
	v_add3_u32 v168, s35, v29, v55
	v_mul_f32_e32 v29, v7, v149
	v_cos_f32_e32 v65, v29
	v_sin_f32_e32 v67, v29
	v_add_u32_e32 v29, s52, v148
	v_ashrrev_i32_e32 v29, 4, v29
	v_lshlrev_b32_e32 v29, 3, v29
	v_add3_u32 v169, s35, v29, v55
	v_mul_f32_e32 v29, v7, v151
	v_mul_f32_e32 v7, v7, v153
	v_cos_f32_e32 v68, v29
	v_sin_f32_e32 v70, v29
	v_cos_f32_e32 v69, v7
	v_sin_f32_e32 v71, v7
	v_add_u32_e32 v29, s52, v150
	v_add_u32_e32 v7, s52, v152
	v_ashrrev_i32_e32 v29, 4, v29
	v_ashrrev_i32_e32 v7, 4, v7
	v_lshlrev_b32_e32 v29, 3, v29
	v_lshlrev_b32_e32 v7, 3, v7
	v_add3_u32 v174, s35, v29, v55
	v_add3_u32 v175, s35, v7, v55
	v_mov_b32_e32 v55, v54
	v_mov_b32_e32 v7, v6
	v_mov_b32_e32 v29, v28
	v_mov_b32_e32 v72, v30
	v_mov_b32_e32 v73, v30
	v_mov_b32_e32 v74, v32
	v_mov_b32_e32 v75, v32
	v_mov_b32_e32 v76, v31
	v_mov_b32_e32 v77, v31
	v_mov_b32_e32 v78, v33
	v_mov_b32_e32 v79, v33
	v_mov_b32_e32 v80, v34
	v_mov_b32_e32 v81, v34
	v_mov_b32_e32 v82, v62
	v_mov_b32_e32 v83, v62
	v_mov_b32_e32 v84, v35
	v_mov_b32_e32 v85, v35
	v_mov_b32_e32 v86, v63
	v_mov_b32_e32 v87, v63
	v_mov_b32_e32 v88, v64
	v_mov_b32_e32 v89, v64
	v_mov_b32_e32 v90, v66
	v_mov_b32_e32 v91, v66
	v_mov_b32_e32 v92, v65
	v_mov_b32_e32 v93, v65
	v_mov_b32_e32 v94, v67
	v_mov_b32_e32 v95, v67
	v_mov_b32_e32 v96, v68
	v_mov_b32_e32 v97, v68
	v_mov_b32_e32 v98, v70
	v_mov_b32_e32 v99, v70
	v_mov_b32_e32 v100, v69
	v_mov_b32_e32 v101, v69
	v_mov_b32_e32 v102, v71
	v_mov_b32_e32 v103, v71
	s_waitcnt lgkmcnt(0)
	s_barrier
	s_branch .LBB0_277

.LBB0_299:
	s_or_b64 exec, exec, s[16:17]
	v_mov_b32_e32 v206, v208
	s_waitcnt lgkmcnt(0)
	s_barrier
	s_xor_b64 s[16:17], s[18:19], -1
	v_and_b32_e32 v104, 0xff, v206
	v_lshlrev_b32_e32 v105, 4, v206
	v_and_or_b32 v104, v105, s93, v104
	v_ashrrev_i32_e32 v105, 4, v104
	v_lshlrev_b32_e32 v105, 3, v105
	v_lshlrev_b32_e32 v104, 3, v104
	v_add3_u32 v207, s35, v105, v104
	ds_read_b64 v[106:107], v207
	ds_read_b64 v[108:109], v207 offset:2176
	ds_read_b64 v[110:111], v207 offset:4352
	ds_read_b64 v[112:113], v207 offset:6528
	ds_read_b64 v[114:115], v207 offset:8704
	ds_read_b64 v[116:117], v207 offset:10880
	ds_read_b64 v[118:119], v207 offset:13056
	ds_read_b64 v[120:121], v207 offset:15232
	ds_read_b64 v[122:123], v207 offset:17408
	ds_read_b64 v[124:125], v207 offset:19584
	ds_read_b64 v[126:127], v207 offset:21760
	ds_read_b64 v[128:129], v207 offset:23936
	ds_read_b64 v[130:131], v207 offset:26112
	ds_read_b64 v[132:133], v207 offset:28288
	ds_read_b64 v[134:135], v207 offset:30464
	ds_read_b64 v[176:177], v207 offset:32640
	s_waitcnt lgkmcnt(5)
	v_pk_add_f32 v[184:185], v[110:111], v[126:127]
	v_pk_add_f32 v[110:111], v[110:111], v[126:127] neg_lo:[0,1] neg_hi:[0,1]
	s_waitcnt lgkmcnt(2)
	v_pk_add_f32 v[194:195], v[116:117], v[132:133]
	s_waitcnt lgkmcnt(1)
	v_pk_add_f32 v[186:187], v[118:119], v[134:135]
	v_pk_add_f32 v[118:119], v[118:119], v[134:135] neg_lo:[0,1] neg_hi:[0,1]
	v_pk_add_f32 v[116:117], v[116:117], v[132:133] neg_lo:[0,1] neg_hi:[0,1]
	v_xor_b32_e32 v127, 0x80000000, v118
	v_mov_b32_e32 v126, v119
	v_pk_add_f32 v[192:193], v[108:109], v[124:125]
	v_pk_add_f32 v[118:119], v[110:111], v[126:127]
	v_pk_add_f32 v[108:109], v[108:109], v[124:125] neg_lo:[0,1] neg_hi:[0,1]
	v_xor_b32_e32 v125, 0x80000000, v116
	v_mov_b32_e32 v124, v117
	v_pk_add_f32 v[180:181], v[114:115], v[130:131]
	v_pk_add_f32 v[114:115], v[114:115], v[130:131] neg_lo:[0,1] neg_hi:[0,1]
	v_pk_mul_f32 v[130:131], v[118:119], s[24:25] op_sel_hi:[1,0]
	v_pk_add_f32 v[116:117], v[108:109], v[124:125]
	v_pk_fma_f32 v[134:135], v[118:119], s[24:25], v[130:131] op_sel:[0,0,1] op_sel_hi:[1,0,0]
	v_pk_fma_f32 v[118:119], v[118:119], s[24:25], v[130:131] op_sel_hi:[1,0,0] neg_lo:[0,0,1] neg_hi:[0,0,1]
	v_pk_mul_f32 v[130:131], v[116:117], s[30:31] op_sel_hi:[1,0]
	v_pk_add_f32 v[178:179], v[106:107], v[122:123]
	v_pk_fma_f32 v[132:133], v[116:117], s[22:23], v[130:131] op_sel:[0,0,1] op_sel_hi:[1,0,0]
	v_pk_fma_f32 v[116:117], v[116:117], s[22:23], v[130:131] op_sel:[0,0,1] op_sel_hi:[1,0,0] neg_lo:[0,0,1] neg_hi:[0,0,1]
	v_pk_add_f32 v[182:183], v[178:179], v[180:181]
	v_pk_add_f32 v[188:189], v[184:185], v[186:187]
	s_waitcnt lgkmcnt(0)
	v_pk_add_f32 v[200:201], v[120:121], v[176:177]
	v_mov_b32_e32 v133, v117
	v_pk_add_f32 v[116:117], v[120:121], v[176:177] neg_lo:[0,1] neg_hi:[0,1]
	v_pk_add_f32 v[176:177], v[178:179], v[180:181] neg_lo:[0,1] neg_hi:[0,1]
	v_pk_add_f32 v[178:179], v[184:185], v[186:187] neg_lo:[0,1] neg_hi:[0,1]
	v_pk_add_f32 v[184:185], v[192:193], v[194:195] neg_lo:[0,1] neg_hi:[0,1]
	v_pk_add_f32 v[198:199], v[112:113], v[128:129]
	v_pk_add_f32 v[112:113], v[112:113], v[128:129] neg_lo:[0,1] neg_hi:[0,1]
	v_xor_b32_e32 v121, 0x80000000, v116
	v_mov_b32_e32 v120, v117
	v_pk_mul_f32 v[186:187], v[184:185], s[24:25] op_sel_hi:[1,0]
	v_pk_add_f32 v[196:197], v[192:193], v[194:195]
	v_pk_add_f32 v[116:117], v[112:113], v[120:121]
	v_pk_fma_f32 v[192:193], v[184:185], s[24:25], v[186:187] op_sel:[0,0,1] op_sel_hi:[1,0,0]
	v_pk_fma_f32 v[184:185], v[184:185], s[24:25], v[186:187] op_sel_hi:[1,0,0] neg_lo:[0,0,1] neg_hi:[0,0,1]
	v_pk_mul_f32 v[128:129], v[116:117], s[22:23] op_sel_hi:[1,0]
	v_mov_b32_e32 v193, v185
	v_pk_add_f32 v[184:185], v[198:199], v[200:201] neg_lo:[0,1] neg_hi:[0,1]
	v_pk_fma_f32 v[130:131], v[116:117], s[30:31], v[128:129] op_sel:[0,0,1] op_sel_hi:[1,0,0]
	v_pk_fma_f32 v[116:117], v[116:117], s[30:31], v[128:129] op_sel:[0,0,1] op_sel_hi:[1,0,0] neg_lo:[0,0,1] neg_hi:[0,0,1]
	v_mul_f32_e32 v186, 0x3f3504f3, v184
	v_pk_add_f32 v[106:107], v[106:107], v[122:123] neg_lo:[0,1] neg_hi:[0,1]
	v_xor_b32_e32 v123, 0x80000000, v114
	v_mov_b32_e32 v122, v115
	v_mov_b32_e32 v131, v117
	v_pk_fma_f32 v[184:185], v[184:185], s[24:25], v[186:187] op_sel:[1,0,0] op_sel_hi:[1,1,0] neg_lo:[0,0,1] neg_hi:[0,0,1]
	v_pk_add_f32 v[108:109], v[108:109], v[124:125] neg_lo:[0,1] neg_hi:[0,1]
	v_pk_add_f32 v[114:115], v[106:107], v[122:123]
	v_mov_b32_e32 v135, v119
	v_pk_add_f32 v[116:117], v[132:133], v[130:131] neg_lo:[0,1] neg_hi:[0,1]
	v_xor_b32_e32 v181, 0x80000000, v178
	v_mov_b32_e32 v180, v179
	v_pk_add_f32 v[186:187], v[192:193], v[184:185] neg_lo:[0,1] neg_hi:[0,1]
	v_pk_mul_f32 v[124:125], v[108:109], s[22:23] op_sel_hi:[1,0]
	v_pk_add_f32 v[118:119], v[114:115], v[134:135] neg_lo:[0,1] neg_hi:[0,1]
	v_xor_b32_e32 v129, 0x80000000, v116
	v_mov_b32_e32 v128, v117
	v_pk_add_f32 v[178:179], v[176:177], v[180:181] neg_lo:[0,1] neg_hi:[0,1]
	v_xor_b32_e32 v195, 0x80000000, v186
	v_mov_b32_e32 v194, v187
	v_pk_add_f32 v[110:111], v[110:111], v[126:127] neg_lo:[0,1] neg_hi:[0,1]
	v_pk_fma_f32 v[126:127], v[108:109], s[30:31], v[124:125] op_sel:[0,0,1] op_sel_hi:[1,0,0]
	v_pk_fma_f32 v[108:109], v[108:109], s[30:31], v[124:125] op_sel:[0,0,1] op_sel_hi:[1,0,0] neg_lo:[0,0,1] neg_hi:[0,0,1]
	v_pk_add_f32 v[116:117], v[118:119], v[128:129]
	v_pk_add_f32 v[186:187], v[178:179], v[194:195]
	v_mov_b32_e32 v127, v109
	v_pk_add_f32 v[108:109], v[112:113], v[120:121] neg_lo:[0,1] neg_hi:[0,1]
	v_pk_add_f32 v[118:119], v[118:119], v[128:129] neg_lo:[0,1] neg_hi:[0,1]
	v_pk_add_f32 v[128:129], v[178:179], v[194:195] neg_lo:[0,1] neg_hi:[0,1]
	v_cvt_f32_ubyte0_e32 v178, v206
	v_pk_mul_f32 v[112:113], v[108:109], s[30:31]
	v_pk_add_f32 v[114:115], v[114:115], v[134:135]
	v_pk_add_f32 v[134:135], v[176:177], v[180:181]
	v_pk_add_f32 v[176:177], v[192:193], v[184:185]
	v_mul_f32_e32 v192, 0x39800000, v178
	v_pk_fma_f32 v[108:109], v[108:109], s[22:23], v[112:113] op_sel:[0,0,1] op_sel_hi:[1,0,0] neg_lo:[1,0,0] neg_hi:[1,0,0]
	v_sin_f32_e32 v178, v192
	v_pk_add_f32 v[190:191], v[182:183], v[188:189]
	v_pk_add_f32 v[106:107], v[106:107], v[122:123] neg_lo:[0,1] neg_hi:[0,1]
	v_mul_f32_e32 v122, 0x3f3504f3, v110
	v_pk_add_f32 v[112:113], v[126:127], v[108:109] neg_lo:[0,1] neg_hi:[0,1]
	v_pk_add_f32 v[108:109], v[126:127], v[108:109]
	v_pk_add_f32 v[126:127], v[182:183], v[188:189] neg_lo:[0,1] neg_hi:[0,1]
	v_cos_f32_e32 v188, v192
	v_pk_fma_f32 v[110:111], v[110:111], s[24:25], v[122:123] op_sel:[1,0,0] op_sel_hi:[1,1,0] neg_lo:[0,0,1] neg_hi:[0,0,1]
	v_pk_add_f32 v[130:131], v[132:133], v[130:131]
	v_pk_add_f32 v[122:123], v[106:107], v[110:111] neg_lo:[0,1] neg_hi:[0,1]
	v_xor_b32_e32 v121, 0x80000000, v112
	v_mov_b32_e32 v120, v113
	v_pk_add_f32 v[132:133], v[114:115], v[130:131] neg_lo:[0,1] neg_hi:[0,1]
	v_pk_add_f32 v[114:115], v[114:115], v[130:131]
	v_pk_add_f32 v[112:113], v[122:123], v[120:121]
	v_pk_add_f32 v[120:121], v[122:123], v[120:121] neg_lo:[0,1] neg_hi:[0,1]
	v_pk_mul_f32 v[122:123], v[178:179], v[114:115] op_sel:[0,1] op_sel_hi:[0,0]
	v_pk_fma_f32 v[130:131], v[188:189], v[114:115], v[122:123]
	v_pk_fma_f32 v[114:115], v[188:189], v[114:115], v[122:123] op_sel_hi:[0,1,1] neg_lo:[0,0,1] neg_hi:[0,0,1]
	v_mov_b32_e32 v189, v178
	v_pk_add_f32 v[180:181], v[134:135], v[176:177] neg_lo:[0,1] neg_hi:[0,1]
	v_mov_b32_e32 v131, v115
	v_pk_mul_f32 v[114:115], v[188:189], v[188:189]
	v_pk_add_f32 v[122:123], v[134:135], v[176:177]
	v_mul_f32_e32 v135, v188, v178
	v_mov_b32_e32 v134, v114
	v_mov_b32_e32 v114, v115
	v_mov_b32_e32 v115, v135
	v_pk_add_f32 v[202:203], v[198:199], v[200:201]
	v_pk_add_f32 v[176:177], v[134:135], v[114:115] neg_lo:[0,1] neg_hi:[0,1]
	v_pk_add_f32 v[114:115], v[134:135], v[114:115]
	v_pk_add_f32 v[204:205], v[196:197], v[202:203]
	v_pk_add_f32 v[106:107], v[106:107], v[110:111]
	v_mov_b32_e32 v134, v176
	v_mov_b32_e32 v135, v115
	v_pk_mul_f32 v[114:115], v[114:115], v[122:123] op_sel:[1,1] op_sel_hi:[1,0]
	v_mov_b32_e32 v179, v188
	v_pk_add_f32 v[104:105], v[190:191], v[204:205]
	v_pk_add_f32 v[124:125], v[190:191], v[204:205] neg_lo:[0,1] neg_hi:[0,1]
	v_pk_add_f32 v[110:111], v[106:107], v[108:109] neg_lo:[0,1] neg_hi:[0,1]
	v_pk_fma_f32 v[190:191], v[176:177], v[122:123], v[114:115]
	v_pk_fma_f32 v[114:115], v[176:177], v[122:123], v[114:115] op_sel_hi:[0,1,1] neg_lo:[0,0,1] neg_hi:[0,0,1]
	v_pk_add_f32 v[106:107], v[106:107], v[108:109]
	v_pk_mul_f32 v[108:109], v[178:179], v[134:135]
	v_mov_b32_e32 v191, v115
	v_pk_mul_f32 v[114:115], v[188:189], v[134:135]
	v_pk_add_f32 v[108:109], v[108:109], v[108:109] op_sel:[1,0] op_sel_hi:[1,0]
	v_pk_add_f32 v[114:115], v[114:115], v[114:115] op_sel:[0,1] op_sel_hi:[0,1] neg_lo:[0,1] neg_hi:[0,1]
	v_pk_mul_f32 v[108:109], v[108:109], v[106:107] op_sel:[0,1] op_sel_hi:[1,0]
	v_pk_add_f32 v[182:183], v[196:197], v[202:203] neg_lo:[0,1] neg_hi:[0,1]
	v_pk_fma_f32 v[122:123], v[114:115], v[106:107], v[108:109]
	v_pk_fma_f32 v[106:107], v[114:115], v[106:107], v[108:109] neg_lo:[0,0,1] neg_hi:[0,0,1]
	v_mul_f32_e32 v108, 4.0, v192
	v_sin_f32_e32 v106, v108
	v_cos_f32_e32 v108, v108
	v_xor_b32_e32 v185, 0x80000000, v182
	v_mov_b32_e32 v184, v183
	v_pk_add_f32 v[114:115], v[126:127], v[184:185]
	v_pk_add_f32 v[182:183], v[126:127], v[184:185] neg_lo:[0,1] neg_hi:[0,1]
	v_pk_mul_f32 v[126:127], v[106:107], v[114:115] op_sel:[0,1] op_sel_hi:[0,0]
	v_mov_b32_e32 v123, v107
	v_pk_fma_f32 v[134:135], v[108:109], v[114:115], v[126:127]
	v_pk_fma_f32 v[114:115], v[108:109], v[114:115], v[126:127] op_sel_hi:[0,1,1] neg_lo:[0,0,1] neg_hi:[0,0,1]
	v_mov_b32_e32 v109, v106
	v_mov_b32_e32 v107, v108
	v_mov_b32_e32 v135, v115
	v_pk_mul_f32 v[114:115], v[188:189], v[108:109]
	v_pk_mul_f32 v[106:107], v[188:189], v[106:107]
	v_mov_b32_e32 v108, v114
	v_mov_b32_e32 v109, v106
	v_mov_b32_e32 v106, v115
	v_pk_add_f32 v[114:115], v[108:109], v[106:107] neg_lo:[0,1] neg_hi:[0,1]
	v_pk_add_f32 v[106:107], v[108:109], v[106:107]
	v_mov_b32_e32 v108, v114
	v_mov_b32_e32 v109, v107
	v_pk_mul_f32 v[106:107], v[106:107], v[116:117] op_sel:[1,1] op_sel_hi:[1,0]
	s_mov_b32 s18, s25
	v_pk_fma_f32 v[126:127], v[114:115], v[116:117], v[106:107]
	v_pk_fma_f32 v[106:107], v[114:115], v[116:117], v[106:107] op_sel_hi:[0,1,1] neg_lo:[0,0,1] neg_hi:[0,0,1]
	v_mov_b32_e32 v127, v107
	v_pk_mul_f32 v[106:107], v[188:189], v[108:109]
	v_pk_mul_f32 v[108:109], v[178:179], v[108:109]
	v_mov_b32_e32 v114, v106
	v_mov_b32_e32 v115, v109
	v_pk_mov_b32 v[106:107], v[106:107], v[108:109] op_sel:[1,0]
	s_mov_b32 s19, s24
	v_pk_add_f32 v[108:109], v[114:115], v[106:107] neg_lo:[0,1] neg_hi:[0,1]
	v_pk_add_f32 v[106:107], v[114:115], v[106:107]
	v_mov_b32_e32 v114, v108
	v_mov_b32_e32 v115, v107
	v_pk_mul_f32 v[106:107], v[106:107], v[186:187] op_sel:[1,1] op_sel_hi:[1,0]
	s_mov_b32 s88, s31
	v_pk_fma_f32 v[116:117], v[108:109], v[186:187], v[106:107]
	v_pk_fma_f32 v[106:107], v[108:109], v[186:187], v[106:107] op_sel_hi:[0,1,1] neg_lo:[0,0,1] neg_hi:[0,0,1]
	v_pk_mul_f32 v[108:109], v[178:179], v[114:115]
	v_mov_b32_e32 v117, v107
	v_pk_mul_f32 v[106:107], v[188:189], v[114:115]
	v_pk_add_f32 v[108:109], v[108:109], v[108:109] op_sel:[1,0] op_sel_hi:[1,0]
	v_pk_add_f32 v[106:107], v[106:107], v[106:107] op_sel:[0,1] op_sel_hi:[0,1] neg_lo:[0,1] neg_hi:[0,1]
	v_pk_mul_f32 v[108:109], v[108:109], v[112:113] op_sel:[0,1] op_sel_hi:[1,0]
	s_mov_b32 s89, s30
	v_pk_fma_f32 v[114:115], v[106:107], v[112:113], v[108:109]
	v_pk_fma_f32 v[106:107], v[106:107], v[112:113], v[108:109] neg_lo:[0,0,1] neg_hi:[0,0,1]
	v_mul_f32_e32 v115, 0x41000000, v192
	v_sin_f32_e32 v176, v115
	v_cos_f32_e32 v184, v115
	v_mov_b32_e32 v115, v107
	v_pk_mul_f32 v[106:107], v[176:177], v[124:125] op_sel:[0,1] op_sel_hi:[0,0]
	v_pk_fma_f32 v[108:109], v[184:185], v[124:125], v[106:107]
	v_pk_fma_f32 v[106:107], v[184:185], v[124:125], v[106:107] op_sel_hi:[0,1,1] neg_lo:[0,0,1] neg_hi:[0,0,1]
	v_mov_b32_e32 v185, v176
	v_mov_b32_e32 v177, v184
	v_mov_b32_e32 v109, v107
	v_pk_mul_f32 v[106:107], v[188:189], v[184:185]
	v_pk_mul_f32 v[112:113], v[188:189], v[176:177]
	v_mov_b32_e32 v124, v106
	v_mov_b32_e32 v125, v112
	v_mov_b32_e32 v112, v107
	v_pk_add_f32 v[106:107], v[124:125], v[112:113] neg_lo:[0,1] neg_hi:[0,1]
	v_pk_add_f32 v[112:113], v[124:125], v[112:113]
	v_mov_b32_e32 v124, v106
	v_mov_b32_e32 v125, v113
	v_pk_mul_f32 v[112:113], v[112:113], v[132:133] op_sel:[1,1] op_sel_hi:[1,0]
	s_nop 0
	v_pk_fma_f32 v[176:177], v[106:107], v[132:133], v[112:113]
	v_pk_fma_f32 v[106:107], v[106:107], v[132:133], v[112:113] op_sel_hi:[0,1,1] neg_lo:[0,0,1] neg_hi:[0,0,1]
	v_mov_b32_e32 v177, v107
	v_pk_mul_f32 v[106:107], v[188:189], v[124:125]
	v_pk_mul_f32 v[112:113], v[178:179], v[124:125]
	v_mov_b32_e32 v124, v106
	v_mov_b32_e32 v125, v113
	v_pk_mov_b32 v[106:107], v[106:107], v[112:113] op_sel:[1,0]
	s_nop 0
	v_pk_add_f32 v[112:113], v[124:125], v[106:107] neg_lo:[0,1] neg_hi:[0,1]
	v_pk_add_f32 v[106:107], v[124:125], v[106:107]
	v_mov_b32_e32 v124, v112
	v_mov_b32_e32 v125, v107
	v_pk_mul_f32 v[106:107], v[106:107], v[180:181] op_sel:[1,1] op_sel_hi:[1,0]
	s_nop 0
	v_pk_fma_f32 v[132:133], v[112:113], v[180:181], v[106:107]
	v_pk_fma_f32 v[106:107], v[112:113], v[180:181], v[106:107] op_sel_hi:[0,1,1] neg_lo:[0,0,1] neg_hi:[0,0,1]
	v_pk_mul_f32 v[112:113], v[178:179], v[124:125]
	v_mov_b32_e32 v133, v107
	v_pk_mul_f32 v[106:107], v[188:189], v[124:125]
	v_pk_add_f32 v[112:113], v[112:113], v[112:113] op_sel:[1,0] op_sel_hi:[1,0]
	v_pk_add_f32 v[106:107], v[106:107], v[106:107] op_sel:[0,1] op_sel_hi:[0,1] neg_lo:[0,1] neg_hi:[0,1]
	v_pk_mul_f32 v[112:113], v[112:113], v[110:111] op_sel:[0,1] op_sel_hi:[1,0]
	s_nop 0
	v_pk_fma_f32 v[124:125], v[106:107], v[110:111], v[112:113]
	v_pk_fma_f32 v[106:107], v[106:107], v[110:111], v[112:113] neg_lo:[0,0,1] neg_hi:[0,0,1]
	v_mul_f32_e32 v125, 0x41400000, v192
	v_sin_f32_e32 v180, v125
	v_cos_f32_e32 v184, v125
	v_mov_b32_e32 v125, v107
	v_pk_mul_f32 v[106:107], v[180:181], v[182:183] op_sel:[0,1] op_sel_hi:[0,0]
	v_pk_fma_f32 v[110:111], v[184:185], v[182:183], v[106:107]
	v_pk_fma_f32 v[106:107], v[184:185], v[182:183], v[106:107] op_sel_hi:[0,1,1] neg_lo:[0,0,1] neg_hi:[0,0,1]
	v_mov_b32_e32 v185, v180
	v_mov_b32_e32 v181, v184
	v_mov_b32_e32 v111, v107
	v_pk_mul_f32 v[106:107], v[188:189], v[184:185]
	v_pk_mul_f32 v[112:113], v[188:189], v[180:181]
	v_mov_b32_e32 v180, v106
	v_mov_b32_e32 v181, v112
	v_mov_b32_e32 v112, v107
	v_pk_add_f32 v[106:107], v[180:181], v[112:113] neg_lo:[0,1] neg_hi:[0,1]
	v_pk_add_f32 v[112:113], v[180:181], v[112:113]
	v_mov_b32_e32 v180, v106
	v_mov_b32_e32 v181, v113
	v_pk_mul_f32 v[112:113], v[112:113], v[118:119] op_sel:[1,1] op_sel_hi:[1,0]
	s_nop 0
	v_pk_fma_f32 v[182:183], v[106:107], v[118:119], v[112:113]
	v_pk_fma_f32 v[106:107], v[106:107], v[118:119], v[112:113] op_sel_hi:[0,1,1] neg_lo:[0,0,1] neg_hi:[0,0,1]
	v_mov_b32_e32 v183, v107
	v_pk_mul_f32 v[106:107], v[188:189], v[180:181]
	v_pk_mul_f32 v[112:113], v[178:179], v[180:181]
	v_mov_b32_e32 v118, v106
	v_mov_b32_e32 v119, v113
	v_pk_mov_b32 v[106:107], v[106:107], v[112:113] op_sel:[1,0]
	s_nop 0
	v_pk_add_f32 v[112:113], v[118:119], v[106:107] neg_lo:[0,1] neg_hi:[0,1]
	v_pk_add_f32 v[106:107], v[118:119], v[106:107]
	v_mov_b32_e32 v118, v112
	v_mov_b32_e32 v119, v107
	v_pk_mul_f32 v[106:107], v[106:107], v[128:129] op_sel:[1,1] op_sel_hi:[1,0]
	s_nop 0
	v_pk_fma_f32 v[180:181], v[112:113], v[128:129], v[106:107]
	v_pk_fma_f32 v[106:107], v[112:113], v[128:129], v[106:107] op_sel_hi:[0,1,1] neg_lo:[0,0,1] neg_hi:[0,0,1]
	v_pk_mul_f32 v[112:113], v[178:179], v[118:119]
	v_mov_b32_e32 v181, v107
	v_pk_mul_f32 v[106:107], v[188:189], v[118:119]
	v_pk_add_f32 v[112:113], v[112:113], v[112:113] op_sel:[1,0] op_sel_hi:[1,0]
	v_pk_add_f32 v[106:107], v[106:107], v[106:107] op_sel:[0,1] op_sel_hi:[0,1] neg_lo:[0,1] neg_hi:[0,1]
	v_pk_mul_f32 v[112:113], v[112:113], v[120:121] op_sel:[0,1] op_sel_hi:[1,0]
	s_nop 0
	v_pk_fma_f32 v[118:119], v[106:107], v[120:121], v[112:113]
	v_pk_fma_f32 v[106:107], v[106:107], v[120:121], v[112:113] neg_lo:[0,0,1] neg_hi:[0,0,1]
	s_nop 0
	v_mov_b32_e32 v119, v107
	ds_write_b64 v207, v[104:105]
	ds_write_b64 v207, v[130:131] offset:2176
	ds_write_b64 v207, v[190:191] offset:4352
	ds_write_b64 v207, v[122:123] offset:6528
	ds_write_b64 v207, v[134:135] offset:8704
	ds_write_b64 v207, v[126:127] offset:10880
	ds_write_b64 v207, v[116:117] offset:13056
	ds_write_b64 v207, v[114:115] offset:15232
	ds_write_b64 v207, v[108:109] offset:17408
	ds_write_b64 v207, v[176:177] offset:19584
	ds_write_b64 v207, v[132:133] offset:21760
	ds_write_b64 v207, v[124:125] offset:23936
	ds_write_b64 v207, v[110:111] offset:26112
	ds_write_b64 v207, v[182:183] offset:28288
	ds_write_b64 v207, v[180:181] offset:30464
	ds_write_b64 v207, v[118:119] offset:32640
	v_mov_b32_e32 v104, v208
	s_waitcnt lgkmcnt(0)
	s_barrier
	s_nop 0
	v_and_b32_e32 v206, 15, v104
	v_lshlrev_b32_e32 v104, 4, v104
	v_and_b32_e32 v104, 0xffffff00, v104
	v_ashrrev_i32_e32 v105, 1, v104
	v_add_u32_e32 v105, s35, v105
	v_lshlrev_b32_e32 v104, 3, v104
	v_lshlrev_b32_e32 v106, 3, v206
	v_add3_u32 v207, v105, v104, v106
	ds_read_b64 v[106:107], v207
	ds_read_b64 v[108:109], v207 offset:136
	ds_read_b64 v[110:111], v207 offset:272
	ds_read_b64 v[112:113], v207 offset:408
	ds_read_b64 v[114:115], v207 offset:544
	ds_read_b64 v[116:117], v207 offset:680
	ds_read_b64 v[118:119], v207 offset:1088
	ds_read_b64 v[120:121], v207 offset:1224
	ds_read_b64 v[122:123], v207 offset:1632
	ds_read_b64 v[124:125], v207 offset:1768
	ds_read_b64 v[126:127], v207 offset:816
	ds_read_b64 v[128:129], v207 offset:952
	ds_read_b64 v[130:131], v207 offset:1360
	ds_read_b64 v[132:133], v207 offset:1496
	ds_read_b64 v[176:177], v207 offset:1904
	ds_read_b64 v[178:179], v207 offset:2040
	s_waitcnt lgkmcnt(8)
	v_pk_add_f32 v[192:193], v[108:109], v[120:121]
	s_waitcnt lgkmcnt(6)
	v_pk_add_f32 v[180:181], v[114:115], v[122:123]
	v_pk_add_f32 v[194:195], v[116:117], v[124:125]
	v_pk_add_f32 v[114:115], v[114:115], v[122:123] neg_lo:[0,1] neg_hi:[0,1]
	s_waitcnt lgkmcnt(0)
	v_pk_add_f32 v[122:123], v[126:127], v[176:177] neg_lo:[0,1] neg_hi:[0,1]
	v_pk_add_f32 v[116:117], v[116:117], v[124:125] neg_lo:[0,1] neg_hi:[0,1]
	v_pk_add_f32 v[184:185], v[110:111], v[130:131]
	v_pk_add_f32 v[186:187], v[126:127], v[176:177]
	v_pk_add_f32 v[110:111], v[110:111], v[130:131] neg_lo:[0,1] neg_hi:[0,1]
	v_xor_b32_e32 v127, 0x80000000, v122
	v_mov_b32_e32 v126, v123
	v_pk_add_f32 v[108:109], v[108:109], v[120:121] neg_lo:[0,1] neg_hi:[0,1]
	v_xor_b32_e32 v121, 0x80000000, v116
	v_mov_b32_e32 v120, v117
	v_pk_add_f32 v[122:123], v[110:111], v[126:127]
	v_pk_add_f32 v[116:117], v[108:109], v[120:121]
	v_pk_mul_f32 v[130:131], v[122:123], s[24:25] op_sel_hi:[1,0]
	v_pk_mul_f32 v[124:125], v[116:117], s[30:31] op_sel_hi:[1,0]
	v_pk_fma_f32 v[176:177], v[122:123], s[24:25], v[130:131] op_sel:[0,0,1] op_sel_hi:[1,0,0]
	v_pk_fma_f32 v[122:123], v[122:123], s[24:25], v[130:131] op_sel_hi:[1,0,0] neg_lo:[0,0,1] neg_hi:[0,0,1]
	v_pk_fma_f32 v[130:131], v[116:117], s[22:23], v[124:125] op_sel:[0,0,1] op_sel_hi:[1,0,0]
	v_pk_fma_f32 v[116:117], v[116:117], s[22:23], v[124:125] op_sel:[0,0,1] op_sel_hi:[1,0,0] neg_lo:[0,0,1] neg_hi:[0,0,1]
	v_pk_add_f32 v[188:189], v[184:185], v[186:187]
	v_pk_add_f32 v[200:201], v[128:129], v[178:179]
	v_mov_b32_e32 v131, v117
	v_pk_add_f32 v[116:117], v[128:129], v[178:179] neg_lo:[0,1] neg_hi:[0,1]
	v_pk_add_f32 v[178:179], v[184:185], v[186:187] neg_lo:[0,1] neg_hi:[0,1]
	v_pk_add_f32 v[184:185], v[192:193], v[194:195] neg_lo:[0,1] neg_hi:[0,1]
	v_pk_add_f32 v[198:199], v[112:113], v[132:133]
	v_pk_add_f32 v[112:113], v[112:113], v[132:133] neg_lo:[0,1] neg_hi:[0,1]
	v_xor_b32_e32 v125, 0x80000000, v116
	v_mov_b32_e32 v124, v117
	v_pk_mul_f32 v[186:187], v[184:185], s[24:25] op_sel_hi:[1,0]
	v_pk_add_f32 v[196:197], v[192:193], v[194:195]
	v_pk_add_f32 v[116:117], v[112:113], v[124:125]
	v_pk_fma_f32 v[192:193], v[184:185], s[24:25], v[186:187] op_sel:[0,0,1] op_sel_hi:[1,0,0]
	v_pk_fma_f32 v[184:185], v[184:185], s[24:25], v[186:187] op_sel_hi:[1,0,0] neg_lo:[0,0,1] neg_hi:[0,0,1]
	v_pk_mul_f32 v[128:129], v[116:117], s[22:23] op_sel_hi:[1,0]
	v_mov_b32_e32 v193, v185
	v_pk_add_f32 v[184:185], v[198:199], v[200:201] neg_lo:[0,1] neg_hi:[0,1]
	v_pk_fma_f32 v[132:133], v[116:117], s[30:31], v[128:129] op_sel:[0,0,1] op_sel_hi:[1,0,0]
	v_pk_fma_f32 v[116:117], v[116:117], s[30:31], v[128:129] op_sel:[0,0,1] op_sel_hi:[1,0,0] neg_lo:[0,0,1] neg_hi:[0,0,1]
	v_mul_f32_e32 v186, 0x3f3504f3, v184
	v_pk_add_f32 v[134:135], v[106:107], v[118:119]
	v_pk_add_f32 v[106:107], v[106:107], v[118:119] neg_lo:[0,1] neg_hi:[0,1]
	v_xor_b32_e32 v119, 0x80000000, v114
	v_mov_b32_e32 v118, v115
	v_mov_b32_e32 v133, v117
	v_pk_fma_f32 v[184:185], v[184:185], s[24:25], v[186:187] op_sel:[1,0,0] op_sel_hi:[1,1,0] neg_lo:[0,0,1] neg_hi:[0,0,1]
	v_pk_add_f32 v[108:109], v[108:109], v[120:121] neg_lo:[0,1] neg_hi:[0,1]
	v_pk_add_f32 v[182:183], v[134:135], v[180:181]
	v_pk_add_f32 v[114:115], v[106:107], v[118:119]
	v_mov_b32_e32 v177, v123
	v_pk_add_f32 v[116:117], v[130:131], v[132:133] neg_lo:[0,1] neg_hi:[0,1]
	v_pk_add_f32 v[134:135], v[134:135], v[180:181] neg_lo:[0,1] neg_hi:[0,1]
	v_xor_b32_e32 v181, 0x80000000, v178
	v_mov_b32_e32 v180, v179
	v_pk_add_f32 v[186:187], v[192:193], v[184:185] neg_lo:[0,1] neg_hi:[0,1]
	v_pk_mul_f32 v[120:121], v[108:109], s[22:23] op_sel_hi:[1,0]
	v_pk_add_f32 v[122:123], v[114:115], v[176:177] neg_lo:[0,1] neg_hi:[0,1]
	v_xor_b32_e32 v129, 0x80000000, v116
	v_mov_b32_e32 v128, v117
	v_pk_add_f32 v[178:179], v[134:135], v[180:181] neg_lo:[0,1] neg_hi:[0,1]
	v_xor_b32_e32 v195, 0x80000000, v186
	v_mov_b32_e32 v194, v187
	v_pk_add_f32 v[110:111], v[110:111], v[126:127] neg_lo:[0,1] neg_hi:[0,1]
	v_pk_fma_f32 v[126:127], v[108:109], s[30:31], v[120:121] op_sel:[0,0,1] op_sel_hi:[1,0,0]
	v_pk_fma_f32 v[108:109], v[108:109], s[30:31], v[120:121] op_sel:[0,0,1] op_sel_hi:[1,0,0] neg_lo:[0,0,1] neg_hi:[0,0,1]
	v_pk_add_f32 v[116:117], v[122:123], v[128:129]
	v_pk_add_f32 v[186:187], v[178:179], v[194:195]
	v_mov_b32_e32 v127, v109
	v_pk_add_f32 v[108:109], v[112:113], v[124:125] neg_lo:[0,1] neg_hi:[0,1]
	v_pk_add_f32 v[122:123], v[122:123], v[128:129] neg_lo:[0,1] neg_hi:[0,1]
	v_pk_add_f32 v[128:129], v[178:179], v[194:195] neg_lo:[0,1] neg_hi:[0,1]
	v_cvt_f32_ubyte0_e32 v178, v206
	v_pk_mul_f32 v[112:113], v[108:109], s[30:31]
	v_pk_add_f32 v[114:115], v[114:115], v[176:177]
	v_pk_add_f32 v[176:177], v[192:193], v[184:185]
	v_mul_f32_e32 v192, 0x3b800000, v178
	v_pk_fma_f32 v[108:109], v[108:109], s[22:23], v[112:113] op_sel:[0,0,1] op_sel_hi:[1,0,0] neg_lo:[1,0,0] neg_hi:[1,0,0]
	v_sin_f32_e32 v178, v192
	v_pk_add_f32 v[190:191], v[182:183], v[188:189]
	v_pk_add_f32 v[106:107], v[106:107], v[118:119] neg_lo:[0,1] neg_hi:[0,1]
	v_mul_f32_e32 v118, 0x3f3504f3, v110
	v_pk_add_f32 v[112:113], v[126:127], v[108:109] neg_lo:[0,1] neg_hi:[0,1]
	v_pk_add_f32 v[108:109], v[126:127], v[108:109]
	v_pk_add_f32 v[126:127], v[182:183], v[188:189] neg_lo:[0,1] neg_hi:[0,1]
	v_cos_f32_e32 v188, v192
	v_pk_fma_f32 v[110:111], v[110:111], s[24:25], v[118:119] op_sel:[1,0,0] op_sel_hi:[1,1,0] neg_lo:[0,0,1] neg_hi:[0,0,1]
	v_pk_add_f32 v[130:131], v[130:131], v[132:133]
	v_pk_add_f32 v[118:119], v[106:107], v[110:111] neg_lo:[0,1] neg_hi:[0,1]
	v_xor_b32_e32 v121, 0x80000000, v112
	v_mov_b32_e32 v120, v113
	v_pk_add_f32 v[132:133], v[114:115], v[130:131] neg_lo:[0,1] neg_hi:[0,1]
	v_pk_add_f32 v[114:115], v[114:115], v[130:131]
	v_pk_add_f32 v[112:113], v[118:119], v[120:121]
	v_pk_add_f32 v[118:119], v[118:119], v[120:121] neg_lo:[0,1] neg_hi:[0,1]
	v_pk_mul_f32 v[120:121], v[178:179], v[114:115] op_sel:[0,1] op_sel_hi:[0,0]
	v_pk_add_f32 v[134:135], v[134:135], v[180:181]
	v_pk_fma_f32 v[130:131], v[188:189], v[114:115], v[120:121]
	v_pk_fma_f32 v[114:115], v[188:189], v[114:115], v[120:121] op_sel_hi:[0,1,1] neg_lo:[0,0,1] neg_hi:[0,0,1]
	v_mov_b32_e32 v189, v178
	v_pk_add_f32 v[180:181], v[134:135], v[176:177] neg_lo:[0,1] neg_hi:[0,1]
	v_mov_b32_e32 v131, v115
	v_pk_mul_f32 v[114:115], v[188:189], v[188:189]
	v_pk_add_f32 v[120:121], v[134:135], v[176:177]
	v_mul_f32_e32 v135, v188, v178
	v_mov_b32_e32 v134, v114
	v_mov_b32_e32 v114, v115
	v_mov_b32_e32 v115, v135
	v_pk_add_f32 v[202:203], v[198:199], v[200:201]
	v_pk_add_f32 v[176:177], v[134:135], v[114:115] neg_lo:[0,1] neg_hi:[0,1]
	v_pk_add_f32 v[114:115], v[134:135], v[114:115]
	v_pk_add_f32 v[204:205], v[196:197], v[202:203]
	v_pk_add_f32 v[106:107], v[106:107], v[110:111]
	v_mov_b32_e32 v134, v176
	v_mov_b32_e32 v135, v115
	v_pk_mul_f32 v[114:115], v[114:115], v[120:121] op_sel:[1,1] op_sel_hi:[1,0]
	v_mov_b32_e32 v179, v188
	v_pk_add_f32 v[104:105], v[190:191], v[204:205]
	v_pk_add_f32 v[124:125], v[190:191], v[204:205] neg_lo:[0,1] neg_hi:[0,1]
	v_pk_add_f32 v[110:111], v[106:107], v[108:109] neg_lo:[0,1] neg_hi:[0,1]
	v_pk_fma_f32 v[190:191], v[176:177], v[120:121], v[114:115]
	v_pk_fma_f32 v[114:115], v[176:177], v[120:121], v[114:115] op_sel_hi:[0,1,1] neg_lo:[0,0,1] neg_hi:[0,0,1]
	v_pk_add_f32 v[106:107], v[106:107], v[108:109]
	v_pk_mul_f32 v[108:109], v[178:179], v[134:135]
	v_mov_b32_e32 v191, v115
	v_pk_mul_f32 v[114:115], v[188:189], v[134:135]
	v_pk_add_f32 v[108:109], v[108:109], v[108:109] op_sel:[1,0] op_sel_hi:[1,0]
	v_pk_add_f32 v[114:115], v[114:115], v[114:115] op_sel:[0,1] op_sel_hi:[0,1] neg_lo:[0,1] neg_hi:[0,1]
	v_pk_mul_f32 v[108:109], v[108:109], v[106:107] op_sel:[0,1] op_sel_hi:[1,0]
	v_pk_add_f32 v[182:183], v[196:197], v[202:203] neg_lo:[0,1] neg_hi:[0,1]
	v_pk_fma_f32 v[120:121], v[114:115], v[106:107], v[108:109]
	v_pk_fma_f32 v[106:107], v[114:115], v[106:107], v[108:109] neg_lo:[0,0,1] neg_hi:[0,0,1]
	v_mul_f32_e32 v108, 4.0, v192
	v_sin_f32_e32 v106, v108
	v_cos_f32_e32 v108, v108
	v_xor_b32_e32 v185, 0x80000000, v182
	v_mov_b32_e32 v184, v183
	v_pk_add_f32 v[114:115], v[126:127], v[184:185]
	v_pk_add_f32 v[182:183], v[126:127], v[184:185] neg_lo:[0,1] neg_hi:[0,1]
	v_pk_mul_f32 v[126:127], v[106:107], v[114:115] op_sel:[0,1] op_sel_hi:[0,0]
	v_mov_b32_e32 v121, v107
	v_pk_fma_f32 v[134:135], v[108:109], v[114:115], v[126:127]
	v_pk_fma_f32 v[114:115], v[108:109], v[114:115], v[126:127] op_sel_hi:[0,1,1] neg_lo:[0,0,1] neg_hi:[0,0,1]
	v_mov_b32_e32 v109, v106
	v_mov_b32_e32 v107, v108
	v_mov_b32_e32 v135, v115
	v_pk_mul_f32 v[114:115], v[188:189], v[108:109]
	v_pk_mul_f32 v[106:107], v[188:189], v[106:107]
	v_mov_b32_e32 v108, v114
	v_mov_b32_e32 v109, v106
	v_mov_b32_e32 v106, v115
	v_pk_add_f32 v[114:115], v[108:109], v[106:107] neg_lo:[0,1] neg_hi:[0,1]
	v_pk_add_f32 v[106:107], v[108:109], v[106:107]
	v_mov_b32_e32 v108, v114
	v_mov_b32_e32 v109, v107
	v_pk_mul_f32 v[106:107], v[106:107], v[116:117] op_sel:[1,1] op_sel_hi:[1,0]
	s_nop 0
	v_pk_fma_f32 v[126:127], v[114:115], v[116:117], v[106:107]
	v_pk_fma_f32 v[106:107], v[114:115], v[116:117], v[106:107] op_sel_hi:[0,1,1] neg_lo:[0,0,1] neg_hi:[0,0,1]
	v_mov_b32_e32 v127, v107
	v_pk_mul_f32 v[106:107], v[188:189], v[108:109]
	v_pk_mul_f32 v[108:109], v[178:179], v[108:109]
	v_mov_b32_e32 v114, v106
	v_mov_b32_e32 v115, v109
	v_pk_mov_b32 v[106:107], v[106:107], v[108:109] op_sel:[1,0]
	s_nop 0
	v_pk_add_f32 v[108:109], v[114:115], v[106:107] neg_lo:[0,1] neg_hi:[0,1]
	v_pk_add_f32 v[106:107], v[114:115], v[106:107]
	v_mov_b32_e32 v114, v108
	v_mov_b32_e32 v115, v107
	v_pk_mul_f32 v[106:107], v[106:107], v[186:187] op_sel:[1,1] op_sel_hi:[1,0]
	s_nop 0
	v_pk_fma_f32 v[116:117], v[108:109], v[186:187], v[106:107]
	v_pk_fma_f32 v[106:107], v[108:109], v[186:187], v[106:107] op_sel_hi:[0,1,1] neg_lo:[0,0,1] neg_hi:[0,0,1]
	v_pk_mul_f32 v[108:109], v[178:179], v[114:115]
	v_mov_b32_e32 v117, v107
	v_pk_mul_f32 v[106:107], v[188:189], v[114:115]
	v_pk_add_f32 v[108:109], v[108:109], v[108:109] op_sel:[1,0] op_sel_hi:[1,0]
	v_pk_add_f32 v[106:107], v[106:107], v[106:107] op_sel:[0,1] op_sel_hi:[0,1] neg_lo:[0,1] neg_hi:[0,1]
	v_pk_mul_f32 v[108:109], v[108:109], v[112:113] op_sel:[0,1] op_sel_hi:[1,0]
	s_nop 0
	v_pk_fma_f32 v[114:115], v[106:107], v[112:113], v[108:109]
	v_pk_fma_f32 v[106:107], v[106:107], v[112:113], v[108:109] neg_lo:[0,0,1] neg_hi:[0,0,1]
	v_mul_f32_e32 v115, 0x41000000, v192
	v_sin_f32_e32 v176, v115
	v_cos_f32_e32 v184, v115
	v_mov_b32_e32 v115, v107
	v_pk_mul_f32 v[106:107], v[176:177], v[124:125] op_sel:[0,1] op_sel_hi:[0,0]
	v_pk_fma_f32 v[108:109], v[184:185], v[124:125], v[106:107]
	v_pk_fma_f32 v[106:107], v[184:185], v[124:125], v[106:107] op_sel_hi:[0,1,1] neg_lo:[0,0,1] neg_hi:[0,0,1]
	v_mov_b32_e32 v185, v176
	v_mov_b32_e32 v177, v184
	v_mov_b32_e32 v109, v107
	v_pk_mul_f32 v[106:107], v[188:189], v[184:185]
	v_pk_mul_f32 v[112:113], v[188:189], v[176:177]
	v_mov_b32_e32 v124, v106
	v_mov_b32_e32 v125, v112
	v_mov_b32_e32 v112, v107
	v_pk_add_f32 v[106:107], v[124:125], v[112:113] neg_lo:[0,1] neg_hi:[0,1]
	v_pk_add_f32 v[112:113], v[124:125], v[112:113]
	v_mov_b32_e32 v124, v106
	v_mov_b32_e32 v125, v113
	v_pk_mul_f32 v[112:113], v[112:113], v[132:133] op_sel:[1,1] op_sel_hi:[1,0]
	s_nop 0
	v_pk_fma_f32 v[176:177], v[106:107], v[132:133], v[112:113]
	v_pk_fma_f32 v[106:107], v[106:107], v[132:133], v[112:113] op_sel_hi:[0,1,1] neg_lo:[0,0,1] neg_hi:[0,0,1]
	v_mov_b32_e32 v177, v107
	v_pk_mul_f32 v[106:107], v[188:189], v[124:125]
	v_pk_mul_f32 v[112:113], v[178:179], v[124:125]
	v_mov_b32_e32 v124, v106
	v_mov_b32_e32 v125, v113
	v_pk_mov_b32 v[106:107], v[106:107], v[112:113] op_sel:[1,0]
	s_nop 0
	v_pk_add_f32 v[112:113], v[124:125], v[106:107] neg_lo:[0,1] neg_hi:[0,1]
	v_pk_add_f32 v[106:107], v[124:125], v[106:107]
	v_mov_b32_e32 v124, v112
	v_mov_b32_e32 v125, v107
	v_pk_mul_f32 v[106:107], v[106:107], v[180:181] op_sel:[1,1] op_sel_hi:[1,0]
	s_nop 0
	v_pk_fma_f32 v[132:133], v[112:113], v[180:181], v[106:107]
	v_pk_fma_f32 v[106:107], v[112:113], v[180:181], v[106:107] op_sel_hi:[0,1,1] neg_lo:[0,0,1] neg_hi:[0,0,1]
	v_pk_mul_f32 v[112:113], v[178:179], v[124:125]
	v_mov_b32_e32 v133, v107
	v_pk_mul_f32 v[106:107], v[188:189], v[124:125]
	v_pk_add_f32 v[112:113], v[112:113], v[112:113] op_sel:[1,0] op_sel_hi:[1,0]
	v_pk_add_f32 v[106:107], v[106:107], v[106:107] op_sel:[0,1] op_sel_hi:[0,1] neg_lo:[0,1] neg_hi:[0,1]
	v_pk_mul_f32 v[112:113], v[112:113], v[110:111] op_sel:[0,1] op_sel_hi:[1,0]
	s_nop 0
	v_pk_fma_f32 v[124:125], v[106:107], v[110:111], v[112:113]
	v_pk_fma_f32 v[106:107], v[106:107], v[110:111], v[112:113] neg_lo:[0,0,1] neg_hi:[0,0,1]
	v_mul_f32_e32 v125, 0x41400000, v192
	v_sin_f32_e32 v180, v125
	v_cos_f32_e32 v184, v125
	v_mov_b32_e32 v125, v107
	v_pk_mul_f32 v[106:107], v[180:181], v[182:183] op_sel:[0,1] op_sel_hi:[0,0]
	v_pk_fma_f32 v[110:111], v[184:185], v[182:183], v[106:107]
	v_pk_fma_f32 v[106:107], v[184:185], v[182:183], v[106:107] op_sel_hi:[0,1,1] neg_lo:[0,0,1] neg_hi:[0,0,1]
	v_mov_b32_e32 v185, v180
	v_mov_b32_e32 v181, v184
	v_mov_b32_e32 v111, v107
	v_pk_mul_f32 v[106:107], v[188:189], v[184:185]
	v_pk_mul_f32 v[112:113], v[188:189], v[180:181]
	v_mov_b32_e32 v180, v106
	v_mov_b32_e32 v181, v112
	v_mov_b32_e32 v112, v107
	v_pk_add_f32 v[106:107], v[180:181], v[112:113] neg_lo:[0,1] neg_hi:[0,1]
	v_pk_add_f32 v[112:113], v[180:181], v[112:113]
	v_mov_b32_e32 v180, v106
	v_mov_b32_e32 v181, v113
	v_pk_mul_f32 v[112:113], v[112:113], v[122:123] op_sel:[1,1] op_sel_hi:[1,0]
	s_nop 0
	v_pk_fma_f32 v[182:183], v[106:107], v[122:123], v[112:113]
	v_pk_fma_f32 v[106:107], v[106:107], v[122:123], v[112:113] op_sel_hi:[0,1,1] neg_lo:[0,0,1] neg_hi:[0,0,1]
	v_mov_b32_e32 v183, v107
	v_pk_mul_f32 v[106:107], v[188:189], v[180:181]
	v_pk_mul_f32 v[112:113], v[178:179], v[180:181]
	v_mov_b32_e32 v122, v106
	v_mov_b32_e32 v123, v113
	v_pk_mov_b32 v[106:107], v[106:107], v[112:113] op_sel:[1,0]
	s_nop 0
	v_pk_add_f32 v[112:113], v[122:123], v[106:107] neg_lo:[0,1] neg_hi:[0,1]
	v_pk_add_f32 v[106:107], v[122:123], v[106:107]
	v_mov_b32_e32 v122, v112
	v_mov_b32_e32 v123, v107
	v_pk_mul_f32 v[106:107], v[106:107], v[128:129] op_sel:[1,1] op_sel_hi:[1,0]
	s_nop 0
	v_pk_fma_f32 v[180:181], v[112:113], v[128:129], v[106:107]
	v_pk_fma_f32 v[106:107], v[112:113], v[128:129], v[106:107] op_sel_hi:[0,1,1] neg_lo:[0,0,1] neg_hi:[0,0,1]
	v_pk_mul_f32 v[112:113], v[178:179], v[122:123]
	v_mov_b32_e32 v181, v107
	v_pk_mul_f32 v[106:107], v[188:189], v[122:123]
	v_pk_add_f32 v[112:113], v[112:113], v[112:113] op_sel:[1,0] op_sel_hi:[1,0]
	v_pk_add_f32 v[106:107], v[106:107], v[106:107] op_sel:[0,1] op_sel_hi:[0,1] neg_lo:[0,1] neg_hi:[0,1]
	v_pk_mul_f32 v[112:113], v[112:113], v[118:119] op_sel:[0,1] op_sel_hi:[1,0]
	s_nop 0
	v_pk_fma_f32 v[122:123], v[106:107], v[118:119], v[112:113]
	v_pk_fma_f32 v[106:107], v[106:107], v[118:119], v[112:113] neg_lo:[0,0,1] neg_hi:[0,0,1]
	s_nop 0
	v_mov_b32_e32 v123, v107
	ds_write2_b64 v207, v[104:105], v[130:131] offset1:17
	ds_write2_b64 v207, v[190:191], v[120:121] offset0:34 offset1:51
	ds_write2_b64 v207, v[134:135], v[126:127] offset0:68 offset1:85
	ds_write2_b64 v207, v[116:117], v[114:115] offset0:102 offset1:119
	ds_write2_b64 v207, v[108:109], v[176:177] offset0:136 offset1:153
	ds_write2_b64 v207, v[132:133], v[124:125] offset0:170 offset1:187
	ds_write2_b64 v207, v[110:111], v[182:183] offset0:204 offset1:221
	ds_write2_b64 v207, v[180:181], v[122:123] offset0:238 offset1:255
	v_mov_b32_e32 v104, v208
	s_waitcnt lgkmcnt(0)
	s_nop 0
	v_lshlrev_b32_e32 v105, 4, v104
	v_bfe_i32 v104, v104, 0, 28
	v_add_lshl_u32 v182, v104, v105, 3
	v_add_u32_e32 v188, s35, v182
	ds_read_b64 v[104:105], v188
	ds_read_b64 v[106:107], v188 offset:8
	ds_read_b64 v[108:109], v188 offset:16
	ds_read_b64 v[110:111], v188 offset:24
	ds_read_b64 v[112:113], v188 offset:64
	ds_read_b64 v[114:115], v188 offset:72
	ds_read_b64 v[116:117], v188 offset:32
	ds_read_b64 v[118:119], v188 offset:40
	ds_read_b64 v[120:121], v188 offset:48
	ds_read_b64 v[122:123], v188 offset:56
	ds_read_b64 v[124:125], v188 offset:96
	ds_read_b64 v[126:127], v188 offset:104
	ds_read_b64 v[128:129], v188 offset:80
	ds_read_b64 v[130:131], v188 offset:88
	ds_read_b64 v[132:133], v188 offset:112
	ds_read_b64 v[134:135], v188 offset:120
	s_waitcnt lgkmcnt(10)
	v_pk_add_f32 v[176:177], v[104:105], v[112:113]
	v_pk_add_f32 v[104:105], v[104:105], v[112:113] neg_lo:[0,1] neg_hi:[0,1]
	s_waitcnt lgkmcnt(4)
	v_pk_add_f32 v[112:113], v[116:117], v[124:125]
	v_pk_add_f32 v[116:117], v[116:117], v[124:125] neg_lo:[0,1] neg_hi:[0,1]
	v_add_u32_e32 v189, 0, v182
	v_xor_b32_e32 v125, 0x80000000, v116
	v_mov_b32_e32 v124, v117
	v_pk_add_f32 v[116:117], v[176:177], v[112:113]
	v_pk_add_f32 v[112:113], v[176:177], v[112:113] neg_lo:[0,1] neg_hi:[0,1]
	v_pk_add_f32 v[176:177], v[104:105], v[124:125]
	v_pk_add_f32 v[104:105], v[104:105], v[124:125] neg_lo:[0,1] neg_hi:[0,1]
	v_pk_add_f32 v[124:125], v[106:107], v[114:115]
	v_pk_add_f32 v[106:107], v[106:107], v[114:115] neg_lo:[0,1] neg_hi:[0,1]
	v_pk_add_f32 v[114:115], v[118:119], v[126:127]
	v_pk_add_f32 v[118:119], v[118:119], v[126:127] neg_lo:[0,1] neg_hi:[0,1]
	s_nop 0
	v_xor_b32_e32 v127, 0x80000000, v118
	v_mov_b32_e32 v126, v119
	v_pk_add_f32 v[118:119], v[124:125], v[114:115]
	v_pk_add_f32 v[114:115], v[124:125], v[114:115] neg_lo:[0,1] neg_hi:[0,1]
	v_pk_add_f32 v[124:125], v[106:107], v[126:127]
	v_pk_add_f32 v[106:107], v[106:107], v[126:127] neg_lo:[0,1] neg_hi:[0,1]
	s_waitcnt lgkmcnt(2)
	v_pk_add_f32 v[126:127], v[108:109], v[128:129]
	v_pk_add_f32 v[108:109], v[108:109], v[128:129] neg_lo:[0,1] neg_hi:[0,1]
	s_waitcnt lgkmcnt(0)
	v_pk_add_f32 v[128:129], v[120:121], v[132:133]
	v_pk_add_f32 v[120:121], v[120:121], v[132:133] neg_lo:[0,1] neg_hi:[0,1]
	s_nop 0
	v_xor_b32_e32 v133, 0x80000000, v120
	v_mov_b32_e32 v132, v121
	v_pk_add_f32 v[120:121], v[126:127], v[128:129]
	v_pk_add_f32 v[126:127], v[126:127], v[128:129] neg_lo:[0,1] neg_hi:[0,1]
	v_pk_add_f32 v[128:129], v[108:109], v[132:133]
	v_pk_add_f32 v[108:109], v[108:109], v[132:133] neg_lo:[0,1] neg_hi:[0,1]
	v_pk_add_f32 v[132:133], v[110:111], v[130:131]
	v_pk_add_f32 v[110:111], v[110:111], v[130:131] neg_lo:[0,1] neg_hi:[0,1]
	v_pk_add_f32 v[130:131], v[122:123], v[134:135]
	v_pk_add_f32 v[122:123], v[122:123], v[134:135] neg_lo:[0,1] neg_hi:[0,1]
	s_nop 0
	v_xor_b32_e32 v135, 0x80000000, v122
	v_mov_b32_e32 v134, v123
	v_pk_add_f32 v[122:123], v[132:133], v[130:131]
	v_pk_add_f32 v[130:131], v[132:133], v[130:131] neg_lo:[0,1] neg_hi:[0,1]
	v_pk_add_f32 v[132:133], v[110:111], v[134:135]
	v_pk_add_f32 v[110:111], v[110:111], v[134:135] neg_lo:[0,1] neg_hi:[0,1]
	v_pk_mul_f32 v[134:135], v[124:125], s[30:31] op_sel_hi:[1,0]
	s_nop 0
	v_pk_fma_f32 v[178:179], v[124:125], s[22:23], v[134:135] op_sel:[0,0,1] op_sel_hi:[1,0,0]
	v_pk_fma_f32 v[124:125], v[124:125], s[22:23], v[134:135] op_sel:[0,0,1] op_sel_hi:[1,0,0] neg_lo:[0,0,1] neg_hi:[0,0,1]
	s_nop 0
	v_mov_b32_e32 v179, v125
	v_pk_mul_f32 v[124:125], v[114:115], s[24:25] op_sel_hi:[1,0]
	s_nop 0
	v_pk_fma_f32 v[134:135], v[114:115], s[24:25], v[124:125] op_sel:[0,0,1] op_sel_hi:[1,0,0]
	v_pk_fma_f32 v[114:115], v[114:115], s[24:25], v[124:125] op_sel_hi:[1,0,0] neg_lo:[0,0,1] neg_hi:[0,0,1]
	s_nop 0
	v_mov_b32_e32 v135, v115
	v_pk_mul_f32 v[114:115], v[106:107], s[22:23] op_sel_hi:[1,0]
	s_nop 0
	v_pk_fma_f32 v[124:125], v[106:107], s[30:31], v[114:115] op_sel:[0,0,1] op_sel_hi:[1,0,0]
	v_pk_fma_f32 v[106:107], v[106:107], s[30:31], v[114:115] op_sel:[0,0,1] op_sel_hi:[1,0,0] neg_lo:[0,0,1] neg_hi:[0,0,1]
	s_nop 0
	v_mov_b32_e32 v125, v107
	v_pk_mul_f32 v[106:107], v[128:129], s[24:25] op_sel_hi:[1,0]
	s_nop 0
	v_pk_fma_f32 v[114:115], v[128:129], s[24:25], v[106:107] op_sel:[0,0,1] op_sel_hi:[1,0,0]
	v_pk_fma_f32 v[106:107], v[128:129], s[24:25], v[106:107] op_sel_hi:[1,0,0] neg_lo:[0,0,1] neg_hi:[0,0,1]
	s_nop 0
	v_mov_b32_e32 v115, v107
	v_xor_b32_e32 v107, 0x80000000, v126
	v_mul_f32_e32 v126, 0x3f3504f3, v108
	v_mov_b32_e32 v106, v127
	v_pk_fma_f32 v[108:109], v[108:109], s[24:25], v[126:127] op_sel:[1,0,0] op_sel_hi:[1,1,0] neg_lo:[0,0,1] neg_hi:[0,0,1]
	v_pk_mul_f32 v[126:127], v[132:133], s[22:23] op_sel_hi:[1,0]
	s_nop 0
	v_pk_fma_f32 v[128:129], v[132:133], s[30:31], v[126:127] op_sel:[0,0,1] op_sel_hi:[1,0,0]
	v_pk_fma_f32 v[126:127], v[132:133], s[30:31], v[126:127] op_sel:[0,0,1] op_sel_hi:[1,0,0] neg_lo:[0,0,1] neg_hi:[0,0,1]
	s_nop 0
	v_mul_f32_e32 v126, 0x3f3504f3, v130
	v_mov_b32_e32 v129, v127
	v_pk_fma_f32 v[126:127], v[130:131], s[24:25], v[126:127] op_sel:[1,0,0] op_sel_hi:[1,1,0] neg_lo:[0,0,1] neg_hi:[0,0,1]
	v_pk_mul_f32 v[130:131], v[110:111], s[30:31]
	v_pk_add_f32 v[132:133], v[178:179], v[128:129]
	v_pk_fma_f32 v[110:111], v[110:111], s[22:23], v[130:131] op_sel:[0,0,1] op_sel_hi:[1,0,0] neg_lo:[1,0,0] neg_hi:[1,0,0]
	v_pk_add_f32 v[130:131], v[116:117], v[120:121]
	v_pk_add_f32 v[116:117], v[116:117], v[120:121] neg_lo:[0,1] neg_hi:[0,1]
	v_pk_add_f32 v[120:121], v[118:119], v[122:123]
	v_pk_add_f32 v[118:119], v[118:119], v[122:123] neg_lo:[0,1] neg_hi:[0,1]
	v_pk_add_f32 v[128:129], v[178:179], v[128:129] neg_lo:[0,1] neg_hi:[0,1]
	v_xor_b32_e32 v123, 0x80000000, v118
	v_mov_b32_e32 v122, v119
	v_pk_add_f32 v[118:119], v[130:131], v[120:121]
	v_pk_add_f32 v[120:121], v[130:131], v[120:121] neg_lo:[0,1] neg_hi:[0,1]
	v_pk_add_f32 v[130:131], v[116:117], v[122:123]
	v_pk_add_f32 v[116:117], v[116:117], v[122:123] neg_lo:[0,1] neg_hi:[0,1]
	v_pk_add_f32 v[122:123], v[176:177], v[114:115]
	v_pk_add_f32 v[114:115], v[176:177], v[114:115] neg_lo:[0,1] neg_hi:[0,1]
	v_xor_b32_e32 v177, 0x80000000, v128
	v_mov_b32_e32 v176, v129
	v_pk_add_f32 v[128:129], v[122:123], v[132:133]
	v_pk_add_f32 v[122:123], v[122:123], v[132:133] neg_lo:[0,1] neg_hi:[0,1]
	v_pk_add_f32 v[132:133], v[114:115], v[176:177]
	v_pk_add_f32 v[114:115], v[114:115], v[176:177] neg_lo:[0,1] neg_hi:[0,1]
	v_pk_add_f32 v[176:177], v[112:113], v[106:107]
	v_pk_add_f32 v[106:107], v[112:113], v[106:107] neg_lo:[0,1] neg_hi:[0,1]
	v_pk_add_f32 v[112:113], v[134:135], v[126:127]
	v_pk_add_f32 v[126:127], v[134:135], v[126:127] neg_lo:[0,1] neg_hi:[0,1]
	v_pk_add_f32 v[178:179], v[104:105], v[108:109]
	v_xor_b32_e32 v135, 0x80000000, v126
	v_mov_b32_e32 v134, v127
	v_pk_add_f32 v[108:109], v[104:105], v[108:109] neg_lo:[0,1] neg_hi:[0,1]
	v_pk_add_f32 v[104:105], v[124:125], v[110:111] neg_lo:[0,1] neg_hi:[0,1]
	v_pk_add_f32 v[126:127], v[176:177], v[112:113]
	v_pk_add_f32 v[112:113], v[176:177], v[112:113] neg_lo:[0,1] neg_hi:[0,1]
	v_pk_add_f32 v[176:177], v[106:107], v[134:135]
	v_pk_add_f32 v[134:135], v[106:107], v[134:135] neg_lo:[0,1] neg_hi:[0,1]
	v_pk_add_f32 v[180:181], v[124:125], v[110:111]
	v_xor_b32_e32 v111, 0x80000000, v104
	v_mov_b32_e32 v110, v105
	ds_read_b64 v[104:105], v189
	ds_read_b64 v[106:107], v189 offset:8
	v_pk_add_f32 v[124:125], v[178:179], v[180:181]
	v_pk_add_f32 v[178:179], v[178:179], v[180:181] neg_lo:[0,1] neg_hi:[0,1]
	v_pk_add_f32 v[180:181], v[108:109], v[110:111]
	v_pk_add_f32 v[182:183], v[108:109], v[110:111] neg_lo:[0,1] neg_hi:[0,1]
	ds_read_b64 v[108:109], v189 offset:16
	ds_read_b64 v[110:111], v189 offset:24
	s_waitcnt lgkmcnt(2)
	v_pk_mul_f32 v[184:185], v[104:105], v[118:119] op_sel:[1,1] op_sel_hi:[0,1]
	v_pk_fma_f32 v[186:187], v[104:105], v[118:119], v[184:185] neg_lo:[0,0,1] neg_hi:[0,0,1]
	v_pk_fma_f32 v[104:105], v[104:105], v[118:119], v[184:185] op_sel_hi:[1,0,1]
	s_nop 0
	v_mov_b32_e32 v187, v105
	v_pk_mul_f32 v[104:105], v[106:107], v[128:129] op_sel:[1,1] op_sel_hi:[0,1]
	v_pk_fma_f32 v[184:185], v[106:107], v[128:129], v[104:105] neg_lo:[0,0,1] neg_hi:[0,0,1]
	v_pk_fma_f32 v[104:105], v[106:107], v[128:129], v[104:105] op_sel_hi:[1,0,1]
	v_pk_mul_f32 v[118:119], v[28:29], v[186:187]
	v_mov_b32_e32 v185, v105
	s_waitcnt lgkmcnt(0)
	v_pk_mul_f32 v[104:105], v[108:109], v[126:127] op_sel:[1,1] op_sel_hi:[0,1]
	v_pk_fma_f32 v[106:107], v[108:109], v[126:127], v[104:105] neg_lo:[0,0,1] neg_hi:[0,0,1]
	v_pk_fma_f32 v[104:105], v[108:109], v[126:127], v[104:105] op_sel_hi:[1,0,1]
	v_pk_mul_f32 v[108:109], v[110:111], v[124:125] op_sel:[1,1] op_sel_hi:[0,1]
	v_mov_b32_e32 v107, v105
	v_pk_mul_f32 v[126:127], v[28:29], v[106:107]
	ds_read_b64 v[104:105], v189 offset:32
	ds_read_b64 v[106:107], v189 offset:40
	v_pk_mul_f32 v[128:129], v[28:29], v[184:185]
	v_pk_fma_f32 v[184:185], v[110:111], v[124:125], v[108:109] neg_lo:[0,0,1] neg_hi:[0,0,1]
	v_pk_fma_f32 v[108:109], v[110:111], v[124:125], v[108:109] op_sel_hi:[1,0,1]
	s_nop 0
	v_mov_b32_e32 v185, v109
	ds_read_b64 v[108:109], v189 offset:48
	ds_read_b64 v[110:111], v189 offset:56
	v_pk_mul_f32 v[124:125], v[28:29], v[184:185]
	s_waitcnt lgkmcnt(2)
	v_pk_mul_f32 v[184:185], v[104:105], v[130:131] op_sel:[1,1] op_sel_hi:[0,1]
	v_pk_fma_f32 v[186:187], v[104:105], v[130:131], v[184:185] neg_lo:[0,0,1] neg_hi:[0,0,1]
	v_pk_fma_f32 v[104:105], v[104:105], v[130:131], v[184:185] op_sel_hi:[1,0,1]
	s_nop 0
	v_mov_b32_e32 v187, v105
	v_pk_mul_f32 v[104:105], v[106:107], v[132:133] op_sel:[1,1] op_sel_hi:[0,1]
	v_pk_fma_f32 v[184:185], v[106:107], v[132:133], v[104:105] neg_lo:[0,0,1] neg_hi:[0,0,1]
	v_pk_fma_f32 v[104:105], v[106:107], v[132:133], v[104:105] op_sel_hi:[1,0,1]
	v_pk_mul_f32 v[130:131], v[28:29], v[186:187]
	v_mov_b32_e32 v185, v105
	s_waitcnt lgkmcnt(0)
	v_pk_mul_f32 v[104:105], v[108:109], v[176:177] op_sel:[1,1] op_sel_hi:[0,1]
	v_pk_fma_f32 v[106:107], v[108:109], v[176:177], v[104:105] neg_lo:[0,0,1] neg_hi:[0,0,1]
	v_pk_fma_f32 v[104:105], v[108:109], v[176:177], v[104:105] op_sel_hi:[1,0,1]
	v_pk_mul_f32 v[108:109], v[110:111], v[180:181] op_sel:[1,1] op_sel_hi:[0,1]
	v_mov_b32_e32 v107, v105
	v_pk_mul_f32 v[176:177], v[28:29], v[106:107]
	ds_read_b64 v[104:105], v189 offset:64
	ds_read_b64 v[106:107], v189 offset:72
	v_pk_mul_f32 v[132:133], v[28:29], v[184:185]
	v_pk_fma_f32 v[184:185], v[110:111], v[180:181], v[108:109] neg_lo:[0,0,1] neg_hi:[0,0,1]
	v_pk_fma_f32 v[108:109], v[110:111], v[180:181], v[108:109] op_sel_hi:[1,0,1]
	s_nop 0
	v_mov_b32_e32 v185, v109
	ds_read_b64 v[108:109], v189 offset:80
	ds_read_b64 v[110:111], v189 offset:88
	v_pk_mul_f32 v[180:181], v[28:29], v[184:185]
	s_waitcnt lgkmcnt(2)
	v_pk_mul_f32 v[184:185], v[120:121], v[104:105] op_sel:[1,1] op_sel_hi:[1,0]
	s_nop 0
	v_pk_fma_f32 v[186:187], v[120:121], v[104:105], v[184:185] neg_lo:[0,0,1] neg_hi:[0,0,1]
	v_pk_fma_f32 v[104:105], v[120:121], v[104:105], v[184:185] op_sel_hi:[0,1,1]
	v_mov_b32_e32 v187, v105
	v_pk_mul_f32 v[104:105], v[106:107], v[122:123] op_sel:[1,1] op_sel_hi:[0,1]
	v_pk_fma_f32 v[184:185], v[106:107], v[122:123], v[104:105] neg_lo:[0,0,1] neg_hi:[0,0,1]
	v_pk_fma_f32 v[104:105], v[106:107], v[122:123], v[104:105] op_sel_hi:[1,0,1]
	v_pk_mul_f32 v[120:121], v[28:29], v[186:187]
	v_mov_b32_e32 v185, v105
	s_waitcnt lgkmcnt(0)
	v_pk_mul_f32 v[104:105], v[112:113], v[108:109] op_sel:[1,1] op_sel_hi:[1,0]
	v_pk_mul_f32 v[122:123], v[28:29], v[184:185]
	v_pk_fma_f32 v[106:107], v[112:113], v[108:109], v[104:105] neg_lo:[0,0,1] neg_hi:[0,0,1]
	v_pk_fma_f32 v[104:105], v[112:113], v[108:109], v[104:105] op_sel_hi:[0,1,1]
	v_mov_b32_e32 v107, v105
	v_pk_mul_f32 v[112:113], v[28:29], v[106:107]
	v_pk_mul_f32 v[108:109], v[178:179], v[110:111] op_sel:[1,1] op_sel_hi:[1,0]
	ds_read_b64 v[104:105], v189 offset:96
	ds_read_b64 v[106:107], v189 offset:104
	v_pk_fma_f32 v[184:185], v[178:179], v[110:111], v[108:109] neg_lo:[0,0,1] neg_hi:[0,0,1]
	v_pk_fma_f32 v[108:109], v[178:179], v[110:111], v[108:109] op_sel_hi:[0,1,1]
	v_mov_b32_e32 v185, v109
	ds_read_b64 v[108:109], v189 offset:112
	ds_read_b64 v[110:111], v189 offset:120
	v_pk_mul_f32 v[178:179], v[28:29], v[184:185]
	s_waitcnt lgkmcnt(2)
	v_pk_mul_f32 v[184:185], v[116:117], v[104:105] op_sel:[1,1] op_sel_hi:[1,0]
	s_nop 0
	v_pk_fma_f32 v[186:187], v[116:117], v[104:105], v[184:185] neg_lo:[0,0,1] neg_hi:[0,0,1]
	v_pk_fma_f32 v[104:105], v[116:117], v[104:105], v[184:185] op_sel_hi:[0,1,1]
	v_pk_mul_f32 v[116:117], v[106:107], v[114:115] op_sel:[1,1] op_sel_hi:[0,1]
	v_pk_fma_f32 v[184:185], v[106:107], v[114:115], v[116:117] neg_lo:[0,0,1] neg_hi:[0,0,1]
	v_pk_fma_f32 v[106:107], v[106:107], v[114:115], v[116:117] op_sel_hi:[1,0,1]
	s_waitcnt lgkmcnt(0)
	v_pk_mul_f32 v[114:115], v[134:135], v[108:109] op_sel:[1,1] op_sel_hi:[1,0]
	v_mov_b32_e32 v187, v105
	v_pk_fma_f32 v[116:117], v[134:135], v[108:109], v[114:115] neg_lo:[0,0,1] neg_hi:[0,0,1]
	v_pk_fma_f32 v[108:109], v[134:135], v[108:109], v[114:115] op_sel_hi:[0,1,1]
	v_mov_b32_e32 v117, v109
	v_pk_mul_f32 v[114:115], v[182:183], v[110:111] op_sel:[1,1] op_sel_hi:[1,0]
	v_pk_mul_f32 v[108:109], v[28:29], v[116:117]
	v_pk_fma_f32 v[116:117], v[182:183], v[110:111], v[114:115] neg_lo:[0,0,1] neg_hi:[0,0,1]
	v_pk_fma_f32 v[110:111], v[182:183], v[110:111], v[114:115] op_sel_hi:[0,1,1]
	v_pk_mul_f32 v[104:105], v[28:29], v[186:187]
	v_mov_b32_e32 v185, v107
	v_mov_b32_e32 v117, v111
	v_pk_mul_f32 v[106:107], v[28:29], v[184:185]
	v_pk_mul_f32 v[110:111], v[28:29], v[116:117]
	ds_write2_b64 v188, v[118:119], v[128:129] offset1:1
	ds_write2_b64 v188, v[126:127], v[124:125] offset0:2 offset1:3
	ds_write2_b64 v188, v[130:131], v[132:133] offset0:4 offset1:5
	ds_write2_b64 v188, v[176:177], v[180:181] offset0:6 offset1:7
	ds_write2_b64 v188, v[120:121], v[122:123] offset0:8 offset1:9
	ds_write2_b64 v188, v[112:113], v[178:179] offset0:10 offset1:11
	ds_write2_b64 v188, v[104:105], v[106:107] offset0:12 offset1:13
	ds_write2_b64 v188, v[108:109], v[110:111] offset0:14 offset1:15
	v_mov_b32_e32 v104, v208
	s_waitcnt lgkmcnt(0)
	s_barrier
	s_nop 0
	v_lshlrev_b32_e32 v105, 4, v104
	v_ashrrev_i32_e32 v105, 1, v105
	v_lshlrev_b32_e32 v104, 7, v104
	v_add3_u32 v180, s35, v105, v104
	ds_read_b64 v[104:105], v180
	ds_read_b64 v[106:107], v180 offset:8
	ds_read_b64 v[108:109], v180 offset:16
	ds_read_b64 v[110:111], v180 offset:24
	ds_read_b64 v[112:113], v180 offset:64
	ds_read_b64 v[114:115], v180 offset:72
	ds_read_b64 v[116:117], v180 offset:32
	ds_read_b64 v[118:119], v180 offset:40
	ds_read_b64 v[120:121], v180 offset:48
	ds_read_b64 v[122:123], v180 offset:56
	ds_read_b64 v[124:125], v180 offset:96
	ds_read_b64 v[126:127], v180 offset:104
	ds_read_b64 v[128:129], v180 offset:80
	ds_read_b64 v[130:131], v180 offset:88
	ds_read_b64 v[132:133], v180 offset:112
	ds_read_b64 v[134:135], v180 offset:120
	s_waitcnt lgkmcnt(10)
	v_pk_add_f32 v[176:177], v[104:105], v[112:113]
	v_pk_add_f32 v[104:105], v[104:105], v[112:113] neg_lo:[0,1] neg_hi:[0,1]
	s_waitcnt lgkmcnt(4)
	v_pk_add_f32 v[112:113], v[116:117], v[124:125]
	v_pk_add_f32 v[116:117], v[116:117], v[124:125] neg_lo:[0,1] neg_hi:[0,1]
	s_nop 0
	v_xor_b32_e32 v124, 0x80000000, v117
	v_mov_b32_e32 v125, v116
	v_pk_add_f32 v[116:117], v[176:177], v[112:113]
	v_pk_add_f32 v[112:113], v[176:177], v[112:113] neg_lo:[0,1] neg_hi:[0,1]
	v_pk_add_f32 v[176:177], v[104:105], v[124:125]
	v_pk_add_f32 v[104:105], v[104:105], v[124:125] neg_lo:[0,1] neg_hi:[0,1]
	v_pk_add_f32 v[124:125], v[106:107], v[114:115]
	v_pk_add_f32 v[106:107], v[106:107], v[114:115] neg_lo:[0,1] neg_hi:[0,1]
	v_pk_add_f32 v[114:115], v[118:119], v[126:127]
	v_pk_add_f32 v[118:119], v[118:119], v[126:127] neg_lo:[0,1] neg_hi:[0,1]
	s_nop 0
	v_xor_b32_e32 v126, 0x80000000, v119
	v_mov_b32_e32 v127, v118
	v_pk_add_f32 v[118:119], v[124:125], v[114:115]
	v_pk_add_f32 v[114:115], v[124:125], v[114:115] neg_lo:[0,1] neg_hi:[0,1]
	v_pk_add_f32 v[124:125], v[106:107], v[126:127]
	v_pk_add_f32 v[106:107], v[106:107], v[126:127] neg_lo:[0,1] neg_hi:[0,1]
	s_waitcnt lgkmcnt(2)
	v_pk_add_f32 v[126:127], v[108:109], v[128:129]
	v_pk_add_f32 v[108:109], v[108:109], v[128:129] neg_lo:[0,1] neg_hi:[0,1]
	s_waitcnt lgkmcnt(0)
	v_pk_add_f32 v[128:129], v[120:121], v[132:133]
	v_pk_add_f32 v[120:121], v[120:121], v[132:133] neg_lo:[0,1] neg_hi:[0,1]
	s_nop 0
	v_xor_b32_e32 v132, 0x80000000, v121
	v_mov_b32_e32 v133, v120
	v_pk_add_f32 v[120:121], v[126:127], v[128:129]
	v_pk_add_f32 v[126:127], v[126:127], v[128:129] neg_lo:[0,1] neg_hi:[0,1]
	v_pk_add_f32 v[128:129], v[108:109], v[132:133]
	v_pk_add_f32 v[108:109], v[108:109], v[132:133] neg_lo:[0,1] neg_hi:[0,1]
	v_pk_add_f32 v[132:133], v[110:111], v[130:131]
	v_pk_add_f32 v[110:111], v[110:111], v[130:131] neg_lo:[0,1] neg_hi:[0,1]
	v_pk_add_f32 v[130:131], v[122:123], v[134:135]
	v_pk_add_f32 v[122:123], v[122:123], v[134:135] neg_lo:[0,1] neg_hi:[0,1]
	s_nop 0
	v_xor_b32_e32 v134, 0x80000000, v123
	v_mov_b32_e32 v135, v122
	v_pk_add_f32 v[122:123], v[132:133], v[130:131]
	v_pk_add_f32 v[130:131], v[132:133], v[130:131] neg_lo:[0,1] neg_hi:[0,1]
	v_pk_add_f32 v[132:133], v[110:111], v[134:135]
	v_pk_add_f32 v[110:111], v[110:111], v[134:135] neg_lo:[0,1] neg_hi:[0,1]
	v_pk_mul_f32 v[134:135], v[124:125], s[30:31] op_sel_hi:[1,0]
	s_nop 0
	v_pk_fma_f32 v[178:179], v[124:125], s[22:23], v[134:135] op_sel:[0,0,1] op_sel_hi:[1,0,0] neg_lo:[0,0,1] neg_hi:[0,0,1]
	v_pk_fma_f32 v[124:125], v[124:125], s[22:23], v[134:135] op_sel:[0,0,1] op_sel_hi:[1,0,0]
	s_nop 0
	v_mov_b32_e32 v179, v125
	v_pk_mul_f32 v[124:125], v[114:115], s[24:25] op_sel_hi:[1,0]
	s_nop 0
	v_pk_fma_f32 v[134:135], v[114:115], s[24:25], v[124:125] op_sel:[0,0,1] op_sel_hi:[1,0,0] neg_lo:[0,0,1] neg_hi:[0,0,1]
	v_pk_fma_f32 v[114:115], v[114:115], s[24:25], v[124:125] op_sel_hi:[1,0,0]
	s_nop 0
	v_mov_b32_e32 v135, v115
	v_pk_mul_f32 v[114:115], v[106:107], s[22:23] op_sel_hi:[1,0]
	s_nop 0
	v_pk_fma_f32 v[124:125], v[106:107], s[30:31], v[114:115] op_sel:[0,0,1] op_sel_hi:[1,0,0] neg_lo:[0,0,1] neg_hi:[0,0,1]
	v_pk_fma_f32 v[106:107], v[106:107], s[30:31], v[114:115] op_sel:[0,0,1] op_sel_hi:[1,0,0]
	s_nop 0
	v_mov_b32_e32 v125, v107
	v_pk_mul_f32 v[106:107], v[128:129], s[24:25] op_sel_hi:[1,0]
	s_nop 0
	v_pk_fma_f32 v[114:115], v[128:129], s[24:25], v[106:107] op_sel:[0,0,1] op_sel_hi:[1,0,0] neg_lo:[0,0,1] neg_hi:[0,0,1]
	v_pk_fma_f32 v[106:107], v[128:129], s[24:25], v[106:107] op_sel_hi:[1,0,0]
	s_nop 0
	v_mov_b32_e32 v115, v107
	v_mov_b32_e32 v107, v126
	v_mul_f32_e32 v126, 0x3f3504f3, v109
	v_xor_b32_e32 v106, 0x80000000, v127
	v_pk_fma_f32 v[108:109], v[108:109], s[18:19], v[126:127] op_sel_hi:[0,1,0] neg_lo:[0,0,1] neg_hi:[0,0,1]
	v_pk_mul_f32 v[126:127], v[132:133], s[22:23] op_sel_hi:[1,0]
	s_nop 0
	v_pk_fma_f32 v[128:129], v[132:133], s[30:31], v[126:127] op_sel:[0,0,1] op_sel_hi:[1,0,0] neg_lo:[0,0,1] neg_hi:[0,0,1]
	v_pk_fma_f32 v[126:127], v[132:133], s[30:31], v[126:127] op_sel:[0,0,1] op_sel_hi:[1,0,0]
	s_nop 0
	v_mul_f32_e32 v126, 0x3f3504f3, v131
	v_mov_b32_e32 v129, v127
	v_pk_fma_f32 v[126:127], v[130:131], s[18:19], v[126:127] op_sel_hi:[0,1,0] neg_lo:[0,0,1] neg_hi:[0,0,1]
	v_pk_mul_f32 v[130:131], v[110:111], s[88:89]
	v_pk_add_f32 v[132:133], v[178:179], v[128:129]
	v_pk_fma_f32 v[110:111], v[110:111], s[22:23], v[130:131] op_sel:[0,0,1] op_sel_hi:[1,0,0] neg_lo:[1,0,0] neg_hi:[1,0,0]
	v_pk_add_f32 v[130:131], v[116:117], v[120:121]
	v_pk_add_f32 v[116:117], v[116:117], v[120:121] neg_lo:[0,1] neg_hi:[0,1]
	v_pk_add_f32 v[120:121], v[118:119], v[122:123]
	v_pk_add_f32 v[118:119], v[118:119], v[122:123] neg_lo:[0,1] neg_hi:[0,1]
	v_pk_add_f32 v[128:129], v[178:179], v[128:129] neg_lo:[0,1] neg_hi:[0,1]
	v_xor_b32_e32 v122, 0x80000000, v119
	v_mov_b32_e32 v123, v118
	v_pk_add_f32 v[118:119], v[130:131], v[120:121]
	v_pk_add_f32 v[120:121], v[130:131], v[120:121] neg_lo:[0,1] neg_hi:[0,1]
	v_pk_add_f32 v[130:131], v[116:117], v[122:123]
	v_pk_add_f32 v[116:117], v[116:117], v[122:123] neg_lo:[0,1] neg_hi:[0,1]
	v_pk_add_f32 v[122:123], v[176:177], v[114:115]
	v_pk_add_f32 v[114:115], v[176:177], v[114:115] neg_lo:[0,1] neg_hi:[0,1]
	v_xor_b32_e32 v176, 0x80000000, v129
	v_mov_b32_e32 v177, v128
	v_pk_add_f32 v[128:129], v[122:123], v[132:133]
	v_pk_add_f32 v[122:123], v[122:123], v[132:133] neg_lo:[0,1] neg_hi:[0,1]
	v_pk_add_f32 v[132:133], v[114:115], v[176:177]
	v_pk_add_f32 v[114:115], v[114:115], v[176:177] neg_lo:[0,1] neg_hi:[0,1]
	v_pk_add_f32 v[176:177], v[112:113], v[106:107]
	v_pk_add_f32 v[106:107], v[112:113], v[106:107] neg_lo:[0,1] neg_hi:[0,1]
	v_pk_add_f32 v[112:113], v[134:135], v[126:127]
	v_pk_add_f32 v[126:127], v[134:135], v[126:127] neg_lo:[0,1] neg_hi:[0,1]
	s_nop 0
	v_xor_b32_e32 v134, 0x80000000, v127
	v_mov_b32_e32 v135, v126
	v_pk_add_f32 v[126:127], v[176:177], v[112:113]
	v_pk_add_f32 v[112:113], v[176:177], v[112:113] neg_lo:[0,1] neg_hi:[0,1]
	v_pk_add_f32 v[176:177], v[106:107], v[134:135]
	v_pk_add_f32 v[106:107], v[106:107], v[134:135] neg_lo:[0,1] neg_hi:[0,1]
	v_pk_add_f32 v[134:135], v[104:105], v[108:109]
	v_pk_add_f32 v[104:105], v[104:105], v[108:109] neg_lo:[0,1] neg_hi:[0,1]
	v_pk_add_f32 v[108:109], v[124:125], v[110:111]
	v_pk_add_f32 v[110:111], v[124:125], v[110:111] neg_lo:[0,1] neg_hi:[0,1]
	s_nop 0
	v_xor_b32_e32 v124, 0x80000000, v111
	v_mov_b32_e32 v125, v110
	v_pk_add_f32 v[110:111], v[134:135], v[108:109]
	v_pk_add_f32 v[108:109], v[134:135], v[108:109] neg_lo:[0,1] neg_hi:[0,1]
	v_pk_add_f32 v[134:135], v[104:105], v[124:125]
	v_pk_add_f32 v[104:105], v[104:105], v[124:125] neg_lo:[0,1] neg_hi:[0,1]
	ds_write2_b64 v180, v[118:119], v[128:129] offset1:1
	ds_write2_b64 v180, v[126:127], v[110:111] offset0:2 offset1:3
	ds_write2_b64 v180, v[130:131], v[132:133] offset0:4 offset1:5
	ds_write2_b64 v180, v[176:177], v[134:135] offset0:6 offset1:7
	ds_write2_b64 v180, v[120:121], v[122:123] offset0:8 offset1:9
	ds_write2_b64 v180, v[112:113], v[108:109] offset0:10 offset1:11
	ds_write2_b64 v180, v[116:117], v[114:115] offset0:12 offset1:13
	ds_write2_b64 v180, v[106:107], v[104:105] offset0:14 offset1:15
	v_mov_b32_e32 v104, v208
	s_waitcnt lgkmcnt(0)
	s_nop 0
	v_and_b32_e32 v128, 15, v104
	v_lshlrev_b32_e32 v106, 3, v128
	v_cvt_f32_ubyte0_e32 v128, v128
	v_mul_f32_e32 v205, 0x3b800000, v128
	v_mul_f32_e32 v128, 0x41400000, v205
	v_sin_f32_e32 v176, v128
	v_sin_f32_e32 v178, v205
	v_cos_f32_e32 v177, v128
	v_cos_f32_e32 v180, v205
	v_lshlrev_b32_e32 v104, 4, v104
	v_and_b32_e32 v104, 0xffffff00, v104
	v_pk_mul_f32 v[182:183], v[178:179], v[176:177] op_sel_hi:[0,1]
	v_ashrrev_i32_e32 v105, 1, v104
	v_pk_fma_f32 v[184:185], v[180:181], v[176:177], v[182:183] op_sel:[0,0,1] op_sel_hi:[0,1,0]
	v_pk_fma_f32 v[182:183], v[180:181], v[176:177], v[182:183] op_sel:[0,0,1] op_sel_hi:[0,1,0] neg_lo:[0,0,1] neg_hi:[0,0,1]
	v_add_u32_e32 v105, s35, v105
	v_lshlrev_b32_e32 v104, 3, v104
	v_pk_mov_b32 v[188:189], v[182:183], v[184:185] op_sel:[1,0]
	v_add3_u32 v204, v105, v104, v106
	v_mov_b32_e32 v186, v184
	v_mov_b32_e32 v187, v183
	v_pk_mul_f32 v[188:189], v[178:179], v[188:189] op_sel_hi:[0,1]
	v_mov_b32_e32 v179, v180
	ds_read_b64 v[104:105], v204
	ds_read_b64 v[106:107], v204 offset:136
	ds_read_b64 v[108:109], v204 offset:272
	ds_read_b64 v[110:111], v204 offset:408
	ds_read_b64 v[112:113], v204 offset:544
	ds_read_b64 v[114:115], v204 offset:680
	ds_read_b64 v[116:117], v204 offset:816
	ds_read_b64 v[118:119], v204 offset:952
	ds_read_b64 v[120:121], v204 offset:1088
	ds_read_b64 v[122:123], v204 offset:1224
	ds_read_b64 v[124:125], v204 offset:1360
	ds_read_b64 v[126:127], v204 offset:1496
	v_pk_fma_f32 v[190:191], v[180:181], v[186:187], v[188:189] op_sel_hi:[0,1,1]
	v_pk_fma_f32 v[186:187], v[180:181], v[186:187], v[188:189] op_sel_hi:[0,1,1] neg_lo:[0,0,1] neg_hi:[0,0,1]
	v_mov_b32_e32 v181, v178
	s_waitcnt lgkmcnt(10)
	v_pk_mul_f32 v[194:195], v[106:107], v[178:179] op_sel_hi:[1,0]
	ds_read_b64 v[128:129], v204 offset:1632
	ds_read_b64 v[130:131], v204 offset:1768
	ds_read_b64 v[132:133], v204 offset:1904
	ds_read_b64 v[134:135], v204 offset:2040
	v_pk_fma_f32 v[196:197], v[106:107], v[180:181], v[194:195] op_sel:[0,0,1] op_sel_hi:[1,1,0] neg_lo:[0,0,1] neg_hi:[0,0,1]
	v_pk_fma_f32 v[106:107], v[106:107], v[180:181], v[194:195] op_sel:[0,0,1] op_sel_hi:[1,0,0]
	v_mov_b32_e32 v188, v190
	v_mov_b32_e32 v197, v107
	v_pk_mul_f32 v[106:107], v[178:179], v[178:179] op_sel:[0,1] op_sel_hi:[0,0]
	v_pk_fma_f32 v[194:195], v[180:181], v[178:179], v[106:107] op_sel_hi:[0,1,1]
	v_pk_fma_f32 v[106:107], v[180:181], v[178:179], v[106:107] op_sel_hi:[0,1,1] neg_lo:[0,0,1] neg_hi:[0,0,1]
	v_mov_b32_e32 v198, v194
	v_mov_b32_e32 v199, v107
	s_waitcnt lgkmcnt(12)
	v_pk_mul_f32 v[194:195], v[108:109], v[194:195] op_sel:[1,0] op_sel_hi:[0,0]
	v_pk_fma_f32 v[200:201], v[108:109], v[106:107], v[194:195] op_sel:[0,1,0] neg_lo:[0,0,1] neg_hi:[0,0,1]
	v_pk_fma_f32 v[106:107], v[108:109], v[106:107], v[194:195] op_sel:[0,1,0]
	v_pk_mul_f32 v[108:109], v[178:179], v[198:199] op_sel:[1,0] op_sel_hi:[0,1]
	v_mov_b32_e32 v201, v107
	v_pk_mul_f32 v[106:107], v[178:179], v[198:199]
	v_pk_add_f32 v[108:109], v[108:109], v[108:109] op_sel:[0,1] op_sel_hi:[0,1]
	v_pk_mul_f32 v[108:109], v[110:111], v[108:109] op_sel:[1,0] op_sel_hi:[0,1]
	v_pk_add_f32 v[106:107], v[106:107], v[106:107] op_sel:[1,0] op_sel_hi:[1,0] neg_lo:[0,1] neg_hi:[0,1]
	v_mov_b32_e32 v189, v187
	v_pk_fma_f32 v[194:195], v[110:111], v[106:107], v[108:109] neg_lo:[0,0,1] neg_hi:[0,0,1]
	v_pk_fma_f32 v[106:107], v[110:111], v[106:107], v[108:109]
	v_mul_f32_e32 v195, 4.0, v205
	v_sin_f32_e32 v198, v195
	v_cos_f32_e32 v202, v195
	v_mov_b32_e32 v195, v107
	v_pk_mul_f32 v[192:193], v[180:181], v[188:189]
	s_waitcnt lgkmcnt(10)
	v_pk_mul_f32 v[106:107], v[198:199], v[112:113] op_sel:[0,1] op_sel_hi:[0,0]
	v_pk_fma_f32 v[108:109], v[202:203], v[112:113], v[106:107] neg_lo:[0,0,1] neg_hi:[0,0,1]
	v_pk_fma_f32 v[106:107], v[202:203], v[112:113], v[106:107] op_sel_hi:[0,1,1]
	v_mov_b32_e32 v199, v202
	v_mov_b32_e32 v109, v107
	v_pk_mul_f32 v[106:107], v[178:179], v[198:199] op_sel_hi:[0,1]
	v_pk_fma_f32 v[110:111], v[180:181], v[198:199], v[106:107] op_sel:[0,0,1] op_sel_hi:[0,1,0]
	v_pk_fma_f32 v[106:107], v[180:181], v[198:199], v[106:107] op_sel:[0,0,1] op_sel_hi:[0,1,0] neg_lo:[0,0,1] neg_hi:[0,0,1]
	v_pk_mul_f32 v[198:199], v[110:111], v[114:115] op_sel:[0,1] op_sel_hi:[0,0]
	v_mov_b32_e32 v112, v110
	v_mov_b32_e32 v113, v107
	v_pk_mov_b32 v[110:111], v[106:107], v[110:111] op_sel:[1,0]
	v_pk_fma_f32 v[202:203], v[106:107], v[114:115], v[198:199] op_sel:[1,0,0] neg_lo:[0,0,1] neg_hi:[0,0,1]
	v_pk_fma_f32 v[106:107], v[106:107], v[114:115], v[198:199] op_sel:[1,0,0]
	v_pk_mul_f32 v[188:189], v[178:179], v[188:189]
	v_mov_b32_e32 v203, v107
	v_pk_mul_f32 v[106:107], v[178:179], v[110:111] op_sel_hi:[0,1]
	v_pk_fma_f32 v[110:111], v[180:181], v[112:113], v[106:107] op_sel_hi:[0,1,1]
	v_pk_fma_f32 v[106:107], v[180:181], v[112:113], v[106:107] op_sel_hi:[0,1,1] neg_lo:[0,0,1] neg_hi:[0,0,1]
	v_mov_b32_e32 v112, v110
	v_mov_b32_e32 v113, v107
	s_waitcnt lgkmcnt(8)
	v_pk_mul_f32 v[110:111], v[116:117], v[110:111] op_sel:[1,0] op_sel_hi:[0,0]
	v_pk_fma_f32 v[114:115], v[116:117], v[106:107], v[110:111] op_sel:[0,1,0] neg_lo:[0,0,1] neg_hi:[0,0,1]
	v_pk_fma_f32 v[106:107], v[116:117], v[106:107], v[110:111] op_sel:[0,1,0]
	v_pk_mul_f32 v[110:111], v[180:181], v[112:113]
	v_mov_b32_e32 v115, v107
	v_pk_mul_f32 v[106:107], v[178:179], v[112:113]
	v_pk_add_f32 v[110:111], v[110:111], v[110:111] op_sel:[0,1] op_sel_hi:[0,1]
	v_pk_mul_f32 v[110:111], v[118:119], v[110:111] op_sel:[1,0] op_sel_hi:[0,1]
	v_pk_add_f32 v[106:107], v[106:107], v[106:107] op_sel:[1,0] op_sel_hi:[1,0] neg_lo:[0,1] neg_hi:[0,1]
	s_nop 0
	v_pk_fma_f32 v[112:113], v[118:119], v[106:107], v[110:111] neg_lo:[0,0,1] neg_hi:[0,0,1]
	v_pk_fma_f32 v[106:107], v[118:119], v[106:107], v[110:111]
	v_mul_f32_e32 v113, 0x41000000, v205
	v_sin_f32_e32 v116, v113
	v_cos_f32_e32 v198, v113
	v_mov_b32_e32 v113, v107
	s_waitcnt lgkmcnt(6)
	v_pk_mul_f32 v[106:107], v[116:117], v[120:121] op_sel:[0,1] op_sel_hi:[0,0]
	v_pk_fma_f32 v[110:111], v[198:199], v[120:121], v[106:107] neg_lo:[0,0,1] neg_hi:[0,0,1]
	v_pk_fma_f32 v[106:107], v[198:199], v[120:121], v[106:107] op_sel_hi:[0,1,1]
	v_mov_b32_e32 v117, v198
	v_mov_b32_e32 v111, v107
	v_pk_mul_f32 v[106:107], v[178:179], v[116:117] op_sel_hi:[0,1]
	v_pk_fma_f32 v[118:119], v[180:181], v[116:117], v[106:107] op_sel:[0,0,1] op_sel_hi:[0,1,0]
	v_pk_fma_f32 v[106:107], v[180:181], v[116:117], v[106:107] op_sel:[0,0,1] op_sel_hi:[0,1,0] neg_lo:[0,0,1] neg_hi:[0,0,1]
	v_pk_mul_f32 v[120:121], v[118:119], v[122:123] op_sel:[0,1] op_sel_hi:[0,0]
	v_mov_b32_e32 v116, v118
	v_mov_b32_e32 v117, v107
	v_pk_mov_b32 v[118:119], v[106:107], v[118:119] op_sel:[1,0]
	v_pk_fma_f32 v[198:199], v[106:107], v[122:123], v[120:121] op_sel:[1,0,0] neg_lo:[0,0,1] neg_hi:[0,0,1]
	v_pk_fma_f32 v[106:107], v[106:107], v[122:123], v[120:121] op_sel:[1,0,0]
	v_mov_b32_e32 v122, v177
	v_mov_b32_e32 v199, v107
	v_pk_mul_f32 v[106:107], v[178:179], v[118:119] op_sel_hi:[0,1]
	v_pk_fma_f32 v[118:119], v[180:181], v[116:117], v[106:107] op_sel_hi:[0,1,1]
	v_pk_fma_f32 v[106:107], v[180:181], v[116:117], v[106:107] op_sel_hi:[0,1,1] neg_lo:[0,0,1] neg_hi:[0,0,1]
	v_mov_b32_e32 v116, v118
	s_waitcnt lgkmcnt(4)
	v_pk_mul_f32 v[118:119], v[118:119], v[124:125] op_sel:[0,1] op_sel_hi:[0,0]
	v_mov_b32_e32 v117, v107
	v_pk_fma_f32 v[120:121], v[106:107], v[124:125], v[118:119] op_sel:[1,0,0] neg_lo:[0,0,1] neg_hi:[0,0,1]
	v_pk_fma_f32 v[106:107], v[106:107], v[124:125], v[118:119] op_sel:[1,0,0]
	s_nop 0
	v_mov_b32_e32 v121, v107
	v_pk_mul_f32 v[106:107], v[178:179], v[116:117]
	v_pk_mul_f32 v[116:117], v[180:181], v[116:117]
	v_pk_add_f32 v[106:107], v[106:107], v[106:107] op_sel:[1,0] op_sel_hi:[1,0] neg_lo:[0,1] neg_hi:[0,1]
	v_pk_add_f32 v[116:117], v[116:117], v[116:117] op_sel:[0,1] op_sel_hi:[0,1]
	v_pk_mul_f32 v[116:117], v[116:117], v[126:127] op_sel:[0,1] op_sel_hi:[1,0]
	s_nop 0
	v_pk_fma_f32 v[118:119], v[106:107], v[126:127], v[116:117] neg_lo:[0,0,1] neg_hi:[0,0,1]
	v_pk_fma_f32 v[106:107], v[106:107], v[126:127], v[116:117]
	v_mov_b32_e32 v116, v177
	v_mov_b32_e32 v119, v107
	s_waitcnt lgkmcnt(2)
	v_pk_mul_f32 v[106:107], v[176:177], v[128:129] op_sel:[0,1] op_sel_hi:[0,0]
	v_pk_fma_f32 v[116:117], v[116:117], v[128:129], v[106:107] neg_lo:[0,0,1] neg_hi:[0,0,1]
	v_pk_fma_f32 v[106:107], v[122:123], v[128:129], v[106:107] op_sel_hi:[0,1,1]
	v_mov_b32_e32 v117, v107
	v_pk_mul_f32 v[106:107], v[184:185], v[130:131] op_sel:[0,1] op_sel_hi:[0,0]
	v_pk_fma_f32 v[122:123], v[182:183], v[130:131], v[106:107] op_sel:[1,0,0] neg_lo:[0,0,1] neg_hi:[0,0,1]
	v_pk_fma_f32 v[106:107], v[182:183], v[130:131], v[106:107] op_sel:[1,0,0]
	v_pk_add_f32 v[126:127], v[192:193], v[192:193] op_sel:[0,1] op_sel_hi:[0,1]
	v_mov_b32_e32 v123, v107
	s_waitcnt lgkmcnt(0)
	v_pk_mul_f32 v[106:107], v[190:191], v[132:133] op_sel:[0,1] op_sel_hi:[0,0]
	v_pk_fma_f32 v[124:125], v[186:187], v[132:133], v[106:107] op_sel:[1,0,0] neg_lo:[0,0,1] neg_hi:[0,0,1]
	v_pk_fma_f32 v[106:107], v[186:187], v[132:133], v[106:107] op_sel:[1,0,0]
	v_pk_mul_f32 v[126:127], v[126:127], v[134:135] op_sel:[0,1] op_sel_hi:[1,0]
	v_mov_b32_e32 v125, v107
	v_pk_add_f32 v[106:107], v[188:189], v[188:189] op_sel:[1,0] op_sel_hi:[1,0] neg_lo:[0,1] neg_hi:[0,1]
	v_pk_add_f32 v[130:131], v[202:203], v[122:123]
	v_pk_fma_f32 v[128:129], v[106:107], v[134:135], v[126:127] neg_lo:[0,0,1] neg_hi:[0,0,1]
	v_pk_fma_f32 v[106:107], v[106:107], v[134:135], v[126:127]
	v_pk_add_f32 v[122:123], v[202:203], v[122:123] neg_lo:[0,1] neg_hi:[0,1]
	v_mov_b32_e32 v129, v107
	v_pk_add_f32 v[106:107], v[104:105], v[110:111]
	v_pk_add_f32 v[104:105], v[104:105], v[110:111] neg_lo:[0,1] neg_hi:[0,1]
	v_pk_add_f32 v[110:111], v[108:109], v[116:117]
	v_pk_add_f32 v[108:109], v[108:109], v[116:117] neg_lo:[0,1] neg_hi:[0,1]
	v_pk_add_f32 v[126:127], v[196:197], v[198:199] neg_lo:[0,1] neg_hi:[0,1]
	v_xor_b32_e32 v116, 0x80000000, v109
	v_mov_b32_e32 v117, v108
	v_pk_add_f32 v[108:109], v[106:107], v[110:111]
	v_pk_add_f32 v[106:107], v[106:107], v[110:111] neg_lo:[0,1] neg_hi:[0,1]
	v_pk_add_f32 v[110:111], v[104:105], v[116:117]
	v_pk_add_f32 v[104:105], v[104:105], v[116:117] neg_lo:[0,1] neg_hi:[0,1]
	v_pk_add_f32 v[116:117], v[196:197], v[198:199]
	v_xor_b32_e32 v132, 0x80000000, v123
	v_mov_b32_e32 v133, v122
	v_pk_add_f32 v[134:135], v[114:115], v[124:125]
	v_pk_add_f32 v[114:115], v[114:115], v[124:125] neg_lo:[0,1] neg_hi:[0,1]
	v_pk_add_f32 v[122:123], v[116:117], v[130:131]
	v_pk_add_f32 v[116:117], v[116:117], v[130:131] neg_lo:[0,1] neg_hi:[0,1]
	v_pk_add_f32 v[130:131], v[126:127], v[132:133]
	v_pk_add_f32 v[126:127], v[126:127], v[132:133] neg_lo:[0,1] neg_hi:[0,1]
	v_pk_add_f32 v[132:133], v[200:201], v[120:121]
	v_pk_add_f32 v[120:121], v[200:201], v[120:121] neg_lo:[0,1] neg_hi:[0,1]
	v_xor_b32_e32 v124, 0x80000000, v115
	v_mov_b32_e32 v125, v114
	v_pk_add_f32 v[176:177], v[112:113], v[128:129]
	v_pk_add_f32 v[112:113], v[112:113], v[128:129] neg_lo:[0,1] neg_hi:[0,1]
	v_pk_add_f32 v[114:115], v[132:133], v[134:135]
	v_pk_add_f32 v[132:133], v[132:133], v[134:135] neg_lo:[0,1] neg_hi:[0,1]
	v_pk_add_f32 v[134:135], v[120:121], v[124:125]
	v_pk_add_f32 v[120:121], v[120:121], v[124:125] neg_lo:[0,1] neg_hi:[0,1]
	v_pk_add_f32 v[124:125], v[194:195], v[118:119]
	v_pk_add_f32 v[118:119], v[194:195], v[118:119] neg_lo:[0,1] neg_hi:[0,1]
	v_xor_b32_e32 v128, 0x80000000, v113
	v_mov_b32_e32 v129, v112
	v_pk_add_f32 v[112:113], v[124:125], v[176:177]
	v_pk_add_f32 v[124:125], v[124:125], v[176:177] neg_lo:[0,1] neg_hi:[0,1]
	v_pk_add_f32 v[176:177], v[118:119], v[128:129]
	v_pk_add_f32 v[118:119], v[118:119], v[128:129] neg_lo:[0,1] neg_hi:[0,1]
	v_pk_mul_f32 v[128:129], v[130:131], s[30:31] op_sel_hi:[1,0]
	s_nop 0
	v_pk_fma_f32 v[178:179], v[130:131], s[22:23], v[128:129] op_sel:[0,0,1] op_sel_hi:[1,0,0] neg_lo:[0,0,1] neg_hi:[0,0,1]
	v_pk_fma_f32 v[128:129], v[130:131], s[22:23], v[128:129] op_sel:[0,0,1] op_sel_hi:[1,0,0]
	s_nop 0
	v_mov_b32_e32 v179, v129
	v_pk_mul_f32 v[128:129], v[116:117], s[24:25] op_sel_hi:[1,0]
	s_nop 0
	v_pk_fma_f32 v[130:131], v[116:117], s[24:25], v[128:129] op_sel:[0,0,1] op_sel_hi:[1,0,0] neg_lo:[0,0,1] neg_hi:[0,0,1]
	v_pk_fma_f32 v[116:117], v[116:117], s[24:25], v[128:129] op_sel_hi:[1,0,0]
	s_nop 0
	v_mov_b32_e32 v131, v117
	v_pk_mul_f32 v[116:117], v[126:127], s[22:23] op_sel_hi:[1,0]
	s_nop 0
	v_pk_fma_f32 v[128:129], v[126:127], s[30:31], v[116:117] op_sel:[0,0,1] op_sel_hi:[1,0,0] neg_lo:[0,0,1] neg_hi:[0,0,1]
	v_pk_fma_f32 v[116:117], v[126:127], s[30:31], v[116:117] op_sel:[0,0,1] op_sel_hi:[1,0,0]
	s_nop 0
	v_mov_b32_e32 v129, v117
	v_pk_mul_f32 v[116:117], v[134:135], s[24:25] op_sel_hi:[1,0]
	s_nop 0
	v_pk_fma_f32 v[126:127], v[134:135], s[24:25], v[116:117] op_sel:[0,0,1] op_sel_hi:[1,0,0] neg_lo:[0,0,1] neg_hi:[0,0,1]
	v_pk_fma_f32 v[116:117], v[134:135], s[24:25], v[116:117] op_sel_hi:[1,0,0]
	s_nop 0
	v_mov_b32_e32 v127, v117
	v_mov_b32_e32 v117, v132
	v_mul_f32_e32 v132, 0x3f3504f3, v121
	v_xor_b32_e32 v116, 0x80000000, v133
	v_pk_fma_f32 v[120:121], v[120:121], s[18:19], v[132:133] op_sel_hi:[0,1,0] neg_lo:[0,0,1] neg_hi:[0,0,1]
	v_pk_mul_f32 v[132:133], v[176:177], s[22:23] op_sel_hi:[1,0]
	s_nop 0
	v_pk_fma_f32 v[134:135], v[176:177], s[30:31], v[132:133] op_sel:[0,0,1] op_sel_hi:[1,0,0] neg_lo:[0,0,1] neg_hi:[0,0,1]
	v_pk_fma_f32 v[132:133], v[176:177], s[30:31], v[132:133] op_sel:[0,0,1] op_sel_hi:[1,0,0]
	s_nop 0
	v_mul_f32_e32 v132, 0x3f3504f3, v125
	v_mov_b32_e32 v135, v133
	v_pk_fma_f32 v[124:125], v[124:125], s[18:19], v[132:133] op_sel_hi:[0,1,0] neg_lo:[0,0,1] neg_hi:[0,0,1]
	v_pk_mul_f32 v[132:133], v[118:119], s[88:89]
	s_nop 0
	v_pk_fma_f32 v[118:119], v[118:119], s[22:23], v[132:133] op_sel:[0,0,1] op_sel_hi:[1,0,0] neg_lo:[1,0,0] neg_hi:[1,0,0]
	v_pk_add_f32 v[132:133], v[108:109], v[114:115]
	v_pk_add_f32 v[108:109], v[108:109], v[114:115] neg_lo:[0,1] neg_hi:[0,1]
	v_pk_add_f32 v[114:115], v[122:123], v[112:113]
	v_pk_add_f32 v[112:113], v[122:123], v[112:113] neg_lo:[0,1] neg_hi:[0,1]
	s_nop 0
	v_xor_b32_e32 v122, 0x80000000, v113
	v_mov_b32_e32 v123, v112
	v_pk_add_f32 v[112:113], v[132:133], v[114:115]
	v_pk_add_f32 v[114:115], v[132:133], v[114:115] neg_lo:[0,1] neg_hi:[0,1]
	v_pk_add_f32 v[132:133], v[108:109], v[122:123]
	v_pk_add_f32 v[108:109], v[108:109], v[122:123] neg_lo:[0,1] neg_hi:[0,1]
	v_pk_add_f32 v[122:123], v[110:111], v[126:127]
	v_pk_add_f32 v[110:111], v[110:111], v[126:127] neg_lo:[0,1] neg_hi:[0,1]
	v_pk_add_f32 v[126:127], v[178:179], v[134:135]
	v_pk_add_f32 v[134:135], v[178:179], v[134:135] neg_lo:[0,1] neg_hi:[0,1]
	s_nop 0
	v_xor_b32_e32 v176, 0x80000000, v135
	v_mov_b32_e32 v177, v134
	v_pk_add_f32 v[134:135], v[122:123], v[126:127]
	v_pk_add_f32 v[122:123], v[122:123], v[126:127] neg_lo:[0,1] neg_hi:[0,1]
	v_pk_add_f32 v[126:127], v[110:111], v[176:177]
	v_pk_add_f32 v[110:111], v[110:111], v[176:177] neg_lo:[0,1] neg_hi:[0,1]
	v_pk_add_f32 v[176:177], v[106:107], v[116:117]
	v_pk_add_f32 v[106:107], v[106:107], v[116:117] neg_lo:[0,1] neg_hi:[0,1]
	v_pk_add_f32 v[116:117], v[130:131], v[124:125]
	v_pk_add_f32 v[124:125], v[130:131], v[124:125] neg_lo:[0,1] neg_hi:[0,1]
	s_nop 0
	v_xor_b32_e32 v130, 0x80000000, v125
	v_mov_b32_e32 v131, v124
	v_pk_add_f32 v[124:125], v[176:177], v[116:117]
	v_pk_add_f32 v[116:117], v[176:177], v[116:117] neg_lo:[0,1] neg_hi:[0,1]
	v_pk_add_f32 v[176:177], v[106:107], v[130:131]
	v_pk_add_f32 v[106:107], v[106:107], v[130:131] neg_lo:[0,1] neg_hi:[0,1]
	v_pk_add_f32 v[130:131], v[104:105], v[120:121]
	v_pk_add_f32 v[104:105], v[104:105], v[120:121] neg_lo:[0,1] neg_hi:[0,1]
	v_pk_add_f32 v[120:121], v[128:129], v[118:119]
	v_pk_add_f32 v[118:119], v[128:129], v[118:119] neg_lo:[0,1] neg_hi:[0,1]
	s_nop 0
	v_xor_b32_e32 v128, 0x80000000, v119
	v_mov_b32_e32 v129, v118
	v_pk_add_f32 v[118:119], v[130:131], v[120:121]
	v_pk_add_f32 v[120:121], v[130:131], v[120:121] neg_lo:[0,1] neg_hi:[0,1]
	v_pk_add_f32 v[130:131], v[104:105], v[128:129]
	v_pk_add_f32 v[104:105], v[104:105], v[128:129] neg_lo:[0,1] neg_hi:[0,1]
	v_mov_b32_e32 v128, v208
	ds_write2_b64 v204, v[112:113], v[134:135] offset1:17
	ds_write2_b64 v204, v[124:125], v[118:119] offset0:34 offset1:51
	ds_write2_b64 v204, v[132:133], v[126:127] offset0:68 offset1:85
	ds_write2_b64 v204, v[176:177], v[130:131] offset0:102 offset1:119
	ds_write2_b64 v204, v[114:115], v[122:123] offset0:136 offset1:153
	ds_write2_b64 v204, v[116:117], v[120:121] offset0:170 offset1:187
	ds_write2_b64 v204, v[108:109], v[110:111] offset0:204 offset1:221
	ds_write2_b64 v204, v[106:107], v[104:105] offset0:238 offset1:255
	s_waitcnt lgkmcnt(0)
	s_barrier
	s_nop 0
	v_and_b32_e32 v104, 0xff, v128
	v_lshlrev_b32_e32 v105, 4, v128
	v_cvt_f32_ubyte0_e32 v128, v128
	v_mul_f32_e32 v205, 0x39800000, v128
	v_mul_f32_e32 v129, 0x41400000, v205
	v_sin_f32_e32 v130, v129
	v_sin_f32_e32 v132, v205
	v_cos_f32_e32 v131, v129
	v_cos_f32_e32 v128, v205
	v_and_or_b32 v104, v105, s93, v104
	v_ashrrev_i32_e32 v105, 4, v104
	v_pk_mul_f32 v[182:183], v[132:133], v[130:131] op_sel_hi:[0,1]
	v_pk_fma_f32 v[184:185], v[128:129], v[130:131], v[182:183] op_sel:[0,0,1] op_sel_hi:[0,1,0]
	v_pk_fma_f32 v[182:183], v[128:129], v[130:131], v[182:183] op_sel:[0,0,1] op_sel_hi:[0,1,0] neg_lo:[0,0,1] neg_hi:[0,0,1]
	v_lshlrev_b32_e32 v105, 3, v105
	v_lshlrev_b32_e32 v104, 3, v104
	v_pk_mov_b32 v[188:189], v[182:183], v[184:185] op_sel:[1,0]
	v_add3_u32 v204, s35, v105, v104
	v_mov_b32_e32 v186, v184
	v_mov_b32_e32 v187, v183
	v_pk_mul_f32 v[188:189], v[132:133], v[188:189] op_sel_hi:[0,1]
	v_mov_b32_e32 v133, v128
	ds_read_b64 v[104:105], v204
	ds_read_b64 v[106:107], v204 offset:2176
	ds_read_b64 v[108:109], v204 offset:4352
	ds_read_b64 v[110:111], v204 offset:6528
	ds_read_b64 v[112:113], v204 offset:8704
	ds_read_b64 v[114:115], v204 offset:10880
	ds_read_b64 v[116:117], v204 offset:13056
	ds_read_b64 v[118:119], v204 offset:15232
	ds_read_b64 v[120:121], v204 offset:17408
	ds_read_b64 v[122:123], v204 offset:19584
	ds_read_b64 v[124:125], v204 offset:21760
	ds_read_b64 v[126:127], v204 offset:23936
	v_pk_fma_f32 v[190:191], v[128:129], v[186:187], v[188:189] op_sel_hi:[0,1,1]
	v_pk_fma_f32 v[186:187], v[128:129], v[186:187], v[188:189] op_sel_hi:[0,1,1] neg_lo:[0,0,1] neg_hi:[0,0,1]
	v_mov_b32_e32 v129, v132
	s_waitcnt lgkmcnt(10)
	v_pk_mul_f32 v[194:195], v[106:107], v[132:133] op_sel_hi:[1,0]
	ds_read_b64 v[134:135], v204 offset:26112
	ds_read_b64 v[176:177], v204 offset:28288
	ds_read_b64 v[178:179], v204 offset:30464
	ds_read_b64 v[180:181], v204 offset:32640
	v_pk_fma_f32 v[196:197], v[106:107], v[128:129], v[194:195] op_sel:[0,0,1] op_sel_hi:[1,1,0] neg_lo:[0,0,1] neg_hi:[0,0,1]
	v_pk_fma_f32 v[106:107], v[106:107], v[128:129], v[194:195] op_sel:[0,0,1] op_sel_hi:[1,0,0]
	v_mov_b32_e32 v188, v190
	v_mov_b32_e32 v197, v107
	v_pk_mul_f32 v[106:107], v[132:133], v[132:133] op_sel:[0,1] op_sel_hi:[0,0]
	v_pk_fma_f32 v[194:195], v[128:129], v[132:133], v[106:107] op_sel_hi:[0,1,1]
	v_pk_fma_f32 v[106:107], v[128:129], v[132:133], v[106:107] op_sel_hi:[0,1,1] neg_lo:[0,0,1] neg_hi:[0,0,1]
	v_mov_b32_e32 v198, v194
	v_mov_b32_e32 v199, v107
	s_waitcnt lgkmcnt(13)
	v_pk_mul_f32 v[194:195], v[108:109], v[194:195] op_sel:[1,0] op_sel_hi:[0,0]
	v_pk_fma_f32 v[200:201], v[108:109], v[106:107], v[194:195] op_sel:[0,1,0] neg_lo:[0,0,1] neg_hi:[0,0,1]
	v_pk_fma_f32 v[106:107], v[108:109], v[106:107], v[194:195] op_sel:[0,1,0]
	v_pk_mul_f32 v[108:109], v[132:133], v[198:199] op_sel:[1,0] op_sel_hi:[0,1]
	v_mov_b32_e32 v201, v107
	v_pk_mul_f32 v[106:107], v[132:133], v[198:199]
	v_pk_add_f32 v[108:109], v[108:109], v[108:109] op_sel:[0,1] op_sel_hi:[0,1]
	s_waitcnt lgkmcnt(12)
	v_pk_mul_f32 v[108:109], v[110:111], v[108:109] op_sel:[1,0] op_sel_hi:[0,1]
	v_pk_add_f32 v[106:107], v[106:107], v[106:107] op_sel:[1,0] op_sel_hi:[1,0] neg_lo:[0,1] neg_hi:[0,1]
	v_mov_b32_e32 v189, v187
	v_pk_fma_f32 v[194:195], v[110:111], v[106:107], v[108:109] neg_lo:[0,0,1] neg_hi:[0,0,1]
	v_pk_fma_f32 v[106:107], v[110:111], v[106:107], v[108:109]
	v_mul_f32_e32 v195, 4.0, v205
	v_sin_f32_e32 v198, v195
	v_cos_f32_e32 v202, v195
	v_mov_b32_e32 v195, v107
	v_pk_mul_f32 v[192:193], v[128:129], v[188:189]
	s_waitcnt lgkmcnt(11)
	v_pk_mul_f32 v[106:107], v[198:199], v[112:113] op_sel:[0,1] op_sel_hi:[0,0]
	v_pk_fma_f32 v[108:109], v[202:203], v[112:113], v[106:107] neg_lo:[0,0,1] neg_hi:[0,0,1]
	v_pk_fma_f32 v[106:107], v[202:203], v[112:113], v[106:107] op_sel_hi:[0,1,1]
	v_mov_b32_e32 v199, v202
	v_mov_b32_e32 v109, v107
	v_pk_mul_f32 v[106:107], v[132:133], v[198:199] op_sel_hi:[0,1]
	v_pk_fma_f32 v[110:111], v[128:129], v[198:199], v[106:107] op_sel:[0,0,1] op_sel_hi:[0,1,0]
	v_pk_fma_f32 v[106:107], v[128:129], v[198:199], v[106:107] op_sel:[0,0,1] op_sel_hi:[0,1,0] neg_lo:[0,0,1] neg_hi:[0,0,1]
	s_waitcnt lgkmcnt(10)
	v_pk_mul_f32 v[198:199], v[110:111], v[114:115] op_sel:[0,1] op_sel_hi:[0,0]
	v_mov_b32_e32 v112, v110
	v_mov_b32_e32 v113, v107
	v_pk_mov_b32 v[110:111], v[106:107], v[110:111] op_sel:[1,0]
	v_pk_fma_f32 v[202:203], v[106:107], v[114:115], v[198:199] op_sel:[1,0,0] neg_lo:[0,0,1] neg_hi:[0,0,1]
	v_pk_fma_f32 v[106:107], v[106:107], v[114:115], v[198:199] op_sel:[1,0,0]
	v_pk_mul_f32 v[188:189], v[132:133], v[188:189]
	v_mov_b32_e32 v203, v107
	v_pk_mul_f32 v[106:107], v[132:133], v[110:111] op_sel_hi:[0,1]
	v_pk_fma_f32 v[110:111], v[128:129], v[112:113], v[106:107] op_sel_hi:[0,1,1]
	v_pk_fma_f32 v[106:107], v[128:129], v[112:113], v[106:107] op_sel_hi:[0,1,1] neg_lo:[0,0,1] neg_hi:[0,0,1]
	v_mov_b32_e32 v112, v110
	v_mov_b32_e32 v113, v107
	s_waitcnt lgkmcnt(9)
	v_pk_mul_f32 v[110:111], v[116:117], v[110:111] op_sel:[1,0] op_sel_hi:[0,0]
	v_pk_fma_f32 v[114:115], v[116:117], v[106:107], v[110:111] op_sel:[0,1,0] neg_lo:[0,0,1] neg_hi:[0,0,1]
	v_pk_fma_f32 v[106:107], v[116:117], v[106:107], v[110:111] op_sel:[0,1,0]
	v_pk_mul_f32 v[110:111], v[128:129], v[112:113]
	v_mov_b32_e32 v115, v107
	v_pk_mul_f32 v[106:107], v[132:133], v[112:113]
	v_pk_add_f32 v[110:111], v[110:111], v[110:111] op_sel:[0,1] op_sel_hi:[0,1]
	s_waitcnt lgkmcnt(8)
	v_pk_mul_f32 v[110:111], v[118:119], v[110:111] op_sel:[1,0] op_sel_hi:[0,1]
	v_pk_add_f32 v[106:107], v[106:107], v[106:107] op_sel:[1,0] op_sel_hi:[1,0] neg_lo:[0,1] neg_hi:[0,1]
	s_nop 0
	v_pk_fma_f32 v[112:113], v[118:119], v[106:107], v[110:111] neg_lo:[0,0,1] neg_hi:[0,0,1]
	v_pk_fma_f32 v[106:107], v[118:119], v[106:107], v[110:111]
	v_mul_f32_e32 v113, 0x41000000, v205
	v_sin_f32_e32 v116, v113
	v_cos_f32_e32 v198, v113
	v_mov_b32_e32 v113, v107
	s_waitcnt lgkmcnt(7)
	v_pk_mul_f32 v[106:107], v[116:117], v[120:121] op_sel:[0,1] op_sel_hi:[0,0]
	v_pk_fma_f32 v[110:111], v[198:199], v[120:121], v[106:107] neg_lo:[0,0,1] neg_hi:[0,0,1]
	v_pk_fma_f32 v[106:107], v[198:199], v[120:121], v[106:107] op_sel_hi:[0,1,1]
	v_mov_b32_e32 v117, v198
	v_mov_b32_e32 v111, v107
	v_pk_mul_f32 v[106:107], v[132:133], v[116:117] op_sel_hi:[0,1]
	v_pk_fma_f32 v[118:119], v[128:129], v[116:117], v[106:107] op_sel:[0,0,1] op_sel_hi:[0,1,0]
	v_pk_fma_f32 v[106:107], v[128:129], v[116:117], v[106:107] op_sel:[0,0,1] op_sel_hi:[0,1,0] neg_lo:[0,0,1] neg_hi:[0,0,1]
	s_waitcnt lgkmcnt(6)
	v_pk_mul_f32 v[120:121], v[118:119], v[122:123] op_sel:[0,1] op_sel_hi:[0,0]
	v_mov_b32_e32 v116, v118
	v_mov_b32_e32 v117, v107
	v_pk_mov_b32 v[118:119], v[106:107], v[118:119] op_sel:[1,0]
	v_pk_fma_f32 v[198:199], v[106:107], v[122:123], v[120:121] op_sel:[1,0,0] neg_lo:[0,0,1] neg_hi:[0,0,1]
	v_pk_fma_f32 v[106:107], v[106:107], v[122:123], v[120:121] op_sel:[1,0,0]
	v_mov_b32_e32 v122, v131
	v_mov_b32_e32 v199, v107
	v_pk_mul_f32 v[106:107], v[132:133], v[118:119] op_sel_hi:[0,1]
	v_pk_fma_f32 v[118:119], v[128:129], v[116:117], v[106:107] op_sel_hi:[0,1,1]
	v_pk_fma_f32 v[106:107], v[128:129], v[116:117], v[106:107] op_sel_hi:[0,1,1] neg_lo:[0,0,1] neg_hi:[0,0,1]
	v_mov_b32_e32 v116, v118
	s_waitcnt lgkmcnt(5)
	v_pk_mul_f32 v[118:119], v[118:119], v[124:125] op_sel:[0,1] op_sel_hi:[0,0]
	v_mov_b32_e32 v117, v107
	v_pk_fma_f32 v[120:121], v[106:107], v[124:125], v[118:119] op_sel:[1,0,0] neg_lo:[0,0,1] neg_hi:[0,0,1]
	v_pk_fma_f32 v[106:107], v[106:107], v[124:125], v[118:119] op_sel:[1,0,0]
	s_nop 0
	v_mov_b32_e32 v121, v107
	v_pk_mul_f32 v[106:107], v[132:133], v[116:117]
	v_pk_mul_f32 v[116:117], v[128:129], v[116:117]
	v_pk_add_f32 v[106:107], v[106:107], v[106:107] op_sel:[1,0] op_sel_hi:[1,0] neg_lo:[0,1] neg_hi:[0,1]
	v_pk_add_f32 v[116:117], v[116:117], v[116:117] op_sel:[0,1] op_sel_hi:[0,1]
	s_waitcnt lgkmcnt(4)
	v_pk_mul_f32 v[116:117], v[116:117], v[126:127] op_sel:[0,1] op_sel_hi:[1,0]
	s_nop 0
	v_pk_fma_f32 v[118:119], v[106:107], v[126:127], v[116:117] neg_lo:[0,0,1] neg_hi:[0,0,1]
	v_pk_fma_f32 v[106:107], v[106:107], v[126:127], v[116:117]
	v_mov_b32_e32 v116, v131
	v_mov_b32_e32 v119, v107
	s_waitcnt lgkmcnt(3)
	v_pk_mul_f32 v[106:107], v[130:131], v[134:135] op_sel:[0,1] op_sel_hi:[0,0]
	v_pk_fma_f32 v[116:117], v[116:117], v[134:135], v[106:107] neg_lo:[0,0,1] neg_hi:[0,0,1]
	v_pk_fma_f32 v[106:107], v[122:123], v[134:135], v[106:107] op_sel_hi:[0,1,1]
	v_mov_b32_e32 v117, v107
	s_waitcnt lgkmcnt(2)
	v_pk_mul_f32 v[106:107], v[184:185], v[176:177] op_sel:[0,1] op_sel_hi:[0,0]
	v_pk_fma_f32 v[122:123], v[182:183], v[176:177], v[106:107] op_sel:[1,0,0] neg_lo:[0,0,1] neg_hi:[0,0,1]
	v_pk_fma_f32 v[106:107], v[182:183], v[176:177], v[106:107] op_sel:[1,0,0]
	v_pk_add_f32 v[126:127], v[192:193], v[192:193] op_sel:[0,1] op_sel_hi:[0,1]
	v_mov_b32_e32 v123, v107
	s_waitcnt lgkmcnt(1)
	v_pk_mul_f32 v[106:107], v[190:191], v[178:179] op_sel:[0,1] op_sel_hi:[0,0]
	v_pk_fma_f32 v[124:125], v[186:187], v[178:179], v[106:107] op_sel:[1,0,0] neg_lo:[0,0,1] neg_hi:[0,0,1]
	v_pk_fma_f32 v[106:107], v[186:187], v[178:179], v[106:107] op_sel:[1,0,0]
	s_waitcnt lgkmcnt(0)
	v_pk_mul_f32 v[126:127], v[126:127], v[180:181] op_sel:[0,1] op_sel_hi:[1,0]
	v_mov_b32_e32 v125, v107
	v_pk_add_f32 v[106:107], v[188:189], v[188:189] op_sel:[1,0] op_sel_hi:[1,0] neg_lo:[0,1] neg_hi:[0,1]
	v_pk_add_f32 v[130:131], v[202:203], v[122:123]
	v_pk_fma_f32 v[128:129], v[106:107], v[180:181], v[126:127] neg_lo:[0,0,1] neg_hi:[0,0,1]
	v_pk_fma_f32 v[106:107], v[106:107], v[180:181], v[126:127]
	v_pk_add_f32 v[122:123], v[202:203], v[122:123] neg_lo:[0,1] neg_hi:[0,1]
	v_mov_b32_e32 v129, v107
	v_pk_add_f32 v[106:107], v[104:105], v[110:111]
	v_pk_add_f32 v[104:105], v[104:105], v[110:111] neg_lo:[0,1] neg_hi:[0,1]
	v_pk_add_f32 v[110:111], v[108:109], v[116:117]
	v_pk_add_f32 v[108:109], v[108:109], v[116:117] neg_lo:[0,1] neg_hi:[0,1]
	v_pk_add_f32 v[126:127], v[196:197], v[198:199] neg_lo:[0,1] neg_hi:[0,1]
	v_xor_b32_e32 v116, 0x80000000, v109
	v_mov_b32_e32 v117, v108
	v_pk_add_f32 v[108:109], v[106:107], v[110:111]
	v_pk_add_f32 v[106:107], v[106:107], v[110:111] neg_lo:[0,1] neg_hi:[0,1]
	v_pk_add_f32 v[110:111], v[104:105], v[116:117]
	v_pk_add_f32 v[104:105], v[104:105], v[116:117] neg_lo:[0,1] neg_hi:[0,1]
	v_pk_add_f32 v[116:117], v[196:197], v[198:199]
	v_xor_b32_e32 v132, 0x80000000, v123
	v_mov_b32_e32 v133, v122
	v_pk_add_f32 v[134:135], v[114:115], v[124:125]
	v_pk_add_f32 v[114:115], v[114:115], v[124:125] neg_lo:[0,1] neg_hi:[0,1]
	v_pk_add_f32 v[122:123], v[116:117], v[130:131]
	v_pk_add_f32 v[116:117], v[116:117], v[130:131] neg_lo:[0,1] neg_hi:[0,1]
	v_pk_add_f32 v[130:131], v[126:127], v[132:133]
	v_pk_add_f32 v[126:127], v[126:127], v[132:133] neg_lo:[0,1] neg_hi:[0,1]
	v_pk_add_f32 v[132:133], v[200:201], v[120:121]
	v_pk_add_f32 v[120:121], v[200:201], v[120:121] neg_lo:[0,1] neg_hi:[0,1]
	v_xor_b32_e32 v124, 0x80000000, v115
	v_mov_b32_e32 v125, v114
	v_pk_add_f32 v[176:177], v[112:113], v[128:129]
	v_pk_add_f32 v[112:113], v[112:113], v[128:129] neg_lo:[0,1] neg_hi:[0,1]
	v_pk_add_f32 v[114:115], v[132:133], v[134:135]
	v_pk_add_f32 v[132:133], v[132:133], v[134:135] neg_lo:[0,1] neg_hi:[0,1]
	v_pk_add_f32 v[134:135], v[120:121], v[124:125]
	v_pk_add_f32 v[120:121], v[120:121], v[124:125] neg_lo:[0,1] neg_hi:[0,1]
	v_pk_add_f32 v[124:125], v[194:195], v[118:119]
	v_pk_add_f32 v[118:119], v[194:195], v[118:119] neg_lo:[0,1] neg_hi:[0,1]
	v_xor_b32_e32 v128, 0x80000000, v113
	v_mov_b32_e32 v129, v112
	v_pk_add_f32 v[112:113], v[124:125], v[176:177]
	v_pk_add_f32 v[124:125], v[124:125], v[176:177] neg_lo:[0,1] neg_hi:[0,1]
	v_pk_add_f32 v[176:177], v[118:119], v[128:129]
	v_pk_add_f32 v[118:119], v[118:119], v[128:129] neg_lo:[0,1] neg_hi:[0,1]
	v_pk_mul_f32 v[128:129], v[130:131], s[30:31] op_sel_hi:[1,0]
	s_nop 0
	v_pk_fma_f32 v[178:179], v[130:131], s[22:23], v[128:129] op_sel:[0,0,1] op_sel_hi:[1,0,0] neg_lo:[0,0,1] neg_hi:[0,0,1]
	v_pk_fma_f32 v[128:129], v[130:131], s[22:23], v[128:129] op_sel:[0,0,1] op_sel_hi:[1,0,0]
	s_nop 0
	v_mov_b32_e32 v179, v129
	v_pk_mul_f32 v[128:129], v[116:117], s[24:25] op_sel_hi:[1,0]
	s_nop 0
	v_pk_fma_f32 v[130:131], v[116:117], s[24:25], v[128:129] op_sel:[0,0,1] op_sel_hi:[1,0,0] neg_lo:[0,0,1] neg_hi:[0,0,1]
	v_pk_fma_f32 v[116:117], v[116:117], s[24:25], v[128:129] op_sel_hi:[1,0,0]
	s_nop 0
	v_mov_b32_e32 v131, v117
	v_pk_mul_f32 v[116:117], v[126:127], s[22:23] op_sel_hi:[1,0]
	s_nop 0
	v_pk_fma_f32 v[128:129], v[126:127], s[30:31], v[116:117] op_sel:[0,0,1] op_sel_hi:[1,0,0] neg_lo:[0,0,1] neg_hi:[0,0,1]
	v_pk_fma_f32 v[116:117], v[126:127], s[30:31], v[116:117] op_sel:[0,0,1] op_sel_hi:[1,0,0]
	s_nop 0
	v_mov_b32_e32 v129, v117
	v_pk_mul_f32 v[116:117], v[134:135], s[24:25] op_sel_hi:[1,0]
	s_nop 0
	v_pk_fma_f32 v[126:127], v[134:135], s[24:25], v[116:117] op_sel:[0,0,1] op_sel_hi:[1,0,0] neg_lo:[0,0,1] neg_hi:[0,0,1]
	v_pk_fma_f32 v[116:117], v[134:135], s[24:25], v[116:117] op_sel_hi:[1,0,0]
	s_nop 0
	v_mov_b32_e32 v127, v117
	v_mov_b32_e32 v117, v132
	v_mul_f32_e32 v132, 0x3f3504f3, v121
	v_xor_b32_e32 v116, 0x80000000, v133
	v_pk_fma_f32 v[120:121], v[120:121], s[18:19], v[132:133] op_sel_hi:[0,1,0] neg_lo:[0,0,1] neg_hi:[0,0,1]
	v_pk_mul_f32 v[132:133], v[176:177], s[22:23] op_sel_hi:[1,0]
	s_nop 0
	v_pk_fma_f32 v[134:135], v[176:177], s[30:31], v[132:133] op_sel:[0,0,1] op_sel_hi:[1,0,0] neg_lo:[0,0,1] neg_hi:[0,0,1]
	v_pk_fma_f32 v[132:133], v[176:177], s[30:31], v[132:133] op_sel:[0,0,1] op_sel_hi:[1,0,0]
	s_nop 0
	v_mul_f32_e32 v132, 0x3f3504f3, v125
	v_mov_b32_e32 v135, v133
	v_pk_fma_f32 v[124:125], v[124:125], s[18:19], v[132:133] op_sel_hi:[0,1,0] neg_lo:[0,0,1] neg_hi:[0,0,1]
	v_pk_mul_f32 v[132:133], v[118:119], s[88:89]
	s_nop 0
	v_pk_fma_f32 v[118:119], v[118:119], s[22:23], v[132:133] op_sel:[0,0,1] op_sel_hi:[1,0,0] neg_lo:[1,0,0] neg_hi:[1,0,0]
	v_pk_add_f32 v[132:133], v[108:109], v[114:115]
	v_pk_add_f32 v[108:109], v[108:109], v[114:115] neg_lo:[0,1] neg_hi:[0,1]
	v_pk_add_f32 v[114:115], v[122:123], v[112:113]
	v_pk_add_f32 v[112:113], v[122:123], v[112:113] neg_lo:[0,1] neg_hi:[0,1]
	s_nop 0
	v_xor_b32_e32 v122, 0x80000000, v113
	v_mov_b32_e32 v123, v112
	v_pk_add_f32 v[112:113], v[132:133], v[114:115]
	v_pk_add_f32 v[114:115], v[132:133], v[114:115] neg_lo:[0,1] neg_hi:[0,1]
	v_pk_add_f32 v[132:133], v[108:109], v[122:123]
	v_pk_add_f32 v[108:109], v[108:109], v[122:123] neg_lo:[0,1] neg_hi:[0,1]
	v_pk_add_f32 v[122:123], v[110:111], v[126:127]
	v_pk_add_f32 v[110:111], v[110:111], v[126:127] neg_lo:[0,1] neg_hi:[0,1]
	v_pk_add_f32 v[126:127], v[178:179], v[134:135]
	v_pk_add_f32 v[134:135], v[178:179], v[134:135] neg_lo:[0,1] neg_hi:[0,1]
	s_nop 0
	v_xor_b32_e32 v176, 0x80000000, v135
	v_mov_b32_e32 v177, v134
	v_pk_add_f32 v[134:135], v[122:123], v[126:127]
	v_pk_add_f32 v[122:123], v[122:123], v[126:127] neg_lo:[0,1] neg_hi:[0,1]
	v_pk_add_f32 v[126:127], v[110:111], v[176:177]
	v_pk_add_f32 v[110:111], v[110:111], v[176:177] neg_lo:[0,1] neg_hi:[0,1]
	v_pk_add_f32 v[176:177], v[106:107], v[116:117]
	v_pk_add_f32 v[106:107], v[106:107], v[116:117] neg_lo:[0,1] neg_hi:[0,1]
	v_pk_add_f32 v[116:117], v[130:131], v[124:125]
	v_pk_add_f32 v[124:125], v[130:131], v[124:125] neg_lo:[0,1] neg_hi:[0,1]
	s_nop 0
	v_xor_b32_e32 v130, 0x80000000, v125
	v_mov_b32_e32 v131, v124
	v_pk_add_f32 v[124:125], v[176:177], v[116:117]
	v_pk_add_f32 v[116:117], v[176:177], v[116:117] neg_lo:[0,1] neg_hi:[0,1]
	v_pk_add_f32 v[176:177], v[106:107], v[130:131]
	v_pk_add_f32 v[106:107], v[106:107], v[130:131] neg_lo:[0,1] neg_hi:[0,1]
	v_pk_add_f32 v[130:131], v[104:105], v[120:121]
	v_pk_add_f32 v[104:105], v[104:105], v[120:121] neg_lo:[0,1] neg_hi:[0,1]
	v_pk_add_f32 v[120:121], v[128:129], v[118:119]
	v_pk_add_f32 v[118:119], v[128:129], v[118:119] neg_lo:[0,1] neg_hi:[0,1]
	s_nop 0
	v_xor_b32_e32 v128, 0x80000000, v119
	v_mov_b32_e32 v129, v118
	v_pk_add_f32 v[118:119], v[130:131], v[120:121]
	v_pk_add_f32 v[120:121], v[130:131], v[120:121] neg_lo:[0,1] neg_hi:[0,1]
	v_pk_add_f32 v[130:131], v[104:105], v[128:129]
	v_pk_add_f32 v[104:105], v[104:105], v[128:129] neg_lo:[0,1] neg_hi:[0,1]
	ds_write_b64 v204, v[112:113]
	ds_write_b64 v204, v[134:135] offset:2176
	ds_write_b64 v204, v[124:125] offset:4352
	ds_write_b64 v204, v[118:119] offset:6528
	ds_write_b64 v204, v[132:133] offset:8704
	ds_write_b64 v204, v[126:127] offset:10880
	ds_write_b64 v204, v[176:177] offset:13056
	ds_write_b64 v204, v[130:131] offset:15232
	ds_write_b64 v204, v[114:115] offset:17408
	ds_write_b64 v204, v[122:123] offset:19584
	ds_write_b64 v204, v[116:117] offset:21760
	ds_write_b64 v204, v[120:121] offset:23936
	ds_write_b64 v204, v[108:109] offset:26112
	ds_write_b64 v204, v[110:111] offset:28288
	ds_write_b64 v204, v[106:107] offset:30464
	ds_write_b64 v204, v[104:105] offset:32640
	s_waitcnt lgkmcnt(0)
	s_barrier
	s_and_saveexec_b64 s[18:19], s[48:49]
	s_cbranch_execz .LBB0_276
	ds_read_b64 v[110:111], v154
	ds_read_b64 v[112:113], v154 offset:8
	ds_read_b64 v[106:107], v0
	ds_read_b64 v[114:115], v165 offset:8
	s_waitcnt vmcnt(1)
	v_lshlrev_b32_e32 v105, 16, v2
	v_lshlrev_b32_e32 v104, 16, v162
	v_and_b32_e32 v109, 16, v3
	v_and_b32_e32 v108, 0xffff0000, v2
	s_waitcnt lgkmcnt(0)
	v_mov_b32_e32 v127, v114
	v_mov_b32_e32 v114, v107
	v_mov_b32_e32 v116, v108
	v_pk_mov_b32 v[108:109], v[104:105], v[108:109] op_sel:[1,0]
	v_pk_fma_f32 v[104:105], v[54:55], v[104:105], v[60:61]
	v_mov_b32_e32 v126, v106
	v_pk_mul_f32 v[106:107], v[32:33], v[114:115]
	v_pk_fma_f32 v[104:105], v[56:57], v[108:109], v[104:105]
	v_pk_fma_f32 v[106:107], v[30:31], v[126:127], v[106:107] neg_lo:[0,0,1] neg_hi:[0,0,1]
	v_mov_b32_e32 v108, v110
	v_mov_b32_e32 v109, v112
	ds_read_b64 v[118:119], v166 offset:16
	ds_read_b64 v[124:125], v167 offset:24
	v_pk_add_f32 v[108:109], v[108:109], v[106:107]
	s_waitcnt vmcnt(0)
	v_lshlrev_b32_e32 v107, 16, v24
	v_lshlrev_b32_e32 v106, 16, v164
	v_and_b32_e32 v129, 16, v25
	v_and_b32_e32 v128, 0xffff0000, v24
	v_mov_b32_e32 v130, v128
	v_pk_mov_b32 v[128:129], v[106:107], v[128:129] op_sel:[1,0]
	v_pk_fma_f32 v[106:107], v[54:55], v[106:107], v[60:61]
	v_pk_mul_f32 v[126:127], v[32:33], v[126:127]
	ds_read_b64 v[120:121], v154 offset:16
	ds_read_b64 v[122:123], v154 offset:24
	v_pk_fma_f32 v[106:107], v[56:57], v[128:129], v[106:107]
	v_pk_fma_f32 v[114:115], v[30:31], v[114:115], v[126:127]
	ds_read_b64 v[126:127], v154 offset:32
	ds_read_b64 v[128:129], v154 offset:40
	ds_read_b64 v[132:133], v168 offset:32
	ds_read_b64 v[134:135], v169 offset:40
	v_mov_b32_e32 v112, v111
	v_pk_add_f32 v[110:111], v[112:113], v[114:115]
	v_and_b32_e32 v114, 0xffff0000, v3
	v_lshlrev_b32_e32 v177, 16, v4
	v_mov_b32_e32 v176, v114
	v_and_b32_e32 v113, 16, v5
	v_and_b32_e32 v112, 0xffff0000, v4
	s_waitcnt lgkmcnt(6)
	v_mov_b32_e32 v185, v124
	v_mov_b32_e32 v124, v119
	v_mov_b32_e32 v180, v112
	v_pk_mov_b32 v[178:179], v[176:177], v[112:113] op_sel:[1,0]
	v_mov_b32_e32 v184, v118
	v_pk_mul_f32 v[112:113], v[62:63], v[124:125]
	s_waitcnt lgkmcnt(4)
	v_mov_b32_e32 v118, v120
	v_pk_fma_f32 v[112:113], v[34:35], v[184:185], v[112:113] neg_lo:[0,0,1] neg_hi:[0,0,1]
	v_mov_b32_e32 v119, v122
	s_waitcnt lgkmcnt(0)
	v_mov_b32_e32 v189, v134
	v_mov_b32_e32 v134, v133
	v_lshlrev_b32_e32 v117, 16, v3
	v_and_b32_e32 v115, 16, v4
	v_pk_add_f32 v[112:113], v[118:119], v[112:113]
	v_mov_b32_e32 v188, v132
	v_pk_mul_f32 v[118:119], v[66:67], v[134:135]
	v_pk_fma_f32 v[182:183], v[54:55], v[116:117], v[60:61]
	v_pk_mov_b32 v[114:115], v[116:117], v[114:115] op_sel:[1,0]
	v_pk_fma_f32 v[118:119], v[64:65], v[188:189], v[118:119] neg_lo:[0,0,1] neg_hi:[0,0,1]
	v_mov_b32_e32 v132, v126
	v_mov_b32_e32 v133, v128
	v_pk_mul_f32 v[184:185], v[62:63], v[184:185]
	v_lshlrev_b32_e32 v131, 16, v25
	v_pk_fma_f32 v[114:115], v[56:57], v[114:115], v[182:183]
	ds_read_b64 v[182:183], v174 offset:48
	ds_read_b64 v[186:187], v175 offset:56
	v_pk_add_f32 v[118:119], v[132:133], v[118:119]
	v_and_b32_e32 v133, 16, v26
	v_and_b32_e32 v132, 0xffff0000, v25
	v_pk_fma_f32 v[124:125], v[34:35], v[124:125], v[184:185]
	v_mov_b32_e32 v122, v121
	v_pk_fma_f32 v[104:105], v[58:59], v[116:117], v[104:105]
	v_pk_fma_f32 v[106:107], v[58:59], v[130:131], v[106:107]
	v_pk_fma_f32 v[116:117], v[58:59], v[176:177], v[114:115]
	v_pk_fma_f32 v[114:115], v[54:55], v[176:177], v[60:61]
	v_pk_fma_f32 v[196:197], v[54:55], v[130:131], v[60:61]
	v_pk_add_f32 v[120:121], v[122:123], v[124:125]
	v_pk_mov_b32 v[122:123], v[130:131], v[132:133] op_sel:[1,0]
	v_pk_mul_f32 v[130:131], v[66:67], v[188:189]
	v_pk_fma_f32 v[114:115], v[56:57], v[178:179], v[114:115]
	ds_read_b64 v[176:177], v154 offset:48
	ds_read_b64 v[178:179], v154 offset:56
	v_pk_fma_f32 v[130:131], v[64:65], v[134:135], v[130:131]
	v_mov_b32_e32 v128, v127
	v_lshlrev_b32_e32 v181, 16, v5
	v_pk_add_f32 v[126:127], v[128:129], v[130:131]
	v_and_b32_e32 v129, 16, v161
	v_and_b32_e32 v128, 0xffff0000, v5
	v_mov_b32_e32 v190, v132
	v_mov_b32_e32 v130, v128
	v_pk_mov_b32 v[128:129], v[180:181], v[128:129] op_sel:[1,0]
	v_pk_fma_f32 v[132:133], v[54:55], v[180:181], v[60:61]
	v_lshlrev_b32_e32 v131, 16, v161
	v_pk_fma_f32 v[128:129], v[56:57], v[128:129], v[132:133]
	s_waitcnt lgkmcnt(2)
	v_mov_b32_e32 v135, v186
	v_mov_b32_e32 v186, v183
	v_pk_fma_f32 v[128:129], v[58:59], v[130:131], v[128:129]
	v_mov_b32_e32 v134, v182
	v_pk_mul_f32 v[130:131], v[70:71], v[186:187]
	v_and_b32_e32 v192, 0xffff0000, v26
	v_pk_fma_f32 v[130:131], v[68:69], v[134:135], v[130:131] neg_lo:[0,0,1] neg_hi:[0,0,1]
	s_waitcnt lgkmcnt(0)
	v_mov_b32_e32 v132, v176
	v_mov_b32_e32 v133, v178
	v_lshlrev_b32_e32 v191, 16, v26
	v_and_b32_e32 v193, 16, v27
	v_lshlrev_b32_e32 v195, 16, v27
	v_mov_b32_e32 v194, v192
	v_pk_fma_f32 v[122:123], v[56:57], v[122:123], v[196:197]
	v_pk_add_f32 v[132:133], v[132:133], v[130:131]
	v_and_b32_e32 v131, 16, v163
	v_and_b32_e32 v130, 0xffff0000, v27
	v_pk_fma_f32 v[114:115], v[58:59], v[180:181], v[114:115]
	v_pk_mov_b32 v[192:193], v[190:191], v[192:193] op_sel:[1,0]
	v_pk_fma_f32 v[124:125], v[58:59], v[190:191], v[122:123]
	v_pk_fma_f32 v[122:123], v[54:55], v[190:191], v[60:61]
	v_mov_b32_e32 v180, v130
	v_pk_mov_b32 v[130:131], v[194:195], v[130:131] op_sel:[1,0]
	v_pk_fma_f32 v[182:183], v[54:55], v[194:195], v[60:61]
	v_pk_mul_f32 v[134:135], v[70:71], v[134:135]
	v_pk_fma_f32 v[122:123], v[56:57], v[192:193], v[122:123]
	v_lshlrev_b32_e32 v181, 16, v163
	v_pk_fma_f32 v[130:131], v[56:57], v[130:131], v[182:183]
	v_pk_fma_f32 v[134:135], v[68:69], v[186:187], v[134:135]
	v_mov_b32_e32 v178, v177
	v_pk_fma_f32 v[122:123], v[58:59], v[194:195], v[122:123]
	v_pk_fma_f32 v[130:131], v[58:59], v[180:181], v[130:131]
	v_pk_add_f32 v[134:135], v[178:179], v[134:135]
	s_andn2_b64 vcc, exec, s[8:9]
	s_mov_b64 s[88:89], -1
	s_cbranch_vccnz .LBB0_302
	s_mov_b64 s[88:89], 0
	v_fma_f32 v108, v6, v8, v108
	v_fma_f32 v109, v6, v9, v109
	v_fma_f32 v112, v6, v10, v112
	v_fma_f32 v113, v6, v11, v113
	v_fma_f32 v118, v6, v12, v118
	v_fma_f32 v119, v6, v13, v119
	v_fma_f32 v132, v6, v14, v132
	v_fma_f32 v133, v6, v15, v133
	v_fma_f32 v110, v6, v16, v110
	v_fma_f32 v111, v6, v17, v111
	v_fma_f32 v120, v6, v18, v120
	v_fma_f32 v121, v6, v19, v121
	v_fma_f32 v126, v6, v20, v126
	v_fma_f32 v127, v6, v21, v127
	v_fma_f32 v134, v6, v22, v134
	v_fma_f32 v135, v6, v23, v135
	v_mul_f32_e32 v108, v104, v108
	v_mul_f32_e32 v109, v105, v109
	v_mul_f32_e32 v112, v116, v112
	v_mul_f32_e32 v113, v117, v113
	v_mul_f32_e32 v118, v114, v118
	v_mul_f32_e32 v119, v115, v119
	v_mul_f32_e32 v132, v128, v132
	v_mul_f32_e32 v133, v129, v133
	v_mul_f32_e32 v110, v106, v110
	v_mul_f32_e32 v111, v107, v111
	v_mul_f32_e32 v120, v124, v120
	v_mul_f32_e32 v121, v125, v121
	v_mul_f32_e32 v126, v122, v126
	v_mul_f32_e32 v127, v123, v127
	v_mul_f32_e32 v134, v130, v134
	v_mul_f32_e32 v135, v131, v135
	v_cvt_pk_bf16_f32 v8, v108, v109
	v_cvt_pk_bf16_f32 v9, v112, v113
	v_cvt_pk_bf16_f32 v10, v118, v119
	v_cvt_pk_bf16_f32 v11, v132, v133
	v_cvt_pk_bf16_f32 v12, v110, v111
	v_cvt_pk_bf16_f32 v13, v120, v121
	v_cvt_pk_bf16_f32 v14, v126, v127
	v_cvt_pk_bf16_f32 v15, v134, v135
	s_mul_i32 s36, s2, 0x11000
	s_add_u32 s36, s36, 0x6d00000
	s_add_u32 s36, s64, s36
	s_addc_u32 s37, s65, 0
	v_add_u32_e32 v176, s14, v44
	v_lshlrev_b32_e32 v176, 1, v176
	v_add_u32_e32 v177, 0x2000, v176
	global_store_dwordx4 v176, v[8:11], s[36:37]
	global_store_dwordx4 v177, v[12:15], s[36:37]
.LBB0_302:
	s_andn2_b64 vcc, exec, s[88:89]
	s_cbranch_vccnz .LBB0_276
	v_pk_fma_f32 v[108:109], v[6:7], v[8:9], v[108:109]
	s_nop 0
	v_pk_mul_f32 v[176:177], v[104:105], v[108:109]
	v_pk_fma_f32 v[104:105], v[6:7], v[10:11], v[112:113]
	v_pk_fma_f32 v[108:109], v[6:7], v[20:21], v[126:127]
	v_pk_mul_f32 v[178:179], v[116:117], v[104:105]
	v_pk_fma_f32 v[104:105], v[6:7], v[12:13], v[118:119]
	v_lshlrev_b64 v[116:117], 2, v[44:45]
	v_pk_mul_f32 v[112:113], v[114:115], v[104:105]
	v_pk_fma_f32 v[104:105], v[6:7], v[14:15], v[132:133]
	v_lshl_add_u64 v[118:119], s[12:13], 0, v[116:117]
	v_pk_mul_f32 v[114:115], v[128:129], v[104:105]
	v_pk_fma_f32 v[104:105], v[6:7], v[16:17], v[110:111]
	v_pk_fma_f32 v[110:111], v[6:7], v[22:23], v[134:135]
	v_pk_mul_f32 v[104:105], v[106:107], v[104:105]
	v_pk_fma_f32 v[106:107], v[6:7], v[18:19], v[120:121]
	global_store_dwordx4 v[118:119], v[176:179], off
	global_store_dwordx4 v[118:119], v[112:115], off offset:16
	v_pk_mul_f32 v[106:107], v[124:125], v[106:107]
	v_pk_mul_f32 v[108:109], v[122:123], v[108:109]
	v_lshl_add_u64 v[112:113], s[10:11], 0, v[116:117]
	v_pk_mul_f32 v[110:111], v[130:131], v[110:111]
	global_store_dwordx4 v[112:113], v[104:107], off
	global_store_dwordx4 v[112:113], v[108:111], off offset:16
	s_branch .LBB0_276
	s_nop 0
	s_nop 0
	s_nop 0
	s_nop 0
	s_nop 0
	s_nop 0
	s_nop 0
	s_nop 0
